# P7 (dilation-group combine) unrolled over a wave's 16 rows with each row's 12 loads issued three rows ahead into spare registers
# baseline (speedup 1.0000x reference)
; __device__ __forceinline__ unsigned pk2(float lo, float hi) { return f2bf(lo) | (f2bf(hi) << 16); }
; __global__ void __launch_bounds__(NWAVES * 64, 2) mk_fwd(Args args) {
;     ...
;     if (IN(7)) {
;         for (int m = gw; m < MTOK; m += NGW) {
; #pragma unroll
;             for (int j = 0; j < 2; ++j) {
;                 const int e = j * 512 + lane * 8, h = e >> 7;
;                 const float l0 = LSE[((size_t)0 * MTOK + m) * 8 + h], l1 = LSE[((size_t)1 * MTOK + m) * 8 + h], l2 = LSE[((size_t)2 * MTOK + m) * 8 + h];
;                 const float mx = fmaxf(l0, fmaxf(l1, l2)); float w0 = __expf(l0 - mx), w1 = __expf(l1 - mx), w2 = __expf(l2 - mx);
;                 const float inv = 1.0f / (w0 + w1 + w2); w0 *= inv; w1 *= inv; w2 *= inv;
;                 const bf16r* p = PROJ + (size_t)m * INW + O_QB + e;
;                 const v4u a0 = *(const v4u*)p, a1 = *(const v4u*)(p + 1024), a2 = *(const v4u*)(p + 2048);
;                 v4u o;
; #pragma unroll
;                 for (int q = 0; q < 4; ++q) {
;                     const float x0 = __builtin_bit_cast(float, a0[q] << 16), y0 = __builtin_bit_cast(float, a0[q] & 0xffff0000u);
;                     const float x1 = __builtin_bit_cast(float, a1[q] << 16), y1 = __builtin_bit_cast(float, a1[q] & 0xffff0000u);
;                     const float x2 = __builtin_bit_cast(float, a2[q] << 16), y2 = __builtin_bit_cast(float, a2[q] & 0xffff0000u);
;                     o[q] = pk2(w0 * x0 + w1 * x1 + w2 * x2, w0 * y0 + w1 * y1 + w2 * y2);
;                 }
;                 *(v4u*)(MIX + (size_t)m * DM + 1024 + e) = o;
.LBB0_607:
	s_cmp_lt_i32 s10, 8
	s_cselect_b64 s[2:3], -1, 0
	s_and_b64 s[2:3], s[2:3], s[0:1]
	s_cmp_lt_i32 s30, 0x8000
	s_cselect_b64 s[0:1], -1, 0
	s_and_b64 s[0:1], s[2:3], s[0:1]
	s_andn2_b64 vcc, exec, s[0:1]
	s_cbranch_vccnz .LBB0_610
	s_ashr_i32 s31, s30, 31
	s_lshl_b64 s[0:1], s[30:31], 12
	v_and_b32_e32 v4, 63, v218
	s_add_u32 s0, s24, s0
	v_lshlrev_b32_e32 v2, 4, v4
	v_mov_b32_e32 v3, 0
	s_addc_u32 s1, s25, s1
	s_waitcnt lgkmcnt(0)
	v_lshl_add_u64 v[0:1], s[0:1], 0, v[2:3]
	s_mov_b64 s[0:1], 0x800
	v_lshl_add_u64 v[0:1], v[0:1], 0, s[0:1]
	s_mul_hi_i32 s0, s30, 0x5400
	s_mul_i32 s1, s30, 0x5400
	v_or_b32_e32 v2, s1, v2
	v_mov_b32_e32 v3, s0
	s_lshl_b64 s[0:1], s[30:31], 5
	v_lshrrev_b32_e32 v4, 2, v4
	s_ashr_i32 s35, s34, 31
	v_and_or_b32 v4, v4, 12, s0
	s_lshl_b64 s[4:5], s[34:35], 12
	s_mul_hi_i32 s13, s34, 0x5400
	s_mul_i32 s12, s34, 0x5400
	v_or_b32_e32 v6, 16, v4
	v_mov_b32_e32 v7, s1
	s_lshl_b64 s[14:15], s[34:35], 5
	v_mov_b32_e32 v5, s1
	s_mov_b32 s16, 0xc200000
	s_mov_b32 s17, 0xc300000
	s_mov_b32 s18, 0xc400000
	s_mov_b32 s19, 0x14800000
	s_mov_b32 s20, 0x14801000
	s_mov_b32 s21, 0xffff0000
	s_movk_i32 s28, 0x7fff
	s_mov_b32 s29, 0x14802000
	s_cmp_lg_u32 s34, 0x800
	s_cbranch_scc1 .LBB0_609
	v_mov_b32_e32 v154, v2
	v_mov_b32_e32 v155, v4
	v_add_u32_e32 v142, 0x14800000, v154
	v_add_u32_e32 v143, 0x14801000, v154
	v_add_u32_e32 v144, 0x14802000, v154
	v_add_u32_e32 v145, 0xc200000, v155
	v_add_u32_e32 v146, 0xc300000, v155
	v_add_u32_e32 v147, 0xc400000, v155
	global_load_dwordx4 v[52:55], v143, s[26:27] offset:1024
	global_load_dword v76, v145, s[26:27]
	global_load_dwordx4 v[56:59], v143, s[26:27] offset:3072
	global_load_dword v77, v146, s[26:27]
	global_load_dword v78, v147, s[26:27]
	global_load_dwordx4 v[60:63], v142, s[26:27] offset:3072
	global_load_dword v79, v145, s[26:27] offset:16
	global_load_dword v80, v146, s[26:27] offset:16
	global_load_dword v81, v147, s[26:27] offset:16
	global_load_dwordx4 v[64:67], v143, s[26:27]
	global_load_dwordx4 v[68:71], v143, s[26:27] offset:2048
	global_load_dwordx4 v[72:75], v144, s[26:27]
	v_add_u32_e32 v154, s12, v154
	v_add_u32_e32 v155, s14, v155
	v_add_u32_e32 v148, 0x14800000, v154
	v_add_u32_e32 v149, 0x14801000, v154
	v_add_u32_e32 v150, 0x14802000, v154
	v_add_u32_e32 v151, 0xc200000, v155
	v_add_u32_e32 v152, 0xc300000, v155
	v_add_u32_e32 v153, 0xc400000, v155
	global_load_dwordx4 v[82:85], v149, s[26:27] offset:1024
	global_load_dword v106, v151, s[26:27]
	global_load_dwordx4 v[86:89], v149, s[26:27] offset:3072
	global_load_dword v107, v152, s[26:27]
	global_load_dword v108, v153, s[26:27]
	global_load_dwordx4 v[90:93], v148, s[26:27] offset:3072
	global_load_dword v109, v151, s[26:27] offset:16
	global_load_dword v110, v152, s[26:27] offset:16
	global_load_dword v111, v153, s[26:27] offset:16
	global_load_dwordx4 v[94:97], v149, s[26:27]
	global_load_dwordx4 v[98:101], v149, s[26:27] offset:2048
	global_load_dwordx4 v[102:105], v150, s[26:27]
	v_add_u32_e32 v154, s12, v154
	v_add_u32_e32 v155, s14, v155
	v_add_u32_e32 v142, 0x14800000, v154
	v_add_u32_e32 v143, 0x14801000, v154
	v_add_u32_e32 v144, 0x14802000, v154
	v_add_u32_e32 v145, 0xc200000, v155
	v_add_u32_e32 v146, 0xc300000, v155
	v_add_u32_e32 v147, 0xc400000, v155
	global_load_dwordx4 v[112:115], v143, s[26:27] offset:1024
	global_load_dword v136, v145, s[26:27]
	global_load_dwordx4 v[116:119], v143, s[26:27] offset:3072
	global_load_dword v137, v146, s[26:27]
	global_load_dword v138, v147, s[26:27]
	global_load_dwordx4 v[120:123], v142, s[26:27] offset:3072
	global_load_dword v139, v145, s[26:27] offset:16
	global_load_dword v140, v146, s[26:27] offset:16
	global_load_dword v141, v147, s[26:27] offset:16
	global_load_dwordx4 v[124:127], v143, s[26:27]
	global_load_dwordx4 v[128:131], v143, s[26:27] offset:2048
	global_load_dwordx4 v[132:135], v144, s[26:27]
	v_add_u32_e32 v154, s12, v154
	v_add_u32_e32 v155, s14, v155
	s_waitcnt vmcnt(24)
	v_mov_b32_e32 v10, v52
	v_mov_b32_e32 v11, v53
	v_mov_b32_e32 v12, v54
	v_mov_b32_e32 v13, v55
	v_mov_b32_e32 v14, v56
	v_mov_b32_e32 v15, v57
	v_mov_b32_e32 v16, v58
	v_mov_b32_e32 v17, v59
	v_mov_b32_e32 v18, v60
	v_mov_b32_e32 v19, v61
	v_mov_b32_e32 v20, v62
	v_mov_b32_e32 v21, v63
	v_mov_b32_e32 v46, v76
	v_mov_b32_e32 v47, v77
	v_mov_b32_e32 v48, v78
	v_lshlrev_b32_e32 v23, 16, v11
	v_and_b32_e32 v35, 0xffff0000, v11
	v_lshlrev_b32_e32 v41, 16, v13
	v_and_b32_e32 v43, 0xffff0000, v13
	v_lshlrev_b32_e32 v8, 16, v10
	v_and_b32_e32 v10, 0xffff0000, v10
	v_max3_f32 v49, v46, v47, v48
	v_lshlrev_b32_e32 v9, 16, v19
	v_and_b32_e32 v11, 0xffff0000, v19
	v_lshlrev_b32_e32 v22, 16, v18
	v_and_b32_e32 v34, 0xffff0000, v18
	v_sub_f32_e32 v18, v46, v49
	v_sub_f32_e32 v19, v47, v49
	v_lshlrev_b32_e32 v39, 16, v21
	v_and_b32_e32 v13, 0xffff0000, v21
	v_lshlrev_b32_e32 v40, 16, v20
	v_and_b32_e32 v42, 0xffff0000, v20
	v_sub_f32_e32 v20, v48, v49
	v_mul_f32_e32 v18, 0x3fb8aa3b, v18
	v_mul_f32_e32 v21, 0x3fb8aa3b, v19
	v_mul_f32_e32 v20, 0x3fb8aa3b, v20
	v_exp_f32_e32 v19, v18
	v_exp_f32_e32 v18, v21
	v_exp_f32_e32 v21, v20
	v_lshlrev_b32_e32 v38, 16, v12
	v_and_b32_e32 v12, 0xffff0000, v12
	v_add_f32_e32 v20, v19, v18
	v_add_f32_e32 v20, v21, v20
	v_div_scale_f32 v46, s[0:1], v20, v20, 1.0
	v_rcp_f32_e32 v48, v46
	v_div_scale_f32 v47, vcc, 1.0, v20, 1.0
	v_lshlrev_b32_e32 v37, 16, v15
	v_fma_f32 v49, -v46, v48, 1.0
	v_fmac_f32_e32 v48, v49, v48
	v_mul_f32_e32 v49, v47, v48
	v_fma_f32 v50, -v46, v49, v47
	v_fmac_f32_e32 v49, v50, v48
	v_fma_f32 v46, -v46, v49, v47
	v_div_fmas_f32 v46, v46, v48, v49
	v_div_fixup_f32 v20, v46, v20, 1.0
	v_pk_mul_f32 v[18:19], v[18:19], v[20:21] op_sel_hi:[1,0]
; __device__ __forceinline__ unsigned pk2(float lo, float hi) { return f2bf(lo) | (f2bf(hi) << 16); }
; __global__ void __launch_bounds__(NWAVES * 64, 2) mk_fwd(Args args) {
;     ...
;                 const int e = j * 512 + lane * 8, h = e >> 7;
;                 const float l0 = LSE[((size_t)0 * MTOK + m) * 8 + h], l1 = LSE[((size_t)1 * MTOK + m) * 8 + h], l2 = LSE[((size_t)2 * MTOK + m) * 8 + h];
;                 const float mx = fmaxf(l0, fmaxf(l1, l2)); float w0 = __expf(l0 - mx), w1 = __expf(l1 - mx), w2 = __expf(l2 - mx);
;                 const float inv = 1.0f / (w0 + w1 + w2); w0 *= inv; w1 *= inv; w2 *= inv;
;                 const bf16r* p = PROJ + (size_t)m * INW + O_QB + e;
;                 const v4u a0 = *(const v4u*)p, a1 = *(const v4u*)(p + 1024), a2 = *(const v4u*)(p + 2048);
;                 v4u o;
; #pragma unroll
;                 for (int q = 0; q < 4; ++q) {
;                     const float x0 = __builtin_bit_cast(float, a0[q] << 16), y0 = __builtin_bit_cast(float, a0[q] & 0xffff0000u);
;                     const float x1 = __builtin_bit_cast(float, a1[q] << 16), y1 = __builtin_bit_cast(float, a1[q] & 0xffff0000u);
;                     const float x2 = __builtin_bit_cast(float, a2[q] << 16), y2 = __builtin_bit_cast(float, a2[q] & 0xffff0000u);
;                     o[q] = pk2(w0 * x0 + w1 * x1 + w2 * x2, w0 * y0 + w1 * y1 + w2 * y2);
;                 }
;                 *(v4u*)(MIX + (size_t)m * DM + 1024 + e) = o;
	v_mul_f32_e32 v46, v21, v20
	v_pk_mul_f32 v[20:21], v[18:19], v[22:23] op_sel:[1,0] op_sel_hi:[0,1]
	v_pk_mul_f32 v[22:23], v[18:19], v[34:35] op_sel:[1,0] op_sel_hi:[0,1]
	v_pk_mul_f32 v[34:35], v[18:19], v[40:41] op_sel:[1,0] op_sel_hi:[0,1]
	v_pk_mul_f32 v[40:41], v[18:19], v[42:43] op_sel:[1,0] op_sel_hi:[0,1]
	v_lshlrev_b32_e32 v36, 16, v14
	v_and_b32_e32 v15, 0xffff0000, v15
	v_and_b32_e32 v14, 0xffff0000, v14
	v_lshlrev_b32_e32 v45, 16, v17
	v_lshlrev_b32_e32 v44, 16, v16
	v_and_b32_e32 v17, 0xffff0000, v17
	v_and_b32_e32 v16, 0xffff0000, v16
	v_pk_fma_f32 v[8:9], v[18:19], v[8:9], v[20:21]
	v_pk_fma_f32 v[10:11], v[18:19], v[10:11], v[22:23]
	v_pk_fma_f32 v[20:21], v[18:19], v[38:39], v[34:35]
	v_pk_fma_f32 v[12:13], v[18:19], v[12:13], v[40:41]
	v_pk_fma_f32 v[8:9], v[46:47], v[36:37], v[8:9] op_sel_hi:[0,1,1]
	v_pk_fma_f32 v[10:11], v[46:47], v[14:15], v[10:11] op_sel_hi:[0,1,1]
	v_pk_fma_f32 v[14:15], v[46:47], v[44:45], v[20:21] op_sel_hi:[0,1,1]
	v_pk_fma_f32 v[12:13], v[46:47], v[16:17], v[12:13] op_sel_hi:[0,1,1]
	v_bfe_u32 v16, v13, 16, 1
	v_bfe_u32 v17, v12, 16, 1
	v_bfe_u32 v18, v11, 16, 1
	v_bfe_u32 v19, v10, 16, 1
	v_bfe_u32 v20, v8, 16, 1
	v_bfe_u32 v21, v9, 16, 1
	v_bfe_u32 v22, v14, 16, 1
	v_bfe_u32 v23, v15, 16, 1
	v_add3_u32 v19, v10, v19, s28
	v_add3_u32 v18, v11, v18, s28
	v_add3_u32 v10, v12, v17, s28
	v_add3_u32 v11, v13, v16, s28
	v_add3_u32 v12, v15, v23, s28
	v_add3_u32 v13, v14, v22, s28
	v_add3_u32 v9, v9, v21, s28
	v_add3_u32 v8, v8, v20, s28
	v_lshrrev_b32_e32 v8, 16, v8
	v_lshrrev_b32_e32 v9, 16, v9
	v_lshrrev_b32_e32 v13, 16, v13
	v_lshrrev_b32_e32 v12, 16, v12
	v_and_or_b32 v11, v11, s21, v12
	v_and_or_b32 v10, v10, s21, v13
	v_and_or_b32 v9, v18, s21, v9
	v_and_or_b32 v8, v19, s21, v8
	global_store_dwordx4 v[0:1], v[8:11], off
	s_nop 1
	v_mov_b32_e32 v8, v64
	v_mov_b32_e32 v9, v65
	v_mov_b32_e32 v10, v66
	v_mov_b32_e32 v11, v67
	v_mov_b32_e32 v12, v68
	v_mov_b32_e32 v13, v69
	v_mov_b32_e32 v14, v70
	v_mov_b32_e32 v15, v71
	v_mov_b32_e32 v16, v72
	v_mov_b32_e32 v17, v73
	v_mov_b32_e32 v18, v74
	v_mov_b32_e32 v19, v75
	v_mov_b32_e32 v34, v79
	v_mov_b32_e32 v35, v80
	v_mov_b32_e32 v36, v81
	v_add_u32_e32 v148, 0x14800000, v154
	v_add_u32_e32 v149, 0x14801000, v154
	v_add_u32_e32 v150, 0x14802000, v154
	v_add_u32_e32 v151, 0xc200000, v155
	v_add_u32_e32 v152, 0xc300000, v155
	v_add_u32_e32 v153, 0xc400000, v155
	global_load_dwordx4 v[52:55], v149, s[26:27] offset:1024
	global_load_dword v76, v151, s[26:27]
	global_load_dwordx4 v[56:59], v149, s[26:27] offset:3072
	global_load_dword v77, v152, s[26:27]
	global_load_dword v78, v153, s[26:27]
	global_load_dwordx4 v[60:63], v148, s[26:27] offset:3072
	global_load_dword v79, v151, s[26:27] offset:16
	global_load_dword v80, v152, s[26:27] offset:16
	global_load_dword v81, v153, s[26:27] offset:16
	global_load_dwordx4 v[64:67], v149, s[26:27]
	global_load_dwordx4 v[68:71], v149, s[26:27] offset:2048
	global_load_dwordx4 v[72:75], v150, s[26:27]
	v_add_u32_e32 v154, s12, v154
	v_add_u32_e32 v155, s14, v155
	v_max3_f32 v32, v34, v35, v36
	v_sub_f32_e32 v33, v34, v32
	v_sub_f32_e32 v34, v35, v32
	v_sub_f32_e32 v32, v36, v32
	v_mul_f32_e32 v33, 0x3fb8aa3b, v33
	v_mul_f32_e32 v34, 0x3fb8aa3b, v34
	v_mul_f32_e32 v35, 0x3fb8aa3b, v32
	v_exp_f32_e32 v33, v33
	v_exp_f32_e32 v32, v34
	v_exp_f32_e32 v35, v35
	v_lshlrev_b32_e32 v21, 16, v9
	v_and_b32_e32 v23, 0xffff0000, v9
	v_add_f32_e32 v34, v33, v32
	v_add_f32_e32 v34, v35, v34
	v_div_scale_f32 v36, s[0:1], v34, v34, 1.0
	v_rcp_f32_e32 v38, v36
	v_div_scale_f32 v37, vcc, 1.0, v34, 1.0
	v_lshlrev_b32_e32 v25, 16, v13
	v_fma_f32 v39, -v36, v38, 1.0
	v_fmac_f32_e32 v38, v39, v38
	v_mul_f32_e32 v39, v37, v38
	v_fma_f32 v40, -v36, v39, v37
	v_fmac_f32_e32 v39, v40, v38
	v_fma_f32 v36, -v36, v39, v37
	v_div_fmas_f32 v36, v36, v38, v39
	v_div_fixup_f32 v34, v36, v34, 1.0
	v_lshlrev_b32_e32 v24, 16, v8
	v_and_b32_e32 v9, 0xffff0000, v13
	v_and_b32_e32 v8, 0xffff0000, v8
	v_lshlrev_b32_e32 v31, 16, v15
	v_lshlrev_b32_e32 v30, 16, v10
	v_pk_mul_f32 v[32:33], v[32:33], v[34:35] op_sel_hi:[1,0]
	v_lshlrev_b32_e32 v20, 16, v12
	v_and_b32_e32 v22, 0xffff0000, v12
	v_lshlrev_b32_e32 v27, 16, v11
	v_lshlrev_b32_e32 v26, 16, v14
	v_and_b32_e32 v29, 0xffff0000, v11
	v_and_b32_e32 v11, 0xffff0000, v15
	v_and_b32_e32 v10, 0xffff0000, v10
	v_pk_mul_f32 v[24:25], v[32:33], v[24:25] op_sel:[1,0] op_sel_hi:[0,1]
	v_pk_mul_f32 v[8:9], v[32:33], v[8:9] op_sel:[1,0] op_sel_hi:[0,1]
	v_pk_mul_f32 v[30:31], v[32:33], v[30:31] op_sel:[1,0] op_sel_hi:[0,1]
	v_lshlrev_b32_e32 v13, 16, v17
	v_lshlrev_b32_e32 v12, 16, v16
	v_and_b32_e32 v28, 0xffff0000, v14
	v_lshlrev_b32_e32 v15, 16, v19
	v_lshlrev_b32_e32 v14, 16, v18
	v_mul_f32_e32 v36, v35, v34
	v_pk_mul_f32 v[10:11], v[32:33], v[10:11] op_sel:[1,0] op_sel_hi:[0,1]
	v_pk_fma_f32 v[20:21], v[32:33], v[20:21], v[24:25]
	v_pk_fma_f32 v[8:9], v[32:33], v[22:23], v[8:9]
	v_pk_fma_f32 v[22:23], v[32:33], v[26:27], v[30:31]
	v_and_b32_e32 v17, 0xffff0000, v17
	v_and_b32_e32 v16, 0xffff0000, v16
	v_and_b32_e32 v19, 0xffff0000, v19
	v_and_b32_e32 v18, 0xffff0000, v18
	v_pk_fma_f32 v[10:11], v[32:33], v[28:29], v[10:11]
	v_pk_fma_f32 v[12:13], v[36:37], v[12:13], v[20:21] op_sel_hi:[0,1,1]
	v_pk_fma_f32 v[14:15], v[36:37], v[14:15], v[22:23] op_sel_hi:[0,1,1]
	v_pk_fma_f32 v[8:9], v[36:37], v[16:17], v[8:9] op_sel_hi:[0,1,1]
	v_pk_fma_f32 v[10:11], v[36:37], v[18:19], v[10:11] op_sel_hi:[0,1,1]
	v_bfe_u32 v20, v12, 16, 1
	v_bfe_u32 v21, v13, 16, 1
	v_bfe_u32 v22, v14, 16, 1
	v_bfe_u32 v23, v15, 16, 1
	v_bfe_u32 v16, v11, 16, 1
	v_bfe_u32 v17, v10, 16, 1
	v_bfe_u32 v18, v9, 16, 1
	v_bfe_u32 v19, v8, 16, 1
	v_add3_u32 v15, v15, v23, s28
	v_add3_u32 v14, v14, v22, s28
	v_add3_u32 v13, v13, v21, s28
	v_add3_u32 v12, v12, v20, s28
	v_add3_u32 v8, v8, v19, s28
	v_add3_u32 v9, v9, v18, s28
	v_add3_u32 v10, v10, v17, s28
	v_add3_u32 v11, v11, v16, s28
	v_lshrrev_b32_e32 v12, 16, v12
	v_lshrrev_b32_e32 v13, 16, v13
	v_lshrrev_b32_e32 v14, 16, v14
	v_lshrrev_b32_e32 v15, 16, v15
	v_and_or_b32 v11, v11, s21, v15
	v_and_or_b32 v10, v10, s21, v14
	v_and_or_b32 v9, v9, s21, v13
	v_and_or_b32 v8, v8, s21, v12
	global_store_dwordx4 v[0:1], v[8:11], off offset:1024
	v_lshl_add_u64 v[0:1], v[0:1], 0, s[4:5]
	s_nop 0
	s_waitcnt vmcnt(26)
; __device__ __forceinline__ unsigned pk2(float lo, float hi) { return f2bf(lo) | (f2bf(hi) << 16); }
; __global__ void __launch_bounds__(NWAVES * 64, 2) mk_fwd(Args args) {
;     ...
;                 const int e = j * 512 + lane * 8, h = e >> 7;
;                 const float l0 = LSE[((size_t)0 * MTOK + m) * 8 + h], l1 = LSE[((size_t)1 * MTOK + m) * 8 + h], l2 = LSE[((size_t)2 * MTOK + m) * 8 + h];
;                 const float mx = fmaxf(l0, fmaxf(l1, l2)); float w0 = __expf(l0 - mx), w1 = __expf(l1 - mx), w2 = __expf(l2 - mx);
;                 const float inv = 1.0f / (w0 + w1 + w2); w0 *= inv; w1 *= inv; w2 *= inv;
;                 const bf16r* p = PROJ + (size_t)m * INW + O_QB + e;
;                 const v4u a0 = *(const v4u*)p, a1 = *(const v4u*)(p + 1024), a2 = *(const v4u*)(p + 2048);
;                 v4u o;
; #pragma unroll
;                 for (int q = 0; q < 4; ++q) {
;                     const float x0 = __builtin_bit_cast(float, a0[q] << 16), y0 = __builtin_bit_cast(float, a0[q] & 0xffff0000u);
;                     const float x1 = __builtin_bit_cast(float, a1[q] << 16), y1 = __builtin_bit_cast(float, a1[q] & 0xffff0000u);
;                     const float x2 = __builtin_bit_cast(float, a2[q] << 16), y2 = __builtin_bit_cast(float, a2[q] & 0xffff0000u);
;                     o[q] = pk2(w0 * x0 + w1 * x1 + w2 * x2, w0 * y0 + w1 * y1 + w2 * y2);
;                 }
;                 *(v4u*)(MIX + (size_t)m * DM + 1024 + e) = o;
	v_mov_b32_e32 v10, v82
	v_mov_b32_e32 v11, v83
	v_mov_b32_e32 v12, v84
	v_mov_b32_e32 v13, v85
	v_mov_b32_e32 v14, v86
	v_mov_b32_e32 v15, v87
	v_mov_b32_e32 v16, v88
	v_mov_b32_e32 v17, v89
	v_mov_b32_e32 v18, v90
	v_mov_b32_e32 v19, v91
	v_mov_b32_e32 v20, v92
	v_mov_b32_e32 v21, v93
	v_mov_b32_e32 v46, v106
	v_mov_b32_e32 v47, v107
	v_mov_b32_e32 v48, v108
	v_lshlrev_b32_e32 v23, 16, v11
	v_and_b32_e32 v35, 0xffff0000, v11
	v_lshlrev_b32_e32 v41, 16, v13
	v_and_b32_e32 v43, 0xffff0000, v13
	v_lshlrev_b32_e32 v8, 16, v10
	v_and_b32_e32 v10, 0xffff0000, v10
	v_max3_f32 v49, v46, v47, v48
	v_lshlrev_b32_e32 v9, 16, v19
	v_and_b32_e32 v11, 0xffff0000, v19
	v_lshlrev_b32_e32 v22, 16, v18
	v_and_b32_e32 v34, 0xffff0000, v18
	v_sub_f32_e32 v18, v46, v49
	v_sub_f32_e32 v19, v47, v49
	v_lshlrev_b32_e32 v39, 16, v21
	v_and_b32_e32 v13, 0xffff0000, v21
	v_lshlrev_b32_e32 v40, 16, v20
	v_and_b32_e32 v42, 0xffff0000, v20
	v_sub_f32_e32 v20, v48, v49
	v_mul_f32_e32 v18, 0x3fb8aa3b, v18
	v_mul_f32_e32 v21, 0x3fb8aa3b, v19
	v_mul_f32_e32 v20, 0x3fb8aa3b, v20
	v_exp_f32_e32 v19, v18
	v_exp_f32_e32 v18, v21
	v_exp_f32_e32 v21, v20
	v_lshlrev_b32_e32 v38, 16, v12
	v_and_b32_e32 v12, 0xffff0000, v12
	v_add_f32_e32 v20, v19, v18
	v_add_f32_e32 v20, v21, v20
	v_div_scale_f32 v46, s[0:1], v20, v20, 1.0
	v_rcp_f32_e32 v48, v46
	v_div_scale_f32 v47, vcc, 1.0, v20, 1.0
	v_lshlrev_b32_e32 v37, 16, v15
	v_fma_f32 v49, -v46, v48, 1.0
	v_fmac_f32_e32 v48, v49, v48
	v_mul_f32_e32 v49, v47, v48
	v_fma_f32 v50, -v46, v49, v47
	v_fmac_f32_e32 v49, v50, v48
	v_fma_f32 v46, -v46, v49, v47
	v_div_fmas_f32 v46, v46, v48, v49
	v_div_fixup_f32 v20, v46, v20, 1.0
	v_pk_mul_f32 v[18:19], v[18:19], v[20:21] op_sel_hi:[1,0]
	v_mul_f32_e32 v46, v21, v20
	v_pk_mul_f32 v[20:21], v[18:19], v[22:23] op_sel:[1,0] op_sel_hi:[0,1]
	v_pk_mul_f32 v[22:23], v[18:19], v[34:35] op_sel:[1,0] op_sel_hi:[0,1]
	v_pk_mul_f32 v[34:35], v[18:19], v[40:41] op_sel:[1,0] op_sel_hi:[0,1]
	v_pk_mul_f32 v[40:41], v[18:19], v[42:43] op_sel:[1,0] op_sel_hi:[0,1]
	v_lshlrev_b32_e32 v36, 16, v14
	v_and_b32_e32 v15, 0xffff0000, v15
	v_and_b32_e32 v14, 0xffff0000, v14
	v_lshlrev_b32_e32 v45, 16, v17
	v_lshlrev_b32_e32 v44, 16, v16
	v_and_b32_e32 v17, 0xffff0000, v17
	v_and_b32_e32 v16, 0xffff0000, v16
	v_pk_fma_f32 v[8:9], v[18:19], v[8:9], v[20:21]
	v_pk_fma_f32 v[10:11], v[18:19], v[10:11], v[22:23]
	v_pk_fma_f32 v[20:21], v[18:19], v[38:39], v[34:35]
	v_pk_fma_f32 v[12:13], v[18:19], v[12:13], v[40:41]
	v_pk_fma_f32 v[8:9], v[46:47], v[36:37], v[8:9] op_sel_hi:[0,1,1]
	v_pk_fma_f32 v[10:11], v[46:47], v[14:15], v[10:11] op_sel_hi:[0,1,1]
	v_pk_fma_f32 v[14:15], v[46:47], v[44:45], v[20:21] op_sel_hi:[0,1,1]
	v_pk_fma_f32 v[12:13], v[46:47], v[16:17], v[12:13] op_sel_hi:[0,1,1]
	v_bfe_u32 v16, v13, 16, 1
	v_bfe_u32 v17, v12, 16, 1
	v_bfe_u32 v18, v11, 16, 1
	v_bfe_u32 v19, v10, 16, 1
	v_bfe_u32 v20, v8, 16, 1
	v_bfe_u32 v21, v9, 16, 1
	v_bfe_u32 v22, v14, 16, 1
	v_bfe_u32 v23, v15, 16, 1
	v_add3_u32 v19, v10, v19, s28
	v_add3_u32 v18, v11, v18, s28
	v_add3_u32 v10, v12, v17, s28
	v_add3_u32 v11, v13, v16, s28
	v_add3_u32 v12, v15, v23, s28
	v_add3_u32 v13, v14, v22, s28
	v_add3_u32 v9, v9, v21, s28
	v_add3_u32 v8, v8, v20, s28
	v_lshrrev_b32_e32 v8, 16, v8
	v_lshrrev_b32_e32 v9, 16, v9
	v_lshrrev_b32_e32 v13, 16, v13
	v_lshrrev_b32_e32 v12, 16, v12
	v_and_or_b32 v11, v11, s21, v12
	v_and_or_b32 v10, v10, s21, v13
	v_and_or_b32 v9, v18, s21, v9
	v_and_or_b32 v8, v19, s21, v8
	global_store_dwordx4 v[0:1], v[8:11], off
	s_nop 1
	v_mov_b32_e32 v8, v94
	v_mov_b32_e32 v9, v95
	v_mov_b32_e32 v10, v96
	v_mov_b32_e32 v11, v97
	v_mov_b32_e32 v12, v98
	v_mov_b32_e32 v13, v99
	v_mov_b32_e32 v14, v100
	v_mov_b32_e32 v15, v101
	v_mov_b32_e32 v16, v102
	v_mov_b32_e32 v17, v103
	v_mov_b32_e32 v18, v104
	v_mov_b32_e32 v19, v105
	v_mov_b32_e32 v34, v109
	v_mov_b32_e32 v35, v110
	v_mov_b32_e32 v36, v111
	v_add_u32_e32 v142, 0x14800000, v154
	v_add_u32_e32 v143, 0x14801000, v154
	v_add_u32_e32 v144, 0x14802000, v154
	v_add_u32_e32 v145, 0xc200000, v155
	v_add_u32_e32 v146, 0xc300000, v155
	v_add_u32_e32 v147, 0xc400000, v155
	global_load_dwordx4 v[82:85], v143, s[26:27] offset:1024
	global_load_dword v106, v145, s[26:27]
	global_load_dwordx4 v[86:89], v143, s[26:27] offset:3072
	global_load_dword v107, v146, s[26:27]
	global_load_dword v108, v147, s[26:27]
	global_load_dwordx4 v[90:93], v142, s[26:27] offset:3072
	global_load_dword v109, v145, s[26:27] offset:16
	global_load_dword v110, v146, s[26:27] offset:16
	global_load_dword v111, v147, s[26:27] offset:16
	global_load_dwordx4 v[94:97], v143, s[26:27]
	global_load_dwordx4 v[98:101], v143, s[26:27] offset:2048
	global_load_dwordx4 v[102:105], v144, s[26:27]
	v_add_u32_e32 v154, s12, v154
	v_add_u32_e32 v155, s14, v155
	v_max3_f32 v32, v34, v35, v36
	v_sub_f32_e32 v33, v34, v32
	v_sub_f32_e32 v34, v35, v32
	v_sub_f32_e32 v32, v36, v32
	v_mul_f32_e32 v33, 0x3fb8aa3b, v33
	v_mul_f32_e32 v34, 0x3fb8aa3b, v34
	v_mul_f32_e32 v35, 0x3fb8aa3b, v32
	v_exp_f32_e32 v33, v33
	v_exp_f32_e32 v32, v34
	v_exp_f32_e32 v35, v35
	v_lshlrev_b32_e32 v21, 16, v9
	v_and_b32_e32 v23, 0xffff0000, v9
	v_add_f32_e32 v34, v33, v32
	v_add_f32_e32 v34, v35, v34
	v_div_scale_f32 v36, s[0:1], v34, v34, 1.0
	v_rcp_f32_e32 v38, v36
	v_div_scale_f32 v37, vcc, 1.0, v34, 1.0
	v_lshlrev_b32_e32 v25, 16, v13
	v_fma_f32 v39, -v36, v38, 1.0
	v_fmac_f32_e32 v38, v39, v38
	v_mul_f32_e32 v39, v37, v38
	v_fma_f32 v40, -v36, v39, v37
	v_fmac_f32_e32 v39, v40, v38
	v_fma_f32 v36, -v36, v39, v37
	v_div_fmas_f32 v36, v36, v38, v39
	v_div_fixup_f32 v34, v36, v34, 1.0
	v_lshlrev_b32_e32 v24, 16, v8
	v_and_b32_e32 v9, 0xffff0000, v13
; __device__ __forceinline__ unsigned pk2(float lo, float hi) { return f2bf(lo) | (f2bf(hi) << 16); }
; __global__ void __launch_bounds__(NWAVES * 64, 2) mk_fwd(Args args) {
;     ...
;                 const int e = j * 512 + lane * 8, h = e >> 7;
;                 const float l0 = LSE[((size_t)0 * MTOK + m) * 8 + h], l1 = LSE[((size_t)1 * MTOK + m) * 8 + h], l2 = LSE[((size_t)2 * MTOK + m) * 8 + h];
;                 const float mx = fmaxf(l0, fmaxf(l1, l2)); float w0 = __expf(l0 - mx), w1 = __expf(l1 - mx), w2 = __expf(l2 - mx);
;                 const float inv = 1.0f / (w0 + w1 + w2); w0 *= inv; w1 *= inv; w2 *= inv;
;                 const bf16r* p = PROJ + (size_t)m * INW + O_QB + e;
;                 const v4u a0 = *(const v4u*)p, a1 = *(const v4u*)(p + 1024), a2 = *(const v4u*)(p + 2048);
;                 v4u o;
; #pragma unroll
;                 for (int q = 0; q < 4; ++q) {
;                     const float x0 = __builtin_bit_cast(float, a0[q] << 16), y0 = __builtin_bit_cast(float, a0[q] & 0xffff0000u);
;                     const float x1 = __builtin_bit_cast(float, a1[q] << 16), y1 = __builtin_bit_cast(float, a1[q] & 0xffff0000u);
;                     const float x2 = __builtin_bit_cast(float, a2[q] << 16), y2 = __builtin_bit_cast(float, a2[q] & 0xffff0000u);
;                     o[q] = pk2(w0 * x0 + w1 * x1 + w2 * x2, w0 * y0 + w1 * y1 + w2 * y2);
;                 }
;                 *(v4u*)(MIX + (size_t)m * DM + 1024 + e) = o;
	v_and_b32_e32 v8, 0xffff0000, v8
	v_lshlrev_b32_e32 v31, 16, v15
	v_lshlrev_b32_e32 v30, 16, v10
	v_pk_mul_f32 v[32:33], v[32:33], v[34:35] op_sel_hi:[1,0]
	v_lshlrev_b32_e32 v20, 16, v12
	v_and_b32_e32 v22, 0xffff0000, v12
	v_lshlrev_b32_e32 v27, 16, v11
	v_lshlrev_b32_e32 v26, 16, v14
	v_and_b32_e32 v29, 0xffff0000, v11
	v_and_b32_e32 v11, 0xffff0000, v15
	v_and_b32_e32 v10, 0xffff0000, v10
	v_pk_mul_f32 v[24:25], v[32:33], v[24:25] op_sel:[1,0] op_sel_hi:[0,1]
	v_pk_mul_f32 v[8:9], v[32:33], v[8:9] op_sel:[1,0] op_sel_hi:[0,1]
	v_pk_mul_f32 v[30:31], v[32:33], v[30:31] op_sel:[1,0] op_sel_hi:[0,1]
	v_lshlrev_b32_e32 v13, 16, v17
	v_lshlrev_b32_e32 v12, 16, v16
	v_and_b32_e32 v28, 0xffff0000, v14
	v_lshlrev_b32_e32 v15, 16, v19
	v_lshlrev_b32_e32 v14, 16, v18
	v_mul_f32_e32 v36, v35, v34
	v_pk_mul_f32 v[10:11], v[32:33], v[10:11] op_sel:[1,0] op_sel_hi:[0,1]
	v_pk_fma_f32 v[20:21], v[32:33], v[20:21], v[24:25]
	v_pk_fma_f32 v[8:9], v[32:33], v[22:23], v[8:9]
	v_pk_fma_f32 v[22:23], v[32:33], v[26:27], v[30:31]
	v_and_b32_e32 v17, 0xffff0000, v17
	v_and_b32_e32 v16, 0xffff0000, v16
	v_and_b32_e32 v19, 0xffff0000, v19
	v_and_b32_e32 v18, 0xffff0000, v18
	v_pk_fma_f32 v[10:11], v[32:33], v[28:29], v[10:11]
	v_pk_fma_f32 v[12:13], v[36:37], v[12:13], v[20:21] op_sel_hi:[0,1,1]
	v_pk_fma_f32 v[14:15], v[36:37], v[14:15], v[22:23] op_sel_hi:[0,1,1]
	v_pk_fma_f32 v[8:9], v[36:37], v[16:17], v[8:9] op_sel_hi:[0,1,1]
	v_pk_fma_f32 v[10:11], v[36:37], v[18:19], v[10:11] op_sel_hi:[0,1,1]
	v_bfe_u32 v20, v12, 16, 1
	v_bfe_u32 v21, v13, 16, 1
	v_bfe_u32 v22, v14, 16, 1
	v_bfe_u32 v23, v15, 16, 1
	v_bfe_u32 v16, v11, 16, 1
	v_bfe_u32 v17, v10, 16, 1
	v_bfe_u32 v18, v9, 16, 1
	v_bfe_u32 v19, v8, 16, 1
	v_add3_u32 v15, v15, v23, s28
	v_add3_u32 v14, v14, v22, s28
	v_add3_u32 v13, v13, v21, s28
	v_add3_u32 v12, v12, v20, s28
	v_add3_u32 v8, v8, v19, s28
	v_add3_u32 v9, v9, v18, s28
	v_add3_u32 v10, v10, v17, s28
	v_add3_u32 v11, v11, v16, s28
	v_lshrrev_b32_e32 v12, 16, v12
	v_lshrrev_b32_e32 v13, 16, v13
	v_lshrrev_b32_e32 v14, 16, v14
	v_lshrrev_b32_e32 v15, 16, v15
	v_and_or_b32 v11, v11, s21, v15
	v_and_or_b32 v10, v10, s21, v14
	v_and_or_b32 v9, v9, s21, v13
	v_and_or_b32 v8, v8, s21, v12
	global_store_dwordx4 v[0:1], v[8:11], off offset:1024
	v_lshl_add_u64 v[0:1], v[0:1], 0, s[4:5]
	s_nop 0
	s_waitcnt vmcnt(28)
	v_mov_b32_e32 v10, v112
	v_mov_b32_e32 v11, v113
	v_mov_b32_e32 v12, v114
	v_mov_b32_e32 v13, v115
	v_mov_b32_e32 v14, v116
	v_mov_b32_e32 v15, v117
	v_mov_b32_e32 v16, v118
	v_mov_b32_e32 v17, v119
	v_mov_b32_e32 v18, v120
	v_mov_b32_e32 v19, v121
	v_mov_b32_e32 v20, v122
	v_mov_b32_e32 v21, v123
	v_mov_b32_e32 v46, v136
	v_mov_b32_e32 v47, v137
	v_mov_b32_e32 v48, v138
	v_lshlrev_b32_e32 v23, 16, v11
	v_and_b32_e32 v35, 0xffff0000, v11
	v_lshlrev_b32_e32 v41, 16, v13
	v_and_b32_e32 v43, 0xffff0000, v13
	v_lshlrev_b32_e32 v8, 16, v10
	v_and_b32_e32 v10, 0xffff0000, v10
	v_max3_f32 v49, v46, v47, v48
	v_lshlrev_b32_e32 v9, 16, v19
	v_and_b32_e32 v11, 0xffff0000, v19
	v_lshlrev_b32_e32 v22, 16, v18
	v_and_b32_e32 v34, 0xffff0000, v18
	v_sub_f32_e32 v18, v46, v49
	v_sub_f32_e32 v19, v47, v49
	v_lshlrev_b32_e32 v39, 16, v21
	v_and_b32_e32 v13, 0xffff0000, v21
	v_lshlrev_b32_e32 v40, 16, v20
	v_and_b32_e32 v42, 0xffff0000, v20
	v_sub_f32_e32 v20, v48, v49
	v_mul_f32_e32 v18, 0x3fb8aa3b, v18
	v_mul_f32_e32 v21, 0x3fb8aa3b, v19
	v_mul_f32_e32 v20, 0x3fb8aa3b, v20
	v_exp_f32_e32 v19, v18
	v_exp_f32_e32 v18, v21
	v_exp_f32_e32 v21, v20
	v_lshlrev_b32_e32 v38, 16, v12
	v_and_b32_e32 v12, 0xffff0000, v12
	v_add_f32_e32 v20, v19, v18
	v_add_f32_e32 v20, v21, v20
	v_div_scale_f32 v46, s[0:1], v20, v20, 1.0
	v_rcp_f32_e32 v48, v46
	v_div_scale_f32 v47, vcc, 1.0, v20, 1.0
	v_lshlrev_b32_e32 v37, 16, v15
	v_fma_f32 v49, -v46, v48, 1.0
	v_fmac_f32_e32 v48, v49, v48
	v_mul_f32_e32 v49, v47, v48
	v_fma_f32 v50, -v46, v49, v47
	v_fmac_f32_e32 v49, v50, v48
	v_fma_f32 v46, -v46, v49, v47
	v_div_fmas_f32 v46, v46, v48, v49
	v_div_fixup_f32 v20, v46, v20, 1.0
	v_pk_mul_f32 v[18:19], v[18:19], v[20:21] op_sel_hi:[1,0]
	v_mul_f32_e32 v46, v21, v20
	v_pk_mul_f32 v[20:21], v[18:19], v[22:23] op_sel:[1,0] op_sel_hi:[0,1]
	v_pk_mul_f32 v[22:23], v[18:19], v[34:35] op_sel:[1,0] op_sel_hi:[0,1]
	v_pk_mul_f32 v[34:35], v[18:19], v[40:41] op_sel:[1,0] op_sel_hi:[0,1]
	v_pk_mul_f32 v[40:41], v[18:19], v[42:43] op_sel:[1,0] op_sel_hi:[0,1]
	v_lshlrev_b32_e32 v36, 16, v14
	v_and_b32_e32 v15, 0xffff0000, v15
	v_and_b32_e32 v14, 0xffff0000, v14
	v_lshlrev_b32_e32 v45, 16, v17
	v_lshlrev_b32_e32 v44, 16, v16
	v_and_b32_e32 v17, 0xffff0000, v17
	v_and_b32_e32 v16, 0xffff0000, v16
	v_pk_fma_f32 v[8:9], v[18:19], v[8:9], v[20:21]
	v_pk_fma_f32 v[10:11], v[18:19], v[10:11], v[22:23]
	v_pk_fma_f32 v[20:21], v[18:19], v[38:39], v[34:35]
	v_pk_fma_f32 v[12:13], v[18:19], v[12:13], v[40:41]
	v_pk_fma_f32 v[8:9], v[46:47], v[36:37], v[8:9] op_sel_hi:[0,1,1]
	v_pk_fma_f32 v[10:11], v[46:47], v[14:15], v[10:11] op_sel_hi:[0,1,1]
	v_pk_fma_f32 v[14:15], v[46:47], v[44:45], v[20:21] op_sel_hi:[0,1,1]
	v_pk_fma_f32 v[12:13], v[46:47], v[16:17], v[12:13] op_sel_hi:[0,1,1]
	v_bfe_u32 v16, v13, 16, 1
	v_bfe_u32 v17, v12, 16, 1
	v_bfe_u32 v18, v11, 16, 1
	v_bfe_u32 v19, v10, 16, 1
	v_bfe_u32 v20, v8, 16, 1
	v_bfe_u32 v21, v9, 16, 1
	v_bfe_u32 v22, v14, 16, 1
	v_bfe_u32 v23, v15, 16, 1
	v_add3_u32 v19, v10, v19, s28
	v_add3_u32 v18, v11, v18, s28
	v_add3_u32 v10, v12, v17, s28
	v_add3_u32 v11, v13, v16, s28
	v_add3_u32 v12, v15, v23, s28
	v_add3_u32 v13, v14, v22, s28
	v_add3_u32 v9, v9, v21, s28
	v_add3_u32 v8, v8, v20, s28
	v_lshrrev_b32_e32 v8, 16, v8
	v_lshrrev_b32_e32 v9, 16, v9
; __device__ __forceinline__ unsigned pk2(float lo, float hi) { return f2bf(lo) | (f2bf(hi) << 16); }
; __global__ void __launch_bounds__(NWAVES * 64, 2) mk_fwd(Args args) {
;     ...
;                 const int e = j * 512 + lane * 8, h = e >> 7;
;                 const float l0 = LSE[((size_t)0 * MTOK + m) * 8 + h], l1 = LSE[((size_t)1 * MTOK + m) * 8 + h], l2 = LSE[((size_t)2 * MTOK + m) * 8 + h];
;                 const float mx = fmaxf(l0, fmaxf(l1, l2)); float w0 = __expf(l0 - mx), w1 = __expf(l1 - mx), w2 = __expf(l2 - mx);
;                 const float inv = 1.0f / (w0 + w1 + w2); w0 *= inv; w1 *= inv; w2 *= inv;
;                 const bf16r* p = PROJ + (size_t)m * INW + O_QB + e;
;                 const v4u a0 = *(const v4u*)p, a1 = *(const v4u*)(p + 1024), a2 = *(const v4u*)(p + 2048);
;                 v4u o;
; #pragma unroll
;                 for (int q = 0; q < 4; ++q) {
;                     const float x0 = __builtin_bit_cast(float, a0[q] << 16), y0 = __builtin_bit_cast(float, a0[q] & 0xffff0000u);
;                     const float x1 = __builtin_bit_cast(float, a1[q] << 16), y1 = __builtin_bit_cast(float, a1[q] & 0xffff0000u);
;                     const float x2 = __builtin_bit_cast(float, a2[q] << 16), y2 = __builtin_bit_cast(float, a2[q] & 0xffff0000u);
;                     o[q] = pk2(w0 * x0 + w1 * x1 + w2 * x2, w0 * y0 + w1 * y1 + w2 * y2);
;                 }
;                 *(v4u*)(MIX + (size_t)m * DM + 1024 + e) = o;
	v_lshrrev_b32_e32 v13, 16, v13
	v_lshrrev_b32_e32 v12, 16, v12
	v_and_or_b32 v11, v11, s21, v12
	v_and_or_b32 v10, v10, s21, v13
	v_and_or_b32 v9, v18, s21, v9
	v_and_or_b32 v8, v19, s21, v8
	global_store_dwordx4 v[0:1], v[8:11], off
	s_nop 1
	v_mov_b32_e32 v8, v124
	v_mov_b32_e32 v9, v125
	v_mov_b32_e32 v10, v126
	v_mov_b32_e32 v11, v127
	v_mov_b32_e32 v12, v128
	v_mov_b32_e32 v13, v129
	v_mov_b32_e32 v14, v130
	v_mov_b32_e32 v15, v131
	v_mov_b32_e32 v16, v132
	v_mov_b32_e32 v17, v133
	v_mov_b32_e32 v18, v134
	v_mov_b32_e32 v19, v135
	v_mov_b32_e32 v34, v139
	v_mov_b32_e32 v35, v140
	v_mov_b32_e32 v36, v141
	v_add_u32_e32 v148, 0x14800000, v154
	v_add_u32_e32 v149, 0x14801000, v154
	v_add_u32_e32 v150, 0x14802000, v154
	v_add_u32_e32 v151, 0xc200000, v155
	v_add_u32_e32 v152, 0xc300000, v155
	v_add_u32_e32 v153, 0xc400000, v155
	global_load_dwordx4 v[112:115], v149, s[26:27] offset:1024
	global_load_dword v136, v151, s[26:27]
	global_load_dwordx4 v[116:119], v149, s[26:27] offset:3072
	global_load_dword v137, v152, s[26:27]
	global_load_dword v138, v153, s[26:27]
	global_load_dwordx4 v[120:123], v148, s[26:27] offset:3072
	global_load_dword v139, v151, s[26:27] offset:16
	global_load_dword v140, v152, s[26:27] offset:16
	global_load_dword v141, v153, s[26:27] offset:16
	global_load_dwordx4 v[124:127], v149, s[26:27]
	global_load_dwordx4 v[128:131], v149, s[26:27] offset:2048
	global_load_dwordx4 v[132:135], v150, s[26:27]
	v_add_u32_e32 v154, s12, v154
	v_add_u32_e32 v155, s14, v155
	v_max3_f32 v32, v34, v35, v36
	v_sub_f32_e32 v33, v34, v32
	v_sub_f32_e32 v34, v35, v32
	v_sub_f32_e32 v32, v36, v32
	v_mul_f32_e32 v33, 0x3fb8aa3b, v33
	v_mul_f32_e32 v34, 0x3fb8aa3b, v34
	v_mul_f32_e32 v35, 0x3fb8aa3b, v32
	v_exp_f32_e32 v33, v33
	v_exp_f32_e32 v32, v34
	v_exp_f32_e32 v35, v35
	v_lshlrev_b32_e32 v21, 16, v9
	v_and_b32_e32 v23, 0xffff0000, v9
	v_add_f32_e32 v34, v33, v32
	v_add_f32_e32 v34, v35, v34
	v_div_scale_f32 v36, s[0:1], v34, v34, 1.0
	v_rcp_f32_e32 v38, v36
	v_div_scale_f32 v37, vcc, 1.0, v34, 1.0
	v_lshlrev_b32_e32 v25, 16, v13
	v_fma_f32 v39, -v36, v38, 1.0
	v_fmac_f32_e32 v38, v39, v38
	v_mul_f32_e32 v39, v37, v38
	v_fma_f32 v40, -v36, v39, v37
	v_fmac_f32_e32 v39, v40, v38
	v_fma_f32 v36, -v36, v39, v37
	v_div_fmas_f32 v36, v36, v38, v39
	v_div_fixup_f32 v34, v36, v34, 1.0
	v_lshlrev_b32_e32 v24, 16, v8
	v_and_b32_e32 v9, 0xffff0000, v13
	v_and_b32_e32 v8, 0xffff0000, v8
	v_lshlrev_b32_e32 v31, 16, v15
	v_lshlrev_b32_e32 v30, 16, v10
	v_pk_mul_f32 v[32:33], v[32:33], v[34:35] op_sel_hi:[1,0]
	v_lshlrev_b32_e32 v20, 16, v12
	v_and_b32_e32 v22, 0xffff0000, v12
	v_lshlrev_b32_e32 v27, 16, v11
	v_lshlrev_b32_e32 v26, 16, v14
	v_and_b32_e32 v29, 0xffff0000, v11
	v_and_b32_e32 v11, 0xffff0000, v15
	v_and_b32_e32 v10, 0xffff0000, v10
	v_pk_mul_f32 v[24:25], v[32:33], v[24:25] op_sel:[1,0] op_sel_hi:[0,1]
	v_pk_mul_f32 v[8:9], v[32:33], v[8:9] op_sel:[1,0] op_sel_hi:[0,1]
	v_pk_mul_f32 v[30:31], v[32:33], v[30:31] op_sel:[1,0] op_sel_hi:[0,1]
	v_lshlrev_b32_e32 v13, 16, v17
	v_lshlrev_b32_e32 v12, 16, v16
	v_and_b32_e32 v28, 0xffff0000, v14
	v_lshlrev_b32_e32 v15, 16, v19
	v_lshlrev_b32_e32 v14, 16, v18
	v_mul_f32_e32 v36, v35, v34
	v_pk_mul_f32 v[10:11], v[32:33], v[10:11] op_sel:[1,0] op_sel_hi:[0,1]
	v_pk_fma_f32 v[20:21], v[32:33], v[20:21], v[24:25]
	v_pk_fma_f32 v[8:9], v[32:33], v[22:23], v[8:9]
	v_pk_fma_f32 v[22:23], v[32:33], v[26:27], v[30:31]
	v_and_b32_e32 v17, 0xffff0000, v17
	v_and_b32_e32 v16, 0xffff0000, v16
	v_and_b32_e32 v19, 0xffff0000, v19
	v_and_b32_e32 v18, 0xffff0000, v18
	v_pk_fma_f32 v[10:11], v[32:33], v[28:29], v[10:11]
	v_pk_fma_f32 v[12:13], v[36:37], v[12:13], v[20:21] op_sel_hi:[0,1,1]
	v_pk_fma_f32 v[14:15], v[36:37], v[14:15], v[22:23] op_sel_hi:[0,1,1]
	v_pk_fma_f32 v[8:9], v[36:37], v[16:17], v[8:9] op_sel_hi:[0,1,1]
	v_pk_fma_f32 v[10:11], v[36:37], v[18:19], v[10:11] op_sel_hi:[0,1,1]
	v_bfe_u32 v20, v12, 16, 1
	v_bfe_u32 v21, v13, 16, 1
	v_bfe_u32 v22, v14, 16, 1
	v_bfe_u32 v23, v15, 16, 1
	v_bfe_u32 v16, v11, 16, 1
	v_bfe_u32 v17, v10, 16, 1
	v_bfe_u32 v18, v9, 16, 1
	v_bfe_u32 v19, v8, 16, 1
	v_add3_u32 v15, v15, v23, s28
	v_add3_u32 v14, v14, v22, s28
	v_add3_u32 v13, v13, v21, s28
	v_add3_u32 v12, v12, v20, s28
	v_add3_u32 v8, v8, v19, s28
	v_add3_u32 v9, v9, v18, s28
	v_add3_u32 v10, v10, v17, s28
	v_add3_u32 v11, v11, v16, s28
	v_lshrrev_b32_e32 v12, 16, v12
	v_lshrrev_b32_e32 v13, 16, v13
	v_lshrrev_b32_e32 v14, 16, v14
	v_lshrrev_b32_e32 v15, 16, v15
	v_and_or_b32 v11, v11, s21, v15
	v_and_or_b32 v10, v10, s21, v14
	v_and_or_b32 v9, v9, s21, v13
	v_and_or_b32 v8, v8, s21, v12
	global_store_dwordx4 v[0:1], v[8:11], off offset:1024
	v_lshl_add_u64 v[0:1], v[0:1], 0, s[4:5]
	s_nop 0
	s_waitcnt vmcnt(29)
; __device__ __forceinline__ unsigned pk2(float lo, float hi) { return f2bf(lo) | (f2bf(hi) << 16); }
; __global__ void __launch_bounds__(NWAVES * 64, 2) mk_fwd(Args args) {
;     ...
;                 const int e = j * 512 + lane * 8, h = e >> 7;
;                 const float l0 = LSE[((size_t)0 * MTOK + m) * 8 + h], l1 = LSE[((size_t)1 * MTOK + m) * 8 + h], l2 = LSE[((size_t)2 * MTOK + m) * 8 + h];
;                 const float mx = fmaxf(l0, fmaxf(l1, l2)); float w0 = __expf(l0 - mx), w1 = __expf(l1 - mx), w2 = __expf(l2 - mx);
;                 const float inv = 1.0f / (w0 + w1 + w2); w0 *= inv; w1 *= inv; w2 *= inv;
;                 const bf16r* p = PROJ + (size_t)m * INW + O_QB + e;
;                 const v4u a0 = *(const v4u*)p, a1 = *(const v4u*)(p + 1024), a2 = *(const v4u*)(p + 2048);
;                 v4u o;
; #pragma unroll
;                 for (int q = 0; q < 4; ++q) {
;                     const float x0 = __builtin_bit_cast(float, a0[q] << 16), y0 = __builtin_bit_cast(float, a0[q] & 0xffff0000u);
;                     const float x1 = __builtin_bit_cast(float, a1[q] << 16), y1 = __builtin_bit_cast(float, a1[q] & 0xffff0000u);
;                     const float x2 = __builtin_bit_cast(float, a2[q] << 16), y2 = __builtin_bit_cast(float, a2[q] & 0xffff0000u);
;                     o[q] = pk2(w0 * x0 + w1 * x1 + w2 * x2, w0 * y0 + w1 * y1 + w2 * y2);
;                 }
;                 *(v4u*)(MIX + (size_t)m * DM + 1024 + e) = o;
	v_mov_b32_e32 v10, v52
	v_mov_b32_e32 v11, v53
	v_mov_b32_e32 v12, v54
	v_mov_b32_e32 v13, v55
	v_mov_b32_e32 v14, v56
	v_mov_b32_e32 v15, v57
	v_mov_b32_e32 v16, v58
	v_mov_b32_e32 v17, v59
	v_mov_b32_e32 v18, v60
	v_mov_b32_e32 v19, v61
	v_mov_b32_e32 v20, v62
	v_mov_b32_e32 v21, v63
	v_mov_b32_e32 v46, v76
	v_mov_b32_e32 v47, v77
	v_mov_b32_e32 v48, v78
	v_lshlrev_b32_e32 v23, 16, v11
	v_and_b32_e32 v35, 0xffff0000, v11
	v_lshlrev_b32_e32 v41, 16, v13
	v_and_b32_e32 v43, 0xffff0000, v13
	v_lshlrev_b32_e32 v8, 16, v10
	v_and_b32_e32 v10, 0xffff0000, v10
	v_max3_f32 v49, v46, v47, v48
	v_lshlrev_b32_e32 v9, 16, v19
	v_and_b32_e32 v11, 0xffff0000, v19
	v_lshlrev_b32_e32 v22, 16, v18
	v_and_b32_e32 v34, 0xffff0000, v18
	v_sub_f32_e32 v18, v46, v49
	v_sub_f32_e32 v19, v47, v49
	v_lshlrev_b32_e32 v39, 16, v21
	v_and_b32_e32 v13, 0xffff0000, v21
	v_lshlrev_b32_e32 v40, 16, v20
	v_and_b32_e32 v42, 0xffff0000, v20
	v_sub_f32_e32 v20, v48, v49
	v_mul_f32_e32 v18, 0x3fb8aa3b, v18
	v_mul_f32_e32 v21, 0x3fb8aa3b, v19
	v_mul_f32_e32 v20, 0x3fb8aa3b, v20
	v_exp_f32_e32 v19, v18
	v_exp_f32_e32 v18, v21
	v_exp_f32_e32 v21, v20
	v_lshlrev_b32_e32 v38, 16, v12
	v_and_b32_e32 v12, 0xffff0000, v12
	v_add_f32_e32 v20, v19, v18
	v_add_f32_e32 v20, v21, v20
	v_div_scale_f32 v46, s[0:1], v20, v20, 1.0
	v_rcp_f32_e32 v48, v46
	v_div_scale_f32 v47, vcc, 1.0, v20, 1.0
	v_lshlrev_b32_e32 v37, 16, v15
	v_fma_f32 v49, -v46, v48, 1.0
	v_fmac_f32_e32 v48, v49, v48
	v_mul_f32_e32 v49, v47, v48
	v_fma_f32 v50, -v46, v49, v47
	v_fmac_f32_e32 v49, v50, v48
	v_fma_f32 v46, -v46, v49, v47
	v_div_fmas_f32 v46, v46, v48, v49
	v_div_fixup_f32 v20, v46, v20, 1.0
	v_pk_mul_f32 v[18:19], v[18:19], v[20:21] op_sel_hi:[1,0]
	v_mul_f32_e32 v46, v21, v20
	v_pk_mul_f32 v[20:21], v[18:19], v[22:23] op_sel:[1,0] op_sel_hi:[0,1]
	v_pk_mul_f32 v[22:23], v[18:19], v[34:35] op_sel:[1,0] op_sel_hi:[0,1]
	v_pk_mul_f32 v[34:35], v[18:19], v[40:41] op_sel:[1,0] op_sel_hi:[0,1]
	v_pk_mul_f32 v[40:41], v[18:19], v[42:43] op_sel:[1,0] op_sel_hi:[0,1]
	v_lshlrev_b32_e32 v36, 16, v14
	v_and_b32_e32 v15, 0xffff0000, v15
	v_and_b32_e32 v14, 0xffff0000, v14
	v_lshlrev_b32_e32 v45, 16, v17
	v_lshlrev_b32_e32 v44, 16, v16
	v_and_b32_e32 v17, 0xffff0000, v17
	v_and_b32_e32 v16, 0xffff0000, v16
	v_pk_fma_f32 v[8:9], v[18:19], v[8:9], v[20:21]
	v_pk_fma_f32 v[10:11], v[18:19], v[10:11], v[22:23]
	v_pk_fma_f32 v[20:21], v[18:19], v[38:39], v[34:35]
	v_pk_fma_f32 v[12:13], v[18:19], v[12:13], v[40:41]
	v_pk_fma_f32 v[8:9], v[46:47], v[36:37], v[8:9] op_sel_hi:[0,1,1]
	v_pk_fma_f32 v[10:11], v[46:47], v[14:15], v[10:11] op_sel_hi:[0,1,1]
	v_pk_fma_f32 v[14:15], v[46:47], v[44:45], v[20:21] op_sel_hi:[0,1,1]
	v_pk_fma_f32 v[12:13], v[46:47], v[16:17], v[12:13] op_sel_hi:[0,1,1]
	v_bfe_u32 v16, v13, 16, 1
	v_bfe_u32 v17, v12, 16, 1
	v_bfe_u32 v18, v11, 16, 1
	v_bfe_u32 v19, v10, 16, 1
	v_bfe_u32 v20, v8, 16, 1
	v_bfe_u32 v21, v9, 16, 1
	v_bfe_u32 v22, v14, 16, 1
	v_bfe_u32 v23, v15, 16, 1
	v_add3_u32 v19, v10, v19, s28
	v_add3_u32 v18, v11, v18, s28
	v_add3_u32 v10, v12, v17, s28
	v_add3_u32 v11, v13, v16, s28
	v_add3_u32 v12, v15, v23, s28
	v_add3_u32 v13, v14, v22, s28
	v_add3_u32 v9, v9, v21, s28
	v_add3_u32 v8, v8, v20, s28
	v_lshrrev_b32_e32 v8, 16, v8
	v_lshrrev_b32_e32 v9, 16, v9
	v_lshrrev_b32_e32 v13, 16, v13
	v_lshrrev_b32_e32 v12, 16, v12
	v_and_or_b32 v11, v11, s21, v12
	v_and_or_b32 v10, v10, s21, v13
	v_and_or_b32 v9, v18, s21, v9
	v_and_or_b32 v8, v19, s21, v8
	global_store_dwordx4 v[0:1], v[8:11], off
	s_nop 1
	v_mov_b32_e32 v8, v64
	v_mov_b32_e32 v9, v65
	v_mov_b32_e32 v10, v66
	v_mov_b32_e32 v11, v67
	v_mov_b32_e32 v12, v68
	v_mov_b32_e32 v13, v69
	v_mov_b32_e32 v14, v70
	v_mov_b32_e32 v15, v71
	v_mov_b32_e32 v16, v72
	v_mov_b32_e32 v17, v73
	v_mov_b32_e32 v18, v74
	v_mov_b32_e32 v19, v75
	v_mov_b32_e32 v34, v79
	v_mov_b32_e32 v35, v80
	v_mov_b32_e32 v36, v81
	v_add_u32_e32 v142, 0x14800000, v154
	v_add_u32_e32 v143, 0x14801000, v154
	v_add_u32_e32 v144, 0x14802000, v154
	v_add_u32_e32 v145, 0xc200000, v155
	v_add_u32_e32 v146, 0xc300000, v155
	v_add_u32_e32 v147, 0xc400000, v155
	global_load_dwordx4 v[52:55], v143, s[26:27] offset:1024
	global_load_dword v76, v145, s[26:27]
	global_load_dwordx4 v[56:59], v143, s[26:27] offset:3072
	global_load_dword v77, v146, s[26:27]
	global_load_dword v78, v147, s[26:27]
	global_load_dwordx4 v[60:63], v142, s[26:27] offset:3072
	global_load_dword v79, v145, s[26:27] offset:16
	global_load_dword v80, v146, s[26:27] offset:16
	global_load_dword v81, v147, s[26:27] offset:16
	global_load_dwordx4 v[64:67], v143, s[26:27]
	global_load_dwordx4 v[68:71], v143, s[26:27] offset:2048
	global_load_dwordx4 v[72:75], v144, s[26:27]
	v_add_u32_e32 v154, s12, v154
	v_add_u32_e32 v155, s14, v155
	v_max3_f32 v32, v34, v35, v36
	v_sub_f32_e32 v33, v34, v32
	v_sub_f32_e32 v34, v35, v32
	v_sub_f32_e32 v32, v36, v32
	v_mul_f32_e32 v33, 0x3fb8aa3b, v33
	v_mul_f32_e32 v34, 0x3fb8aa3b, v34
	v_mul_f32_e32 v35, 0x3fb8aa3b, v32
	v_exp_f32_e32 v33, v33
	v_exp_f32_e32 v32, v34
	v_exp_f32_e32 v35, v35
	v_lshlrev_b32_e32 v21, 16, v9
	v_and_b32_e32 v23, 0xffff0000, v9
	v_add_f32_e32 v34, v33, v32
	v_add_f32_e32 v34, v35, v34
	v_div_scale_f32 v36, s[0:1], v34, v34, 1.0
	v_rcp_f32_e32 v38, v36
	v_div_scale_f32 v37, vcc, 1.0, v34, 1.0
	v_lshlrev_b32_e32 v25, 16, v13
	v_fma_f32 v39, -v36, v38, 1.0
	v_fmac_f32_e32 v38, v39, v38
	v_mul_f32_e32 v39, v37, v38
	v_fma_f32 v40, -v36, v39, v37
	v_fmac_f32_e32 v39, v40, v38
	v_fma_f32 v36, -v36, v39, v37
	v_div_fmas_f32 v36, v36, v38, v39
	v_div_fixup_f32 v34, v36, v34, 1.0
	v_lshlrev_b32_e32 v24, 16, v8
	v_and_b32_e32 v9, 0xffff0000, v13
; __device__ __forceinline__ unsigned pk2(float lo, float hi) { return f2bf(lo) | (f2bf(hi) << 16); }
; __global__ void __launch_bounds__(NWAVES * 64, 2) mk_fwd(Args args) {
;     ...
;         for (int m = gw; m < MTOK; m += NGW) {
; #pragma unroll
;             for (int j = 0; j < 2; ++j) {
;                 const int e = j * 512 + lane * 8, h = e >> 7;
;                 const float l0 = LSE[((size_t)0 * MTOK + m) * 8 + h], l1 = LSE[((size_t)1 * MTOK + m) * 8 + h], l2 = LSE[((size_t)2 * MTOK + m) * 8 + h];
;                 const float mx = fmaxf(l0, fmaxf(l1, l2)); float w0 = __expf(l0 - mx), w1 = __expf(l1 - mx), w2 = __expf(l2 - mx);
;                 const float inv = 1.0f / (w0 + w1 + w2); w0 *= inv; w1 *= inv; w2 *= inv;
;                 const bf16r* p = PROJ + (size_t)m * INW + O_QB + e;
;                 const v4u a0 = *(const v4u*)p, a1 = *(const v4u*)(p + 1024), a2 = *(const v4u*)(p + 2048);
;                 v4u o;
; #pragma unroll
;                 for (int q = 0; q < 4; ++q) {
;                     const float x0 = __builtin_bit_cast(float, a0[q] << 16), y0 = __builtin_bit_cast(float, a0[q] & 0xffff0000u);
;                     const float x1 = __builtin_bit_cast(float, a1[q] << 16), y1 = __builtin_bit_cast(float, a1[q] & 0xffff0000u);
;                     const float x2 = __builtin_bit_cast(float, a2[q] << 16), y2 = __builtin_bit_cast(float, a2[q] & 0xffff0000u);
;                     o[q] = pk2(w0 * x0 + w1 * x1 + w2 * x2, w0 * y0 + w1 * y1 + w2 * y2);
;                 }
;                 *(v4u*)(MIX + (size_t)m * DM + 1024 + e) = o;
;             }
	v_and_b32_e32 v8, 0xffff0000, v8
	v_lshlrev_b32_e32 v31, 16, v15
	v_lshlrev_b32_e32 v30, 16, v10
	v_pk_mul_f32 v[32:33], v[32:33], v[34:35] op_sel_hi:[1,0]
	v_lshlrev_b32_e32 v20, 16, v12
	v_and_b32_e32 v22, 0xffff0000, v12
	v_lshlrev_b32_e32 v27, 16, v11
	v_lshlrev_b32_e32 v26, 16, v14
	v_and_b32_e32 v29, 0xffff0000, v11
	v_and_b32_e32 v11, 0xffff0000, v15
	v_and_b32_e32 v10, 0xffff0000, v10
	v_pk_mul_f32 v[24:25], v[32:33], v[24:25] op_sel:[1,0] op_sel_hi:[0,1]
	v_pk_mul_f32 v[8:9], v[32:33], v[8:9] op_sel:[1,0] op_sel_hi:[0,1]
	v_pk_mul_f32 v[30:31], v[32:33], v[30:31] op_sel:[1,0] op_sel_hi:[0,1]
	v_lshlrev_b32_e32 v13, 16, v17
	v_lshlrev_b32_e32 v12, 16, v16
	v_and_b32_e32 v28, 0xffff0000, v14
	v_lshlrev_b32_e32 v15, 16, v19
	v_lshlrev_b32_e32 v14, 16, v18
	v_mul_f32_e32 v36, v35, v34
	v_pk_mul_f32 v[10:11], v[32:33], v[10:11] op_sel:[1,0] op_sel_hi:[0,1]
	v_pk_fma_f32 v[20:21], v[32:33], v[20:21], v[24:25]
	v_pk_fma_f32 v[8:9], v[32:33], v[22:23], v[8:9]
	v_pk_fma_f32 v[22:23], v[32:33], v[26:27], v[30:31]
	v_and_b32_e32 v17, 0xffff0000, v17
	v_and_b32_e32 v16, 0xffff0000, v16
	v_and_b32_e32 v19, 0xffff0000, v19
	v_and_b32_e32 v18, 0xffff0000, v18
	v_pk_fma_f32 v[10:11], v[32:33], v[28:29], v[10:11]
	v_pk_fma_f32 v[12:13], v[36:37], v[12:13], v[20:21] op_sel_hi:[0,1,1]
	v_pk_fma_f32 v[14:15], v[36:37], v[14:15], v[22:23] op_sel_hi:[0,1,1]
	v_pk_fma_f32 v[8:9], v[36:37], v[16:17], v[8:9] op_sel_hi:[0,1,1]
	v_pk_fma_f32 v[10:11], v[36:37], v[18:19], v[10:11] op_sel_hi:[0,1,1]
	v_bfe_u32 v20, v12, 16, 1
	v_bfe_u32 v21, v13, 16, 1
	v_bfe_u32 v22, v14, 16, 1
	v_bfe_u32 v23, v15, 16, 1
	v_bfe_u32 v16, v11, 16, 1
	v_bfe_u32 v17, v10, 16, 1
	v_bfe_u32 v18, v9, 16, 1
	v_bfe_u32 v19, v8, 16, 1
	v_add3_u32 v15, v15, v23, s28
	v_add3_u32 v14, v14, v22, s28
	v_add3_u32 v13, v13, v21, s28
	v_add3_u32 v12, v12, v20, s28
	v_add3_u32 v8, v8, v19, s28
	v_add3_u32 v9, v9, v18, s28
	v_add3_u32 v10, v10, v17, s28
	v_add3_u32 v11, v11, v16, s28
	v_lshrrev_b32_e32 v12, 16, v12
	v_lshrrev_b32_e32 v13, 16, v13
	v_lshrrev_b32_e32 v14, 16, v14
	v_lshrrev_b32_e32 v15, 16, v15
	v_and_or_b32 v11, v11, s21, v15
	v_and_or_b32 v10, v10, s21, v14
	v_and_or_b32 v9, v9, s21, v13
	v_and_or_b32 v8, v8, s21, v12
	global_store_dwordx4 v[0:1], v[8:11], off offset:1024
	v_lshl_add_u64 v[0:1], v[0:1], 0, s[4:5]
	s_nop 0
	s_waitcnt vmcnt(29)
	v_mov_b32_e32 v10, v82
	v_mov_b32_e32 v11, v83
	v_mov_b32_e32 v12, v84
	v_mov_b32_e32 v13, v85
	v_mov_b32_e32 v14, v86
	v_mov_b32_e32 v15, v87
	v_mov_b32_e32 v16, v88
	v_mov_b32_e32 v17, v89
	v_mov_b32_e32 v18, v90
	v_mov_b32_e32 v19, v91
	v_mov_b32_e32 v20, v92
	v_mov_b32_e32 v21, v93
	v_mov_b32_e32 v46, v106
	v_mov_b32_e32 v47, v107
	v_mov_b32_e32 v48, v108
	v_lshlrev_b32_e32 v23, 16, v11
	v_and_b32_e32 v35, 0xffff0000, v11
	v_lshlrev_b32_e32 v41, 16, v13
	v_and_b32_e32 v43, 0xffff0000, v13
	v_lshlrev_b32_e32 v8, 16, v10
	v_and_b32_e32 v10, 0xffff0000, v10
	v_max3_f32 v49, v46, v47, v48
	v_lshlrev_b32_e32 v9, 16, v19
	v_and_b32_e32 v11, 0xffff0000, v19
	v_lshlrev_b32_e32 v22, 16, v18
	v_and_b32_e32 v34, 0xffff0000, v18
	v_sub_f32_e32 v18, v46, v49
	v_sub_f32_e32 v19, v47, v49
	v_lshlrev_b32_e32 v39, 16, v21
	v_and_b32_e32 v13, 0xffff0000, v21
	v_lshlrev_b32_e32 v40, 16, v20
	v_and_b32_e32 v42, 0xffff0000, v20
	v_sub_f32_e32 v20, v48, v49
	v_mul_f32_e32 v18, 0x3fb8aa3b, v18
	v_mul_f32_e32 v21, 0x3fb8aa3b, v19
	v_mul_f32_e32 v20, 0x3fb8aa3b, v20
	v_exp_f32_e32 v19, v18
	v_exp_f32_e32 v18, v21
	v_exp_f32_e32 v21, v20
	v_lshlrev_b32_e32 v38, 16, v12
	v_and_b32_e32 v12, 0xffff0000, v12
	v_add_f32_e32 v20, v19, v18
	v_add_f32_e32 v20, v21, v20
	v_div_scale_f32 v46, s[0:1], v20, v20, 1.0
	v_rcp_f32_e32 v48, v46
	v_div_scale_f32 v47, vcc, 1.0, v20, 1.0
	v_lshlrev_b32_e32 v37, 16, v15
	v_fma_f32 v49, -v46, v48, 1.0
	v_fmac_f32_e32 v48, v49, v48
	v_mul_f32_e32 v49, v47, v48
	v_fma_f32 v50, -v46, v49, v47
	v_fmac_f32_e32 v49, v50, v48
	v_fma_f32 v46, -v46, v49, v47
	v_div_fmas_f32 v46, v46, v48, v49
	v_div_fixup_f32 v20, v46, v20, 1.0
	v_pk_mul_f32 v[18:19], v[18:19], v[20:21] op_sel_hi:[1,0]
	v_mul_f32_e32 v46, v21, v20
	v_pk_mul_f32 v[20:21], v[18:19], v[22:23] op_sel:[1,0] op_sel_hi:[0,1]
	v_pk_mul_f32 v[22:23], v[18:19], v[34:35] op_sel:[1,0] op_sel_hi:[0,1]
	v_pk_mul_f32 v[34:35], v[18:19], v[40:41] op_sel:[1,0] op_sel_hi:[0,1]
	v_pk_mul_f32 v[40:41], v[18:19], v[42:43] op_sel:[1,0] op_sel_hi:[0,1]
	v_lshlrev_b32_e32 v36, 16, v14
	v_and_b32_e32 v15, 0xffff0000, v15
	v_and_b32_e32 v14, 0xffff0000, v14
	v_lshlrev_b32_e32 v45, 16, v17
	v_lshlrev_b32_e32 v44, 16, v16
	v_and_b32_e32 v17, 0xffff0000, v17
	v_and_b32_e32 v16, 0xffff0000, v16
	v_pk_fma_f32 v[8:9], v[18:19], v[8:9], v[20:21]
	v_pk_fma_f32 v[10:11], v[18:19], v[10:11], v[22:23]
	v_pk_fma_f32 v[20:21], v[18:19], v[38:39], v[34:35]
	v_pk_fma_f32 v[12:13], v[18:19], v[12:13], v[40:41]
	v_pk_fma_f32 v[8:9], v[46:47], v[36:37], v[8:9] op_sel_hi:[0,1,1]
	v_pk_fma_f32 v[10:11], v[46:47], v[14:15], v[10:11] op_sel_hi:[0,1,1]
	v_pk_fma_f32 v[14:15], v[46:47], v[44:45], v[20:21] op_sel_hi:[0,1,1]
	v_pk_fma_f32 v[12:13], v[46:47], v[16:17], v[12:13] op_sel_hi:[0,1,1]
	v_bfe_u32 v16, v13, 16, 1
	v_bfe_u32 v17, v12, 16, 1
	v_bfe_u32 v18, v11, 16, 1
	v_bfe_u32 v19, v10, 16, 1
	v_bfe_u32 v20, v8, 16, 1
	v_bfe_u32 v21, v9, 16, 1
	v_bfe_u32 v22, v14, 16, 1
	v_bfe_u32 v23, v15, 16, 1
	v_add3_u32 v19, v10, v19, s28
	v_add3_u32 v18, v11, v18, s28
	v_add3_u32 v10, v12, v17, s28
	v_add3_u32 v11, v13, v16, s28
	v_add3_u32 v12, v15, v23, s28
	v_add3_u32 v13, v14, v22, s28
	v_add3_u32 v9, v9, v21, s28
	v_add3_u32 v8, v8, v20, s28
	v_lshrrev_b32_e32 v8, 16, v8
	v_lshrrev_b32_e32 v9, 16, v9
; __device__ __forceinline__ unsigned pk2(float lo, float hi) { return f2bf(lo) | (f2bf(hi) << 16); }
; __global__ void __launch_bounds__(NWAVES * 64, 2) mk_fwd(Args args) {
;     ...
;         for (int m = gw; m < MTOK; m += NGW) {
; #pragma unroll
;             for (int j = 0; j < 2; ++j) {
;                 const int e = j * 512 + lane * 8, h = e >> 7;
;                 const float l0 = LSE[((size_t)0 * MTOK + m) * 8 + h], l1 = LSE[((size_t)1 * MTOK + m) * 8 + h], l2 = LSE[((size_t)2 * MTOK + m) * 8 + h];
;                 const float mx = fmaxf(l0, fmaxf(l1, l2)); float w0 = __expf(l0 - mx), w1 = __expf(l1 - mx), w2 = __expf(l2 - mx);
;                 const float inv = 1.0f / (w0 + w1 + w2); w0 *= inv; w1 *= inv; w2 *= inv;
;                 const bf16r* p = PROJ + (size_t)m * INW + O_QB + e;
;                 const v4u a0 = *(const v4u*)p, a1 = *(const v4u*)(p + 1024), a2 = *(const v4u*)(p + 2048);
;                 v4u o;
; #pragma unroll
;                 for (int q = 0; q < 4; ++q) {
;                     const float x0 = __builtin_bit_cast(float, a0[q] << 16), y0 = __builtin_bit_cast(float, a0[q] & 0xffff0000u);
;                     const float x1 = __builtin_bit_cast(float, a1[q] << 16), y1 = __builtin_bit_cast(float, a1[q] & 0xffff0000u);
;                     const float x2 = __builtin_bit_cast(float, a2[q] << 16), y2 = __builtin_bit_cast(float, a2[q] & 0xffff0000u);
;                     o[q] = pk2(w0 * x0 + w1 * x1 + w2 * x2, w0 * y0 + w1 * y1 + w2 * y2);
;                 }
;                 *(v4u*)(MIX + (size_t)m * DM + 1024 + e) = o;
;             }
	v_lshrrev_b32_e32 v13, 16, v13
	v_lshrrev_b32_e32 v12, 16, v12
	v_and_or_b32 v11, v11, s21, v12
	v_and_or_b32 v10, v10, s21, v13
	v_and_or_b32 v9, v18, s21, v9
	v_and_or_b32 v8, v19, s21, v8
	global_store_dwordx4 v[0:1], v[8:11], off
	s_nop 1
	v_mov_b32_e32 v8, v94
	v_mov_b32_e32 v9, v95
	v_mov_b32_e32 v10, v96
	v_mov_b32_e32 v11, v97
	v_mov_b32_e32 v12, v98
	v_mov_b32_e32 v13, v99
	v_mov_b32_e32 v14, v100
	v_mov_b32_e32 v15, v101
	v_mov_b32_e32 v16, v102
	v_mov_b32_e32 v17, v103
	v_mov_b32_e32 v18, v104
	v_mov_b32_e32 v19, v105
	v_mov_b32_e32 v34, v109
	v_mov_b32_e32 v35, v110
	v_mov_b32_e32 v36, v111
	v_add_u32_e32 v148, 0x14800000, v154
	v_add_u32_e32 v149, 0x14801000, v154
	v_add_u32_e32 v150, 0x14802000, v154
	v_add_u32_e32 v151, 0xc200000, v155
	v_add_u32_e32 v152, 0xc300000, v155
	v_add_u32_e32 v153, 0xc400000, v155
	global_load_dwordx4 v[82:85], v149, s[26:27] offset:1024
	global_load_dword v106, v151, s[26:27]
	global_load_dwordx4 v[86:89], v149, s[26:27] offset:3072
	global_load_dword v107, v152, s[26:27]
	global_load_dword v108, v153, s[26:27]
	global_load_dwordx4 v[90:93], v148, s[26:27] offset:3072
	global_load_dword v109, v151, s[26:27] offset:16
	global_load_dword v110, v152, s[26:27] offset:16
	global_load_dword v111, v153, s[26:27] offset:16
	global_load_dwordx4 v[94:97], v149, s[26:27]
	global_load_dwordx4 v[98:101], v149, s[26:27] offset:2048
	global_load_dwordx4 v[102:105], v150, s[26:27]
	v_add_u32_e32 v154, s12, v154
	v_add_u32_e32 v155, s14, v155
	v_max3_f32 v32, v34, v35, v36
	v_sub_f32_e32 v33, v34, v32
	v_sub_f32_e32 v34, v35, v32
	v_sub_f32_e32 v32, v36, v32
	v_mul_f32_e32 v33, 0x3fb8aa3b, v33
	v_mul_f32_e32 v34, 0x3fb8aa3b, v34
	v_mul_f32_e32 v35, 0x3fb8aa3b, v32
	v_exp_f32_e32 v33, v33
	v_exp_f32_e32 v32, v34
	v_exp_f32_e32 v35, v35
	v_lshlrev_b32_e32 v21, 16, v9
	v_and_b32_e32 v23, 0xffff0000, v9
	v_add_f32_e32 v34, v33, v32
	v_add_f32_e32 v34, v35, v34
	v_div_scale_f32 v36, s[0:1], v34, v34, 1.0
	v_rcp_f32_e32 v38, v36
	v_div_scale_f32 v37, vcc, 1.0, v34, 1.0
	v_lshlrev_b32_e32 v25, 16, v13
	v_fma_f32 v39, -v36, v38, 1.0
	v_fmac_f32_e32 v38, v39, v38
	v_mul_f32_e32 v39, v37, v38
	v_fma_f32 v40, -v36, v39, v37
	v_fmac_f32_e32 v39, v40, v38
	v_fma_f32 v36, -v36, v39, v37
	v_div_fmas_f32 v36, v36, v38, v39
	v_div_fixup_f32 v34, v36, v34, 1.0
	v_lshlrev_b32_e32 v24, 16, v8
	v_and_b32_e32 v9, 0xffff0000, v13
	v_and_b32_e32 v8, 0xffff0000, v8
	v_lshlrev_b32_e32 v31, 16, v15
	v_lshlrev_b32_e32 v30, 16, v10
	v_pk_mul_f32 v[32:33], v[32:33], v[34:35] op_sel_hi:[1,0]
	v_lshlrev_b32_e32 v20, 16, v12
	v_and_b32_e32 v22, 0xffff0000, v12
	v_lshlrev_b32_e32 v27, 16, v11
	v_lshlrev_b32_e32 v26, 16, v14
	v_and_b32_e32 v29, 0xffff0000, v11
	v_and_b32_e32 v11, 0xffff0000, v15
	v_and_b32_e32 v10, 0xffff0000, v10
	v_pk_mul_f32 v[24:25], v[32:33], v[24:25] op_sel:[1,0] op_sel_hi:[0,1]
	v_pk_mul_f32 v[8:9], v[32:33], v[8:9] op_sel:[1,0] op_sel_hi:[0,1]
	v_pk_mul_f32 v[30:31], v[32:33], v[30:31] op_sel:[1,0] op_sel_hi:[0,1]
	v_lshlrev_b32_e32 v13, 16, v17
	v_lshlrev_b32_e32 v12, 16, v16
	v_and_b32_e32 v28, 0xffff0000, v14
	v_lshlrev_b32_e32 v15, 16, v19
	v_lshlrev_b32_e32 v14, 16, v18
	v_mul_f32_e32 v36, v35, v34
	v_pk_mul_f32 v[10:11], v[32:33], v[10:11] op_sel:[1,0] op_sel_hi:[0,1]
	v_pk_fma_f32 v[20:21], v[32:33], v[20:21], v[24:25]
	v_pk_fma_f32 v[8:9], v[32:33], v[22:23], v[8:9]
	v_pk_fma_f32 v[22:23], v[32:33], v[26:27], v[30:31]
	v_and_b32_e32 v17, 0xffff0000, v17
	v_and_b32_e32 v16, 0xffff0000, v16
	v_and_b32_e32 v19, 0xffff0000, v19
	v_and_b32_e32 v18, 0xffff0000, v18
	v_pk_fma_f32 v[10:11], v[32:33], v[28:29], v[10:11]
	v_pk_fma_f32 v[12:13], v[36:37], v[12:13], v[20:21] op_sel_hi:[0,1,1]
	v_pk_fma_f32 v[14:15], v[36:37], v[14:15], v[22:23] op_sel_hi:[0,1,1]
	v_pk_fma_f32 v[8:9], v[36:37], v[16:17], v[8:9] op_sel_hi:[0,1,1]
	v_pk_fma_f32 v[10:11], v[36:37], v[18:19], v[10:11] op_sel_hi:[0,1,1]
	v_bfe_u32 v20, v12, 16, 1
	v_bfe_u32 v21, v13, 16, 1
	v_bfe_u32 v22, v14, 16, 1
	v_bfe_u32 v23, v15, 16, 1
	v_bfe_u32 v16, v11, 16, 1
	v_bfe_u32 v17, v10, 16, 1
	v_bfe_u32 v18, v9, 16, 1
	v_bfe_u32 v19, v8, 16, 1
	v_add3_u32 v15, v15, v23, s28
	v_add3_u32 v14, v14, v22, s28
	v_add3_u32 v13, v13, v21, s28
	v_add3_u32 v12, v12, v20, s28
	v_add3_u32 v8, v8, v19, s28
	v_add3_u32 v9, v9, v18, s28
	v_add3_u32 v10, v10, v17, s28
	v_add3_u32 v11, v11, v16, s28
	v_lshrrev_b32_e32 v12, 16, v12
	v_lshrrev_b32_e32 v13, 16, v13
	v_lshrrev_b32_e32 v14, 16, v14
	v_lshrrev_b32_e32 v15, 16, v15
	v_and_or_b32 v11, v11, s21, v15
	v_and_or_b32 v10, v10, s21, v14
	v_and_or_b32 v9, v9, s21, v13
	v_and_or_b32 v8, v8, s21, v12
	global_store_dwordx4 v[0:1], v[8:11], off offset:1024
	v_lshl_add_u64 v[0:1], v[0:1], 0, s[4:5]
	s_nop 0
	s_waitcnt vmcnt(29)
; __device__ __forceinline__ unsigned pk2(float lo, float hi) { return f2bf(lo) | (f2bf(hi) << 16); }
; __global__ void __launch_bounds__(NWAVES * 64, 2) mk_fwd(Args args) {
;     ...
;         for (int m = gw; m < MTOK; m += NGW) {
; #pragma unroll
;             for (int j = 0; j < 2; ++j) {
;                 const int e = j * 512 + lane * 8, h = e >> 7;
;                 const float l0 = LSE[((size_t)0 * MTOK + m) * 8 + h], l1 = LSE[((size_t)1 * MTOK + m) * 8 + h], l2 = LSE[((size_t)2 * MTOK + m) * 8 + h];
;                 const float mx = fmaxf(l0, fmaxf(l1, l2)); float w0 = __expf(l0 - mx), w1 = __expf(l1 - mx), w2 = __expf(l2 - mx);
;                 const float inv = 1.0f / (w0 + w1 + w2); w0 *= inv; w1 *= inv; w2 *= inv;
;                 const bf16r* p = PROJ + (size_t)m * INW + O_QB + e;
;                 const v4u a0 = *(const v4u*)p, a1 = *(const v4u*)(p + 1024), a2 = *(const v4u*)(p + 2048);
;                 v4u o;
; #pragma unroll
;                 for (int q = 0; q < 4; ++q) {
;                     const float x0 = __builtin_bit_cast(float, a0[q] << 16), y0 = __builtin_bit_cast(float, a0[q] & 0xffff0000u);
;                     const float x1 = __builtin_bit_cast(float, a1[q] << 16), y1 = __builtin_bit_cast(float, a1[q] & 0xffff0000u);
;                     const float x2 = __builtin_bit_cast(float, a2[q] << 16), y2 = __builtin_bit_cast(float, a2[q] & 0xffff0000u);
;                     o[q] = pk2(w0 * x0 + w1 * x1 + w2 * x2, w0 * y0 + w1 * y1 + w2 * y2);
;                 }
;                 *(v4u*)(MIX + (size_t)m * DM + 1024 + e) = o;
;             }
	v_mov_b32_e32 v10, v112
	v_mov_b32_e32 v11, v113
	v_mov_b32_e32 v12, v114
	v_mov_b32_e32 v13, v115
	v_mov_b32_e32 v14, v116
	v_mov_b32_e32 v15, v117
	v_mov_b32_e32 v16, v118
	v_mov_b32_e32 v17, v119
	v_mov_b32_e32 v18, v120
	v_mov_b32_e32 v19, v121
	v_mov_b32_e32 v20, v122
	v_mov_b32_e32 v21, v123
	v_mov_b32_e32 v46, v136
	v_mov_b32_e32 v47, v137
	v_mov_b32_e32 v48, v138
	v_lshlrev_b32_e32 v23, 16, v11
	v_and_b32_e32 v35, 0xffff0000, v11
	v_lshlrev_b32_e32 v41, 16, v13
	v_and_b32_e32 v43, 0xffff0000, v13
	v_lshlrev_b32_e32 v8, 16, v10
	v_and_b32_e32 v10, 0xffff0000, v10
	v_max3_f32 v49, v46, v47, v48
	v_lshlrev_b32_e32 v9, 16, v19
	v_and_b32_e32 v11, 0xffff0000, v19
	v_lshlrev_b32_e32 v22, 16, v18
	v_and_b32_e32 v34, 0xffff0000, v18
	v_sub_f32_e32 v18, v46, v49
	v_sub_f32_e32 v19, v47, v49
	v_lshlrev_b32_e32 v39, 16, v21
	v_and_b32_e32 v13, 0xffff0000, v21
	v_lshlrev_b32_e32 v40, 16, v20
	v_and_b32_e32 v42, 0xffff0000, v20
	v_sub_f32_e32 v20, v48, v49
	v_mul_f32_e32 v18, 0x3fb8aa3b, v18
	v_mul_f32_e32 v21, 0x3fb8aa3b, v19
	v_mul_f32_e32 v20, 0x3fb8aa3b, v20
	v_exp_f32_e32 v19, v18
	v_exp_f32_e32 v18, v21
	v_exp_f32_e32 v21, v20
	v_lshlrev_b32_e32 v38, 16, v12
	v_and_b32_e32 v12, 0xffff0000, v12
	v_add_f32_e32 v20, v19, v18
	v_add_f32_e32 v20, v21, v20
	v_div_scale_f32 v46, s[0:1], v20, v20, 1.0
	v_rcp_f32_e32 v48, v46
	v_div_scale_f32 v47, vcc, 1.0, v20, 1.0
	v_lshlrev_b32_e32 v37, 16, v15
	v_fma_f32 v49, -v46, v48, 1.0
	v_fmac_f32_e32 v48, v49, v48
	v_mul_f32_e32 v49, v47, v48
	v_fma_f32 v50, -v46, v49, v47
	v_fmac_f32_e32 v49, v50, v48
	v_fma_f32 v46, -v46, v49, v47
	v_div_fmas_f32 v46, v46, v48, v49
	v_div_fixup_f32 v20, v46, v20, 1.0
	v_pk_mul_f32 v[18:19], v[18:19], v[20:21] op_sel_hi:[1,0]
	v_mul_f32_e32 v46, v21, v20
	v_pk_mul_f32 v[20:21], v[18:19], v[22:23] op_sel:[1,0] op_sel_hi:[0,1]
	v_pk_mul_f32 v[22:23], v[18:19], v[34:35] op_sel:[1,0] op_sel_hi:[0,1]
	v_pk_mul_f32 v[34:35], v[18:19], v[40:41] op_sel:[1,0] op_sel_hi:[0,1]
	v_pk_mul_f32 v[40:41], v[18:19], v[42:43] op_sel:[1,0] op_sel_hi:[0,1]
	v_lshlrev_b32_e32 v36, 16, v14
	v_and_b32_e32 v15, 0xffff0000, v15
	v_and_b32_e32 v14, 0xffff0000, v14
	v_lshlrev_b32_e32 v45, 16, v17
	v_lshlrev_b32_e32 v44, 16, v16
	v_and_b32_e32 v17, 0xffff0000, v17
	v_and_b32_e32 v16, 0xffff0000, v16
	v_pk_fma_f32 v[8:9], v[18:19], v[8:9], v[20:21]
	v_pk_fma_f32 v[10:11], v[18:19], v[10:11], v[22:23]
	v_pk_fma_f32 v[20:21], v[18:19], v[38:39], v[34:35]
	v_pk_fma_f32 v[12:13], v[18:19], v[12:13], v[40:41]
	v_pk_fma_f32 v[8:9], v[46:47], v[36:37], v[8:9] op_sel_hi:[0,1,1]
	v_pk_fma_f32 v[10:11], v[46:47], v[14:15], v[10:11] op_sel_hi:[0,1,1]
	v_pk_fma_f32 v[14:15], v[46:47], v[44:45], v[20:21] op_sel_hi:[0,1,1]
	v_pk_fma_f32 v[12:13], v[46:47], v[16:17], v[12:13] op_sel_hi:[0,1,1]
	v_bfe_u32 v16, v13, 16, 1
	v_bfe_u32 v17, v12, 16, 1
	v_bfe_u32 v18, v11, 16, 1
	v_bfe_u32 v19, v10, 16, 1
	v_bfe_u32 v20, v8, 16, 1
	v_bfe_u32 v21, v9, 16, 1
	v_bfe_u32 v22, v14, 16, 1
	v_bfe_u32 v23, v15, 16, 1
	v_add3_u32 v19, v10, v19, s28
	v_add3_u32 v18, v11, v18, s28
	v_add3_u32 v10, v12, v17, s28
	v_add3_u32 v11, v13, v16, s28
	v_add3_u32 v12, v15, v23, s28
	v_add3_u32 v13, v14, v22, s28
	v_add3_u32 v9, v9, v21, s28
	v_add3_u32 v8, v8, v20, s28
	v_lshrrev_b32_e32 v8, 16, v8
	v_lshrrev_b32_e32 v9, 16, v9
	v_lshrrev_b32_e32 v13, 16, v13
	v_lshrrev_b32_e32 v12, 16, v12
	v_and_or_b32 v11, v11, s21, v12
	v_and_or_b32 v10, v10, s21, v13
	v_and_or_b32 v9, v18, s21, v9
	v_and_or_b32 v8, v19, s21, v8
	global_store_dwordx4 v[0:1], v[8:11], off
	s_nop 1
	v_mov_b32_e32 v8, v124
	v_mov_b32_e32 v9, v125
	v_mov_b32_e32 v10, v126
	v_mov_b32_e32 v11, v127
	v_mov_b32_e32 v12, v128
	v_mov_b32_e32 v13, v129
	v_mov_b32_e32 v14, v130
	v_mov_b32_e32 v15, v131
	v_mov_b32_e32 v16, v132
	v_mov_b32_e32 v17, v133
	v_mov_b32_e32 v18, v134
	v_mov_b32_e32 v19, v135
	v_mov_b32_e32 v34, v139
	v_mov_b32_e32 v35, v140
	v_mov_b32_e32 v36, v141
	v_add_u32_e32 v142, 0x14800000, v154
	v_add_u32_e32 v143, 0x14801000, v154
	v_add_u32_e32 v144, 0x14802000, v154
	v_add_u32_e32 v145, 0xc200000, v155
	v_add_u32_e32 v146, 0xc300000, v155
	v_add_u32_e32 v147, 0xc400000, v155
	global_load_dwordx4 v[112:115], v143, s[26:27] offset:1024
	global_load_dword v136, v145, s[26:27]
	global_load_dwordx4 v[116:119], v143, s[26:27] offset:3072
	global_load_dword v137, v146, s[26:27]
	global_load_dword v138, v147, s[26:27]
	global_load_dwordx4 v[120:123], v142, s[26:27] offset:3072
	global_load_dword v139, v145, s[26:27] offset:16
	global_load_dword v140, v146, s[26:27] offset:16
	global_load_dword v141, v147, s[26:27] offset:16
	global_load_dwordx4 v[124:127], v143, s[26:27]
	global_load_dwordx4 v[128:131], v143, s[26:27] offset:2048
	global_load_dwordx4 v[132:135], v144, s[26:27]
	v_add_u32_e32 v154, s12, v154
	v_add_u32_e32 v155, s14, v155
	v_max3_f32 v32, v34, v35, v36
	v_sub_f32_e32 v33, v34, v32
	v_sub_f32_e32 v34, v35, v32
	v_sub_f32_e32 v32, v36, v32
	v_mul_f32_e32 v33, 0x3fb8aa3b, v33
	v_mul_f32_e32 v34, 0x3fb8aa3b, v34
	v_mul_f32_e32 v35, 0x3fb8aa3b, v32
	v_exp_f32_e32 v33, v33
	v_exp_f32_e32 v32, v34
	v_exp_f32_e32 v35, v35
	v_lshlrev_b32_e32 v21, 16, v9
	v_and_b32_e32 v23, 0xffff0000, v9
	v_add_f32_e32 v34, v33, v32
	v_add_f32_e32 v34, v35, v34
	v_div_scale_f32 v36, s[0:1], v34, v34, 1.0
	v_rcp_f32_e32 v38, v36
	v_div_scale_f32 v37, vcc, 1.0, v34, 1.0
	v_lshlrev_b32_e32 v25, 16, v13
	v_fma_f32 v39, -v36, v38, 1.0
	v_fmac_f32_e32 v38, v39, v38
	v_mul_f32_e32 v39, v37, v38
	v_fma_f32 v40, -v36, v39, v37
	v_fmac_f32_e32 v39, v40, v38
	v_fma_f32 v36, -v36, v39, v37
	v_div_fmas_f32 v36, v36, v38, v39
	v_div_fixup_f32 v34, v36, v34, 1.0
	v_lshlrev_b32_e32 v24, 16, v8
; __device__ __forceinline__ unsigned pk2(float lo, float hi) { return f2bf(lo) | (f2bf(hi) << 16); }
; __global__ void __launch_bounds__(NWAVES * 64, 2) mk_fwd(Args args) {
;     ...
;         for (int m = gw; m < MTOK; m += NGW) {
; #pragma unroll
;             for (int j = 0; j < 2; ++j) {
;                 const int e = j * 512 + lane * 8, h = e >> 7;
;                 const float l0 = LSE[((size_t)0 * MTOK + m) * 8 + h], l1 = LSE[((size_t)1 * MTOK + m) * 8 + h], l2 = LSE[((size_t)2 * MTOK + m) * 8 + h];
;                 const float mx = fmaxf(l0, fmaxf(l1, l2)); float w0 = __expf(l0 - mx), w1 = __expf(l1 - mx), w2 = __expf(l2 - mx);
;                 const float inv = 1.0f / (w0 + w1 + w2); w0 *= inv; w1 *= inv; w2 *= inv;
;                 const bf16r* p = PROJ + (size_t)m * INW + O_QB + e;
;                 const v4u a0 = *(const v4u*)p, a1 = *(const v4u*)(p + 1024), a2 = *(const v4u*)(p + 2048);
;                 v4u o;
; #pragma unroll
;                 for (int q = 0; q < 4; ++q) {
;                     const float x0 = __builtin_bit_cast(float, a0[q] << 16), y0 = __builtin_bit_cast(float, a0[q] & 0xffff0000u);
;                     const float x1 = __builtin_bit_cast(float, a1[q] << 16), y1 = __builtin_bit_cast(float, a1[q] & 0xffff0000u);
;                     const float x2 = __builtin_bit_cast(float, a2[q] << 16), y2 = __builtin_bit_cast(float, a2[q] & 0xffff0000u);
;                     o[q] = pk2(w0 * x0 + w1 * x1 + w2 * x2, w0 * y0 + w1 * y1 + w2 * y2);
;                 }
;                 *(v4u*)(MIX + (size_t)m * DM + 1024 + e) = o;
;             }
	v_and_b32_e32 v9, 0xffff0000, v13
	v_and_b32_e32 v8, 0xffff0000, v8
	v_lshlrev_b32_e32 v31, 16, v15
	v_lshlrev_b32_e32 v30, 16, v10
	v_pk_mul_f32 v[32:33], v[32:33], v[34:35] op_sel_hi:[1,0]
	v_lshlrev_b32_e32 v20, 16, v12
	v_and_b32_e32 v22, 0xffff0000, v12
	v_lshlrev_b32_e32 v27, 16, v11
	v_lshlrev_b32_e32 v26, 16, v14
	v_and_b32_e32 v29, 0xffff0000, v11
	v_and_b32_e32 v11, 0xffff0000, v15
	v_and_b32_e32 v10, 0xffff0000, v10
	v_pk_mul_f32 v[24:25], v[32:33], v[24:25] op_sel:[1,0] op_sel_hi:[0,1]
	v_pk_mul_f32 v[8:9], v[32:33], v[8:9] op_sel:[1,0] op_sel_hi:[0,1]
	v_pk_mul_f32 v[30:31], v[32:33], v[30:31] op_sel:[1,0] op_sel_hi:[0,1]
	v_lshlrev_b32_e32 v13, 16, v17
	v_lshlrev_b32_e32 v12, 16, v16
	v_and_b32_e32 v28, 0xffff0000, v14
	v_lshlrev_b32_e32 v15, 16, v19
	v_lshlrev_b32_e32 v14, 16, v18
	v_mul_f32_e32 v36, v35, v34
	v_pk_mul_f32 v[10:11], v[32:33], v[10:11] op_sel:[1,0] op_sel_hi:[0,1]
	v_pk_fma_f32 v[20:21], v[32:33], v[20:21], v[24:25]
	v_pk_fma_f32 v[8:9], v[32:33], v[22:23], v[8:9]
	v_pk_fma_f32 v[22:23], v[32:33], v[26:27], v[30:31]
	v_and_b32_e32 v17, 0xffff0000, v17
	v_and_b32_e32 v16, 0xffff0000, v16
	v_and_b32_e32 v19, 0xffff0000, v19
	v_and_b32_e32 v18, 0xffff0000, v18
	v_pk_fma_f32 v[10:11], v[32:33], v[28:29], v[10:11]
	v_pk_fma_f32 v[12:13], v[36:37], v[12:13], v[20:21] op_sel_hi:[0,1,1]
	v_pk_fma_f32 v[14:15], v[36:37], v[14:15], v[22:23] op_sel_hi:[0,1,1]
	v_pk_fma_f32 v[8:9], v[36:37], v[16:17], v[8:9] op_sel_hi:[0,1,1]
	v_pk_fma_f32 v[10:11], v[36:37], v[18:19], v[10:11] op_sel_hi:[0,1,1]
	v_bfe_u32 v20, v12, 16, 1
	v_bfe_u32 v21, v13, 16, 1
	v_bfe_u32 v22, v14, 16, 1
	v_bfe_u32 v23, v15, 16, 1
	v_bfe_u32 v16, v11, 16, 1
	v_bfe_u32 v17, v10, 16, 1
	v_bfe_u32 v18, v9, 16, 1
	v_bfe_u32 v19, v8, 16, 1
	v_add3_u32 v15, v15, v23, s28
	v_add3_u32 v14, v14, v22, s28
	v_add3_u32 v13, v13, v21, s28
	v_add3_u32 v12, v12, v20, s28
	v_add3_u32 v8, v8, v19, s28
	v_add3_u32 v9, v9, v18, s28
	v_add3_u32 v10, v10, v17, s28
	v_add3_u32 v11, v11, v16, s28
	v_lshrrev_b32_e32 v12, 16, v12
	v_lshrrev_b32_e32 v13, 16, v13
	v_lshrrev_b32_e32 v14, 16, v14
	v_lshrrev_b32_e32 v15, 16, v15
	v_and_or_b32 v11, v11, s21, v15
	v_and_or_b32 v10, v10, s21, v14
	v_and_or_b32 v9, v9, s21, v13
	v_and_or_b32 v8, v8, s21, v12
	global_store_dwordx4 v[0:1], v[8:11], off offset:1024
	v_lshl_add_u64 v[0:1], v[0:1], 0, s[4:5]
	s_nop 0
	s_waitcnt vmcnt(29)
	v_mov_b32_e32 v10, v52
	v_mov_b32_e32 v11, v53
	v_mov_b32_e32 v12, v54
	v_mov_b32_e32 v13, v55
	v_mov_b32_e32 v14, v56
	v_mov_b32_e32 v15, v57
	v_mov_b32_e32 v16, v58
	v_mov_b32_e32 v17, v59
	v_mov_b32_e32 v18, v60
	v_mov_b32_e32 v19, v61
	v_mov_b32_e32 v20, v62
	v_mov_b32_e32 v21, v63
	v_mov_b32_e32 v46, v76
	v_mov_b32_e32 v47, v77
	v_mov_b32_e32 v48, v78
	v_lshlrev_b32_e32 v23, 16, v11
	v_and_b32_e32 v35, 0xffff0000, v11
	v_lshlrev_b32_e32 v41, 16, v13
	v_and_b32_e32 v43, 0xffff0000, v13
	v_lshlrev_b32_e32 v8, 16, v10
	v_and_b32_e32 v10, 0xffff0000, v10
	v_max3_f32 v49, v46, v47, v48
	v_lshlrev_b32_e32 v9, 16, v19
	v_and_b32_e32 v11, 0xffff0000, v19
	v_lshlrev_b32_e32 v22, 16, v18
	v_and_b32_e32 v34, 0xffff0000, v18
	v_sub_f32_e32 v18, v46, v49
	v_sub_f32_e32 v19, v47, v49
	v_lshlrev_b32_e32 v39, 16, v21
	v_and_b32_e32 v13, 0xffff0000, v21
	v_lshlrev_b32_e32 v40, 16, v20
	v_and_b32_e32 v42, 0xffff0000, v20
	v_sub_f32_e32 v20, v48, v49
	v_mul_f32_e32 v18, 0x3fb8aa3b, v18
	v_mul_f32_e32 v21, 0x3fb8aa3b, v19
	v_mul_f32_e32 v20, 0x3fb8aa3b, v20
	v_exp_f32_e32 v19, v18
	v_exp_f32_e32 v18, v21
	v_exp_f32_e32 v21, v20
	v_lshlrev_b32_e32 v38, 16, v12
	v_and_b32_e32 v12, 0xffff0000, v12
	v_add_f32_e32 v20, v19, v18
	v_add_f32_e32 v20, v21, v20
	v_div_scale_f32 v46, s[0:1], v20, v20, 1.0
	v_rcp_f32_e32 v48, v46
	v_div_scale_f32 v47, vcc, 1.0, v20, 1.0
	v_lshlrev_b32_e32 v37, 16, v15
	v_fma_f32 v49, -v46, v48, 1.0
	v_fmac_f32_e32 v48, v49, v48
	v_mul_f32_e32 v49, v47, v48
	v_fma_f32 v50, -v46, v49, v47
	v_fmac_f32_e32 v49, v50, v48
	v_fma_f32 v46, -v46, v49, v47
	v_div_fmas_f32 v46, v46, v48, v49
	v_div_fixup_f32 v20, v46, v20, 1.0
	v_pk_mul_f32 v[18:19], v[18:19], v[20:21] op_sel_hi:[1,0]
	v_mul_f32_e32 v46, v21, v20
	v_pk_mul_f32 v[20:21], v[18:19], v[22:23] op_sel:[1,0] op_sel_hi:[0,1]
	v_pk_mul_f32 v[22:23], v[18:19], v[34:35] op_sel:[1,0] op_sel_hi:[0,1]
	v_pk_mul_f32 v[34:35], v[18:19], v[40:41] op_sel:[1,0] op_sel_hi:[0,1]
	v_pk_mul_f32 v[40:41], v[18:19], v[42:43] op_sel:[1,0] op_sel_hi:[0,1]
	v_lshlrev_b32_e32 v36, 16, v14
	v_and_b32_e32 v15, 0xffff0000, v15
	v_and_b32_e32 v14, 0xffff0000, v14
	v_lshlrev_b32_e32 v45, 16, v17
	v_lshlrev_b32_e32 v44, 16, v16
	v_and_b32_e32 v17, 0xffff0000, v17
	v_and_b32_e32 v16, 0xffff0000, v16
	v_pk_fma_f32 v[8:9], v[18:19], v[8:9], v[20:21]
	v_pk_fma_f32 v[10:11], v[18:19], v[10:11], v[22:23]
	v_pk_fma_f32 v[20:21], v[18:19], v[38:39], v[34:35]
	v_pk_fma_f32 v[12:13], v[18:19], v[12:13], v[40:41]
	v_pk_fma_f32 v[8:9], v[46:47], v[36:37], v[8:9] op_sel_hi:[0,1,1]
	v_pk_fma_f32 v[10:11], v[46:47], v[14:15], v[10:11] op_sel_hi:[0,1,1]
	v_pk_fma_f32 v[14:15], v[46:47], v[44:45], v[20:21] op_sel_hi:[0,1,1]
	v_pk_fma_f32 v[12:13], v[46:47], v[16:17], v[12:13] op_sel_hi:[0,1,1]
	v_bfe_u32 v16, v13, 16, 1
	v_bfe_u32 v17, v12, 16, 1
	v_bfe_u32 v18, v11, 16, 1
	v_bfe_u32 v19, v10, 16, 1
	v_bfe_u32 v20, v8, 16, 1
	v_bfe_u32 v21, v9, 16, 1
	v_bfe_u32 v22, v14, 16, 1
	v_bfe_u32 v23, v15, 16, 1
	v_add3_u32 v19, v10, v19, s28
	v_add3_u32 v18, v11, v18, s28
	v_add3_u32 v10, v12, v17, s28
	v_add3_u32 v11, v13, v16, s28
	v_add3_u32 v12, v15, v23, s28
	v_add3_u32 v13, v14, v22, s28
	v_add3_u32 v9, v9, v21, s28
	v_add3_u32 v8, v8, v20, s28
	v_lshrrev_b32_e32 v8, 16, v8
; __device__ __forceinline__ unsigned pk2(float lo, float hi) { return f2bf(lo) | (f2bf(hi) << 16); }
; __global__ void __launch_bounds__(NWAVES * 64, 2) mk_fwd(Args args) {
;     ...
;         for (int m = gw; m < MTOK; m += NGW) {
; #pragma unroll
;             for (int j = 0; j < 2; ++j) {
;                 const int e = j * 512 + lane * 8, h = e >> 7;
;                 const float l0 = LSE[((size_t)0 * MTOK + m) * 8 + h], l1 = LSE[((size_t)1 * MTOK + m) * 8 + h], l2 = LSE[((size_t)2 * MTOK + m) * 8 + h];
;                 const float mx = fmaxf(l0, fmaxf(l1, l2)); float w0 = __expf(l0 - mx), w1 = __expf(l1 - mx), w2 = __expf(l2 - mx);
;                 const float inv = 1.0f / (w0 + w1 + w2); w0 *= inv; w1 *= inv; w2 *= inv;
;                 const bf16r* p = PROJ + (size_t)m * INW + O_QB + e;
;                 const v4u a0 = *(const v4u*)p, a1 = *(const v4u*)(p + 1024), a2 = *(const v4u*)(p + 2048);
;                 v4u o;
; #pragma unroll
;                 for (int q = 0; q < 4; ++q) {
;                     const float x0 = __builtin_bit_cast(float, a0[q] << 16), y0 = __builtin_bit_cast(float, a0[q] & 0xffff0000u);
;                     const float x1 = __builtin_bit_cast(float, a1[q] << 16), y1 = __builtin_bit_cast(float, a1[q] & 0xffff0000u);
;                     const float x2 = __builtin_bit_cast(float, a2[q] << 16), y2 = __builtin_bit_cast(float, a2[q] & 0xffff0000u);
;                     o[q] = pk2(w0 * x0 + w1 * x1 + w2 * x2, w0 * y0 + w1 * y1 + w2 * y2);
;                 }
;                 *(v4u*)(MIX + (size_t)m * DM + 1024 + e) = o;
;             }
	v_lshrrev_b32_e32 v9, 16, v9
	v_lshrrev_b32_e32 v13, 16, v13
	v_lshrrev_b32_e32 v12, 16, v12
	v_and_or_b32 v11, v11, s21, v12
	v_and_or_b32 v10, v10, s21, v13
	v_and_or_b32 v9, v18, s21, v9
	v_and_or_b32 v8, v19, s21, v8
	global_store_dwordx4 v[0:1], v[8:11], off
	s_nop 1
	v_mov_b32_e32 v8, v64
	v_mov_b32_e32 v9, v65
	v_mov_b32_e32 v10, v66
	v_mov_b32_e32 v11, v67
	v_mov_b32_e32 v12, v68
	v_mov_b32_e32 v13, v69
	v_mov_b32_e32 v14, v70
	v_mov_b32_e32 v15, v71
	v_mov_b32_e32 v16, v72
	v_mov_b32_e32 v17, v73
	v_mov_b32_e32 v18, v74
	v_mov_b32_e32 v19, v75
	v_mov_b32_e32 v34, v79
	v_mov_b32_e32 v35, v80
	v_mov_b32_e32 v36, v81
	v_add_u32_e32 v148, 0x14800000, v154
	v_add_u32_e32 v149, 0x14801000, v154
	v_add_u32_e32 v150, 0x14802000, v154
	v_add_u32_e32 v151, 0xc200000, v155
	v_add_u32_e32 v152, 0xc300000, v155
	v_add_u32_e32 v153, 0xc400000, v155
	global_load_dwordx4 v[52:55], v149, s[26:27] offset:1024
	global_load_dword v76, v151, s[26:27]
	global_load_dwordx4 v[56:59], v149, s[26:27] offset:3072
	global_load_dword v77, v152, s[26:27]
	global_load_dword v78, v153, s[26:27]
	global_load_dwordx4 v[60:63], v148, s[26:27] offset:3072
	global_load_dword v79, v151, s[26:27] offset:16
	global_load_dword v80, v152, s[26:27] offset:16
	global_load_dword v81, v153, s[26:27] offset:16
	global_load_dwordx4 v[64:67], v149, s[26:27]
	global_load_dwordx4 v[68:71], v149, s[26:27] offset:2048
	global_load_dwordx4 v[72:75], v150, s[26:27]
	v_add_u32_e32 v154, s12, v154
	v_add_u32_e32 v155, s14, v155
	v_max3_f32 v32, v34, v35, v36
	v_sub_f32_e32 v33, v34, v32
	v_sub_f32_e32 v34, v35, v32
	v_sub_f32_e32 v32, v36, v32
	v_mul_f32_e32 v33, 0x3fb8aa3b, v33
	v_mul_f32_e32 v34, 0x3fb8aa3b, v34
	v_mul_f32_e32 v35, 0x3fb8aa3b, v32
	v_exp_f32_e32 v33, v33
	v_exp_f32_e32 v32, v34
	v_exp_f32_e32 v35, v35
	v_lshlrev_b32_e32 v21, 16, v9
	v_and_b32_e32 v23, 0xffff0000, v9
	v_add_f32_e32 v34, v33, v32
	v_add_f32_e32 v34, v35, v34
	v_div_scale_f32 v36, s[0:1], v34, v34, 1.0
	v_rcp_f32_e32 v38, v36
	v_div_scale_f32 v37, vcc, 1.0, v34, 1.0
	v_lshlrev_b32_e32 v25, 16, v13
	v_fma_f32 v39, -v36, v38, 1.0
	v_fmac_f32_e32 v38, v39, v38
	v_mul_f32_e32 v39, v37, v38
	v_fma_f32 v40, -v36, v39, v37
	v_fmac_f32_e32 v39, v40, v38
	v_fma_f32 v36, -v36, v39, v37
	v_div_fmas_f32 v36, v36, v38, v39
	v_div_fixup_f32 v34, v36, v34, 1.0
	v_lshlrev_b32_e32 v24, 16, v8
	v_and_b32_e32 v9, 0xffff0000, v13
	v_and_b32_e32 v8, 0xffff0000, v8
	v_lshlrev_b32_e32 v31, 16, v15
	v_lshlrev_b32_e32 v30, 16, v10
	v_pk_mul_f32 v[32:33], v[32:33], v[34:35] op_sel_hi:[1,0]
	v_lshlrev_b32_e32 v20, 16, v12
	v_and_b32_e32 v22, 0xffff0000, v12
	v_lshlrev_b32_e32 v27, 16, v11
	v_lshlrev_b32_e32 v26, 16, v14
	v_and_b32_e32 v29, 0xffff0000, v11
	v_and_b32_e32 v11, 0xffff0000, v15
	v_and_b32_e32 v10, 0xffff0000, v10
	v_pk_mul_f32 v[24:25], v[32:33], v[24:25] op_sel:[1,0] op_sel_hi:[0,1]
	v_pk_mul_f32 v[8:9], v[32:33], v[8:9] op_sel:[1,0] op_sel_hi:[0,1]
	v_pk_mul_f32 v[30:31], v[32:33], v[30:31] op_sel:[1,0] op_sel_hi:[0,1]
	v_lshlrev_b32_e32 v13, 16, v17
	v_lshlrev_b32_e32 v12, 16, v16
	v_and_b32_e32 v28, 0xffff0000, v14
	v_lshlrev_b32_e32 v15, 16, v19
	v_lshlrev_b32_e32 v14, 16, v18
	v_mul_f32_e32 v36, v35, v34
	v_pk_mul_f32 v[10:11], v[32:33], v[10:11] op_sel:[1,0] op_sel_hi:[0,1]
	v_pk_fma_f32 v[20:21], v[32:33], v[20:21], v[24:25]
	v_pk_fma_f32 v[8:9], v[32:33], v[22:23], v[8:9]
	v_pk_fma_f32 v[22:23], v[32:33], v[26:27], v[30:31]
	v_and_b32_e32 v17, 0xffff0000, v17
	v_and_b32_e32 v16, 0xffff0000, v16
	v_and_b32_e32 v19, 0xffff0000, v19
	v_and_b32_e32 v18, 0xffff0000, v18
	v_pk_fma_f32 v[10:11], v[32:33], v[28:29], v[10:11]
	v_pk_fma_f32 v[12:13], v[36:37], v[12:13], v[20:21] op_sel_hi:[0,1,1]
	v_pk_fma_f32 v[14:15], v[36:37], v[14:15], v[22:23] op_sel_hi:[0,1,1]
	v_pk_fma_f32 v[8:9], v[36:37], v[16:17], v[8:9] op_sel_hi:[0,1,1]
	v_pk_fma_f32 v[10:11], v[36:37], v[18:19], v[10:11] op_sel_hi:[0,1,1]
	v_bfe_u32 v20, v12, 16, 1
	v_bfe_u32 v21, v13, 16, 1
	v_bfe_u32 v22, v14, 16, 1
	v_bfe_u32 v23, v15, 16, 1
	v_bfe_u32 v16, v11, 16, 1
	v_bfe_u32 v17, v10, 16, 1
	v_bfe_u32 v18, v9, 16, 1
	v_bfe_u32 v19, v8, 16, 1
	v_add3_u32 v15, v15, v23, s28
	v_add3_u32 v14, v14, v22, s28
	v_add3_u32 v13, v13, v21, s28
	v_add3_u32 v12, v12, v20, s28
	v_add3_u32 v8, v8, v19, s28
	v_add3_u32 v9, v9, v18, s28
	v_add3_u32 v10, v10, v17, s28
	v_add3_u32 v11, v11, v16, s28
	v_lshrrev_b32_e32 v12, 16, v12
	v_lshrrev_b32_e32 v13, 16, v13
	v_lshrrev_b32_e32 v14, 16, v14
	v_lshrrev_b32_e32 v15, 16, v15
	v_and_or_b32 v11, v11, s21, v15
	v_and_or_b32 v10, v10, s21, v14
	v_and_or_b32 v9, v9, s21, v13
	v_and_or_b32 v8, v8, s21, v12
	global_store_dwordx4 v[0:1], v[8:11], off offset:1024
	v_lshl_add_u64 v[0:1], v[0:1], 0, s[4:5]
	s_nop 0
	s_waitcnt vmcnt(29)
; __device__ __forceinline__ unsigned pk2(float lo, float hi) { return f2bf(lo) | (f2bf(hi) << 16); }
; __global__ void __launch_bounds__(NWAVES * 64, 2) mk_fwd(Args args) {
;     ...
;         for (int m = gw; m < MTOK; m += NGW) {
; #pragma unroll
;             for (int j = 0; j < 2; ++j) {
;                 const int e = j * 512 + lane * 8, h = e >> 7;
;                 const float l0 = LSE[((size_t)0 * MTOK + m) * 8 + h], l1 = LSE[((size_t)1 * MTOK + m) * 8 + h], l2 = LSE[((size_t)2 * MTOK + m) * 8 + h];
;                 const float mx = fmaxf(l0, fmaxf(l1, l2)); float w0 = __expf(l0 - mx), w1 = __expf(l1 - mx), w2 = __expf(l2 - mx);
;                 const float inv = 1.0f / (w0 + w1 + w2); w0 *= inv; w1 *= inv; w2 *= inv;
;                 const bf16r* p = PROJ + (size_t)m * INW + O_QB + e;
;                 const v4u a0 = *(const v4u*)p, a1 = *(const v4u*)(p + 1024), a2 = *(const v4u*)(p + 2048);
;                 v4u o;
; #pragma unroll
;                 for (int q = 0; q < 4; ++q) {
;                     const float x0 = __builtin_bit_cast(float, a0[q] << 16), y0 = __builtin_bit_cast(float, a0[q] & 0xffff0000u);
;                     const float x1 = __builtin_bit_cast(float, a1[q] << 16), y1 = __builtin_bit_cast(float, a1[q] & 0xffff0000u);
;                     const float x2 = __builtin_bit_cast(float, a2[q] << 16), y2 = __builtin_bit_cast(float, a2[q] & 0xffff0000u);
;                     o[q] = pk2(w0 * x0 + w1 * x1 + w2 * x2, w0 * y0 + w1 * y1 + w2 * y2);
;                 }
;                 *(v4u*)(MIX + (size_t)m * DM + 1024 + e) = o;
;             }
	v_mov_b32_e32 v10, v82
	v_mov_b32_e32 v11, v83
	v_mov_b32_e32 v12, v84
	v_mov_b32_e32 v13, v85
	v_mov_b32_e32 v14, v86
	v_mov_b32_e32 v15, v87
	v_mov_b32_e32 v16, v88
	v_mov_b32_e32 v17, v89
	v_mov_b32_e32 v18, v90
	v_mov_b32_e32 v19, v91
	v_mov_b32_e32 v20, v92
	v_mov_b32_e32 v21, v93
	v_mov_b32_e32 v46, v106
	v_mov_b32_e32 v47, v107
	v_mov_b32_e32 v48, v108
	v_lshlrev_b32_e32 v23, 16, v11
	v_and_b32_e32 v35, 0xffff0000, v11
	v_lshlrev_b32_e32 v41, 16, v13
	v_and_b32_e32 v43, 0xffff0000, v13
	v_lshlrev_b32_e32 v8, 16, v10
	v_and_b32_e32 v10, 0xffff0000, v10
	v_max3_f32 v49, v46, v47, v48
	v_lshlrev_b32_e32 v9, 16, v19
	v_and_b32_e32 v11, 0xffff0000, v19
	v_lshlrev_b32_e32 v22, 16, v18
	v_and_b32_e32 v34, 0xffff0000, v18
	v_sub_f32_e32 v18, v46, v49
	v_sub_f32_e32 v19, v47, v49
	v_lshlrev_b32_e32 v39, 16, v21
	v_and_b32_e32 v13, 0xffff0000, v21
	v_lshlrev_b32_e32 v40, 16, v20
	v_and_b32_e32 v42, 0xffff0000, v20
	v_sub_f32_e32 v20, v48, v49
	v_mul_f32_e32 v18, 0x3fb8aa3b, v18
	v_mul_f32_e32 v21, 0x3fb8aa3b, v19
	v_mul_f32_e32 v20, 0x3fb8aa3b, v20
	v_exp_f32_e32 v19, v18
	v_exp_f32_e32 v18, v21
	v_exp_f32_e32 v21, v20
	v_lshlrev_b32_e32 v38, 16, v12
	v_and_b32_e32 v12, 0xffff0000, v12
	v_add_f32_e32 v20, v19, v18
	v_add_f32_e32 v20, v21, v20
	v_div_scale_f32 v46, s[0:1], v20, v20, 1.0
	v_rcp_f32_e32 v48, v46
	v_div_scale_f32 v47, vcc, 1.0, v20, 1.0
	v_lshlrev_b32_e32 v37, 16, v15
	v_fma_f32 v49, -v46, v48, 1.0
	v_fmac_f32_e32 v48, v49, v48
	v_mul_f32_e32 v49, v47, v48
	v_fma_f32 v50, -v46, v49, v47
	v_fmac_f32_e32 v49, v50, v48
	v_fma_f32 v46, -v46, v49, v47
	v_div_fmas_f32 v46, v46, v48, v49
	v_div_fixup_f32 v20, v46, v20, 1.0
	v_pk_mul_f32 v[18:19], v[18:19], v[20:21] op_sel_hi:[1,0]
	v_mul_f32_e32 v46, v21, v20
	v_pk_mul_f32 v[20:21], v[18:19], v[22:23] op_sel:[1,0] op_sel_hi:[0,1]
	v_pk_mul_f32 v[22:23], v[18:19], v[34:35] op_sel:[1,0] op_sel_hi:[0,1]
	v_pk_mul_f32 v[34:35], v[18:19], v[40:41] op_sel:[1,0] op_sel_hi:[0,1]
	v_pk_mul_f32 v[40:41], v[18:19], v[42:43] op_sel:[1,0] op_sel_hi:[0,1]
	v_lshlrev_b32_e32 v36, 16, v14
	v_and_b32_e32 v15, 0xffff0000, v15
	v_and_b32_e32 v14, 0xffff0000, v14
	v_lshlrev_b32_e32 v45, 16, v17
	v_lshlrev_b32_e32 v44, 16, v16
	v_and_b32_e32 v17, 0xffff0000, v17
	v_and_b32_e32 v16, 0xffff0000, v16
	v_pk_fma_f32 v[8:9], v[18:19], v[8:9], v[20:21]
	v_pk_fma_f32 v[10:11], v[18:19], v[10:11], v[22:23]
	v_pk_fma_f32 v[20:21], v[18:19], v[38:39], v[34:35]
	v_pk_fma_f32 v[12:13], v[18:19], v[12:13], v[40:41]
	v_pk_fma_f32 v[8:9], v[46:47], v[36:37], v[8:9] op_sel_hi:[0,1,1]
	v_pk_fma_f32 v[10:11], v[46:47], v[14:15], v[10:11] op_sel_hi:[0,1,1]
	v_pk_fma_f32 v[14:15], v[46:47], v[44:45], v[20:21] op_sel_hi:[0,1,1]
	v_pk_fma_f32 v[12:13], v[46:47], v[16:17], v[12:13] op_sel_hi:[0,1,1]
	v_bfe_u32 v16, v13, 16, 1
	v_bfe_u32 v17, v12, 16, 1
	v_bfe_u32 v18, v11, 16, 1
	v_bfe_u32 v19, v10, 16, 1
	v_bfe_u32 v20, v8, 16, 1
	v_bfe_u32 v21, v9, 16, 1
	v_bfe_u32 v22, v14, 16, 1
	v_bfe_u32 v23, v15, 16, 1
	v_add3_u32 v19, v10, v19, s28
	v_add3_u32 v18, v11, v18, s28
	v_add3_u32 v10, v12, v17, s28
	v_add3_u32 v11, v13, v16, s28
	v_add3_u32 v12, v15, v23, s28
	v_add3_u32 v13, v14, v22, s28
	v_add3_u32 v9, v9, v21, s28
	v_add3_u32 v8, v8, v20, s28
	v_lshrrev_b32_e32 v8, 16, v8
	v_lshrrev_b32_e32 v9, 16, v9
	v_lshrrev_b32_e32 v13, 16, v13
	v_lshrrev_b32_e32 v12, 16, v12
	v_and_or_b32 v11, v11, s21, v12
	v_and_or_b32 v10, v10, s21, v13
	v_and_or_b32 v9, v18, s21, v9
	v_and_or_b32 v8, v19, s21, v8
	global_store_dwordx4 v[0:1], v[8:11], off
	s_nop 1
	v_mov_b32_e32 v8, v94
	v_mov_b32_e32 v9, v95
	v_mov_b32_e32 v10, v96
	v_mov_b32_e32 v11, v97
	v_mov_b32_e32 v12, v98
	v_mov_b32_e32 v13, v99
	v_mov_b32_e32 v14, v100
	v_mov_b32_e32 v15, v101
	v_mov_b32_e32 v16, v102
	v_mov_b32_e32 v17, v103
	v_mov_b32_e32 v18, v104
	v_mov_b32_e32 v19, v105
	v_mov_b32_e32 v34, v109
	v_mov_b32_e32 v35, v110
	v_mov_b32_e32 v36, v111
	v_add_u32_e32 v142, 0x14800000, v154
	v_add_u32_e32 v143, 0x14801000, v154
	v_add_u32_e32 v144, 0x14802000, v154
	v_add_u32_e32 v145, 0xc200000, v155
	v_add_u32_e32 v146, 0xc300000, v155
	v_add_u32_e32 v147, 0xc400000, v155
	global_load_dwordx4 v[82:85], v143, s[26:27] offset:1024
	global_load_dword v106, v145, s[26:27]
	global_load_dwordx4 v[86:89], v143, s[26:27] offset:3072
	global_load_dword v107, v146, s[26:27]
	global_load_dword v108, v147, s[26:27]
	global_load_dwordx4 v[90:93], v142, s[26:27] offset:3072
	global_load_dword v109, v145, s[26:27] offset:16
	global_load_dword v110, v146, s[26:27] offset:16
	global_load_dword v111, v147, s[26:27] offset:16
	global_load_dwordx4 v[94:97], v143, s[26:27]
	global_load_dwordx4 v[98:101], v143, s[26:27] offset:2048
	global_load_dwordx4 v[102:105], v144, s[26:27]
	v_add_u32_e32 v154, s12, v154
	v_add_u32_e32 v155, s14, v155
	v_max3_f32 v32, v34, v35, v36
	v_sub_f32_e32 v33, v34, v32
	v_sub_f32_e32 v34, v35, v32
	v_sub_f32_e32 v32, v36, v32
	v_mul_f32_e32 v33, 0x3fb8aa3b, v33
	v_mul_f32_e32 v34, 0x3fb8aa3b, v34
	v_mul_f32_e32 v35, 0x3fb8aa3b, v32
	v_exp_f32_e32 v33, v33
	v_exp_f32_e32 v32, v34
	v_exp_f32_e32 v35, v35
	v_lshlrev_b32_e32 v21, 16, v9
	v_and_b32_e32 v23, 0xffff0000, v9
	v_add_f32_e32 v34, v33, v32
	v_add_f32_e32 v34, v35, v34
	v_div_scale_f32 v36, s[0:1], v34, v34, 1.0
	v_rcp_f32_e32 v38, v36
	v_div_scale_f32 v37, vcc, 1.0, v34, 1.0
	v_lshlrev_b32_e32 v25, 16, v13
	v_fma_f32 v39, -v36, v38, 1.0
	v_fmac_f32_e32 v38, v39, v38
	v_mul_f32_e32 v39, v37, v38
	v_fma_f32 v40, -v36, v39, v37
	v_fmac_f32_e32 v39, v40, v38
	v_fma_f32 v36, -v36, v39, v37
	v_div_fmas_f32 v36, v36, v38, v39
	v_div_fixup_f32 v34, v36, v34, 1.0
	v_lshlrev_b32_e32 v24, 16, v8
	v_and_b32_e32 v9, 0xffff0000, v13
; __device__ __forceinline__ unsigned pk2(float lo, float hi) { return f2bf(lo) | (f2bf(hi) << 16); }
; __global__ void __launch_bounds__(NWAVES * 64, 2) mk_fwd(Args args) {
;     ...
;         for (int m = gw; m < MTOK; m += NGW) {
; #pragma unroll
;             for (int j = 0; j < 2; ++j) {
;                 const int e = j * 512 + lane * 8, h = e >> 7;
;                 const float l0 = LSE[((size_t)0 * MTOK + m) * 8 + h], l1 = LSE[((size_t)1 * MTOK + m) * 8 + h], l2 = LSE[((size_t)2 * MTOK + m) * 8 + h];
;                 const float mx = fmaxf(l0, fmaxf(l1, l2)); float w0 = __expf(l0 - mx), w1 = __expf(l1 - mx), w2 = __expf(l2 - mx);
;                 const float inv = 1.0f / (w0 + w1 + w2); w0 *= inv; w1 *= inv; w2 *= inv;
;                 const bf16r* p = PROJ + (size_t)m * INW + O_QB + e;
;                 const v4u a0 = *(const v4u*)p, a1 = *(const v4u*)(p + 1024), a2 = *(const v4u*)(p + 2048);
;                 v4u o;
; #pragma unroll
;                 for (int q = 0; q < 4; ++q) {
;                     const float x0 = __builtin_bit_cast(float, a0[q] << 16), y0 = __builtin_bit_cast(float, a0[q] & 0xffff0000u);
;                     const float x1 = __builtin_bit_cast(float, a1[q] << 16), y1 = __builtin_bit_cast(float, a1[q] & 0xffff0000u);
;                     const float x2 = __builtin_bit_cast(float, a2[q] << 16), y2 = __builtin_bit_cast(float, a2[q] & 0xffff0000u);
;                     o[q] = pk2(w0 * x0 + w1 * x1 + w2 * x2, w0 * y0 + w1 * y1 + w2 * y2);
;                 }
;                 *(v4u*)(MIX + (size_t)m * DM + 1024 + e) = o;
;             }
	v_and_b32_e32 v8, 0xffff0000, v8
	v_lshlrev_b32_e32 v31, 16, v15
	v_lshlrev_b32_e32 v30, 16, v10
	v_pk_mul_f32 v[32:33], v[32:33], v[34:35] op_sel_hi:[1,0]
	v_lshlrev_b32_e32 v20, 16, v12
	v_and_b32_e32 v22, 0xffff0000, v12
	v_lshlrev_b32_e32 v27, 16, v11
	v_lshlrev_b32_e32 v26, 16, v14
	v_and_b32_e32 v29, 0xffff0000, v11
	v_and_b32_e32 v11, 0xffff0000, v15
	v_and_b32_e32 v10, 0xffff0000, v10
	v_pk_mul_f32 v[24:25], v[32:33], v[24:25] op_sel:[1,0] op_sel_hi:[0,1]
	v_pk_mul_f32 v[8:9], v[32:33], v[8:9] op_sel:[1,0] op_sel_hi:[0,1]
	v_pk_mul_f32 v[30:31], v[32:33], v[30:31] op_sel:[1,0] op_sel_hi:[0,1]
	v_lshlrev_b32_e32 v13, 16, v17
	v_lshlrev_b32_e32 v12, 16, v16
	v_and_b32_e32 v28, 0xffff0000, v14
	v_lshlrev_b32_e32 v15, 16, v19
	v_lshlrev_b32_e32 v14, 16, v18
	v_mul_f32_e32 v36, v35, v34
	v_pk_mul_f32 v[10:11], v[32:33], v[10:11] op_sel:[1,0] op_sel_hi:[0,1]
	v_pk_fma_f32 v[20:21], v[32:33], v[20:21], v[24:25]
	v_pk_fma_f32 v[8:9], v[32:33], v[22:23], v[8:9]
	v_pk_fma_f32 v[22:23], v[32:33], v[26:27], v[30:31]
	v_and_b32_e32 v17, 0xffff0000, v17
	v_and_b32_e32 v16, 0xffff0000, v16
	v_and_b32_e32 v19, 0xffff0000, v19
	v_and_b32_e32 v18, 0xffff0000, v18
	v_pk_fma_f32 v[10:11], v[32:33], v[28:29], v[10:11]
	v_pk_fma_f32 v[12:13], v[36:37], v[12:13], v[20:21] op_sel_hi:[0,1,1]
	v_pk_fma_f32 v[14:15], v[36:37], v[14:15], v[22:23] op_sel_hi:[0,1,1]
	v_pk_fma_f32 v[8:9], v[36:37], v[16:17], v[8:9] op_sel_hi:[0,1,1]
	v_pk_fma_f32 v[10:11], v[36:37], v[18:19], v[10:11] op_sel_hi:[0,1,1]
	v_bfe_u32 v20, v12, 16, 1
	v_bfe_u32 v21, v13, 16, 1
	v_bfe_u32 v22, v14, 16, 1
	v_bfe_u32 v23, v15, 16, 1
	v_bfe_u32 v16, v11, 16, 1
	v_bfe_u32 v17, v10, 16, 1
	v_bfe_u32 v18, v9, 16, 1
	v_bfe_u32 v19, v8, 16, 1
	v_add3_u32 v15, v15, v23, s28
	v_add3_u32 v14, v14, v22, s28
	v_add3_u32 v13, v13, v21, s28
	v_add3_u32 v12, v12, v20, s28
	v_add3_u32 v8, v8, v19, s28
	v_add3_u32 v9, v9, v18, s28
	v_add3_u32 v10, v10, v17, s28
	v_add3_u32 v11, v11, v16, s28
	v_lshrrev_b32_e32 v12, 16, v12
	v_lshrrev_b32_e32 v13, 16, v13
	v_lshrrev_b32_e32 v14, 16, v14
	v_lshrrev_b32_e32 v15, 16, v15
	v_and_or_b32 v11, v11, s21, v15
	v_and_or_b32 v10, v10, s21, v14
	v_and_or_b32 v9, v9, s21, v13
	v_and_or_b32 v8, v8, s21, v12
	global_store_dwordx4 v[0:1], v[8:11], off offset:1024
	v_lshl_add_u64 v[0:1], v[0:1], 0, s[4:5]
	s_nop 0
	s_waitcnt vmcnt(29)
	v_mov_b32_e32 v10, v112
	v_mov_b32_e32 v11, v113
	v_mov_b32_e32 v12, v114
	v_mov_b32_e32 v13, v115
	v_mov_b32_e32 v14, v116
	v_mov_b32_e32 v15, v117
	v_mov_b32_e32 v16, v118
	v_mov_b32_e32 v17, v119
	v_mov_b32_e32 v18, v120
	v_mov_b32_e32 v19, v121
	v_mov_b32_e32 v20, v122
	v_mov_b32_e32 v21, v123
	v_mov_b32_e32 v46, v136
	v_mov_b32_e32 v47, v137
	v_mov_b32_e32 v48, v138
	v_lshlrev_b32_e32 v23, 16, v11
	v_and_b32_e32 v35, 0xffff0000, v11
	v_lshlrev_b32_e32 v41, 16, v13
	v_and_b32_e32 v43, 0xffff0000, v13
	v_lshlrev_b32_e32 v8, 16, v10
	v_and_b32_e32 v10, 0xffff0000, v10
	v_max3_f32 v49, v46, v47, v48
	v_lshlrev_b32_e32 v9, 16, v19
	v_and_b32_e32 v11, 0xffff0000, v19
	v_lshlrev_b32_e32 v22, 16, v18
	v_and_b32_e32 v34, 0xffff0000, v18
	v_sub_f32_e32 v18, v46, v49
	v_sub_f32_e32 v19, v47, v49
	v_lshlrev_b32_e32 v39, 16, v21
	v_and_b32_e32 v13, 0xffff0000, v21
	v_lshlrev_b32_e32 v40, 16, v20
	v_and_b32_e32 v42, 0xffff0000, v20
	v_sub_f32_e32 v20, v48, v49
	v_mul_f32_e32 v18, 0x3fb8aa3b, v18
	v_mul_f32_e32 v21, 0x3fb8aa3b, v19
	v_mul_f32_e32 v20, 0x3fb8aa3b, v20
	v_exp_f32_e32 v19, v18
	v_exp_f32_e32 v18, v21
	v_exp_f32_e32 v21, v20
	v_lshlrev_b32_e32 v38, 16, v12
	v_and_b32_e32 v12, 0xffff0000, v12
	v_add_f32_e32 v20, v19, v18
	v_add_f32_e32 v20, v21, v20
	v_div_scale_f32 v46, s[0:1], v20, v20, 1.0
	v_rcp_f32_e32 v48, v46
	v_div_scale_f32 v47, vcc, 1.0, v20, 1.0
	v_lshlrev_b32_e32 v37, 16, v15
	v_fma_f32 v49, -v46, v48, 1.0
	v_fmac_f32_e32 v48, v49, v48
	v_mul_f32_e32 v49, v47, v48
	v_fma_f32 v50, -v46, v49, v47
	v_fmac_f32_e32 v49, v50, v48
	v_fma_f32 v46, -v46, v49, v47
	v_div_fmas_f32 v46, v46, v48, v49
	v_div_fixup_f32 v20, v46, v20, 1.0
	v_pk_mul_f32 v[18:19], v[18:19], v[20:21] op_sel_hi:[1,0]
	v_mul_f32_e32 v46, v21, v20
	v_pk_mul_f32 v[20:21], v[18:19], v[22:23] op_sel:[1,0] op_sel_hi:[0,1]
	v_pk_mul_f32 v[22:23], v[18:19], v[34:35] op_sel:[1,0] op_sel_hi:[0,1]
	v_pk_mul_f32 v[34:35], v[18:19], v[40:41] op_sel:[1,0] op_sel_hi:[0,1]
	v_pk_mul_f32 v[40:41], v[18:19], v[42:43] op_sel:[1,0] op_sel_hi:[0,1]
	v_lshlrev_b32_e32 v36, 16, v14
	v_and_b32_e32 v15, 0xffff0000, v15
	v_and_b32_e32 v14, 0xffff0000, v14
	v_lshlrev_b32_e32 v45, 16, v17
	v_lshlrev_b32_e32 v44, 16, v16
	v_and_b32_e32 v17, 0xffff0000, v17
	v_and_b32_e32 v16, 0xffff0000, v16
	v_pk_fma_f32 v[8:9], v[18:19], v[8:9], v[20:21]
	v_pk_fma_f32 v[10:11], v[18:19], v[10:11], v[22:23]
	v_pk_fma_f32 v[20:21], v[18:19], v[38:39], v[34:35]
	v_pk_fma_f32 v[12:13], v[18:19], v[12:13], v[40:41]
	v_pk_fma_f32 v[8:9], v[46:47], v[36:37], v[8:9] op_sel_hi:[0,1,1]
	v_pk_fma_f32 v[10:11], v[46:47], v[14:15], v[10:11] op_sel_hi:[0,1,1]
	v_pk_fma_f32 v[14:15], v[46:47], v[44:45], v[20:21] op_sel_hi:[0,1,1]
	v_pk_fma_f32 v[12:13], v[46:47], v[16:17], v[12:13] op_sel_hi:[0,1,1]
	v_bfe_u32 v16, v13, 16, 1
	v_bfe_u32 v17, v12, 16, 1
	v_bfe_u32 v18, v11, 16, 1
	v_bfe_u32 v19, v10, 16, 1
	v_bfe_u32 v20, v8, 16, 1
	v_bfe_u32 v21, v9, 16, 1
	v_bfe_u32 v22, v14, 16, 1
	v_bfe_u32 v23, v15, 16, 1
	v_add3_u32 v19, v10, v19, s28
	v_add3_u32 v18, v11, v18, s28
	v_add3_u32 v10, v12, v17, s28
	v_add3_u32 v11, v13, v16, s28
	v_add3_u32 v12, v15, v23, s28
	v_add3_u32 v13, v14, v22, s28
	v_add3_u32 v9, v9, v21, s28
	v_add3_u32 v8, v8, v20, s28
	v_lshrrev_b32_e32 v8, 16, v8
	v_lshrrev_b32_e32 v9, 16, v9
; __device__ __forceinline__ unsigned pk2(float lo, float hi) { return f2bf(lo) | (f2bf(hi) << 16); }
; __global__ void __launch_bounds__(NWAVES * 64, 2) mk_fwd(Args args) {
;     ...
;         for (int m = gw; m < MTOK; m += NGW) {
; #pragma unroll
;             for (int j = 0; j < 2; ++j) {
;                 const int e = j * 512 + lane * 8, h = e >> 7;
;                 const float l0 = LSE[((size_t)0 * MTOK + m) * 8 + h], l1 = LSE[((size_t)1 * MTOK + m) * 8 + h], l2 = LSE[((size_t)2 * MTOK + m) * 8 + h];
;                 const float mx = fmaxf(l0, fmaxf(l1, l2)); float w0 = __expf(l0 - mx), w1 = __expf(l1 - mx), w2 = __expf(l2 - mx);
;                 const float inv = 1.0f / (w0 + w1 + w2); w0 *= inv; w1 *= inv; w2 *= inv;
;                 const bf16r* p = PROJ + (size_t)m * INW + O_QB + e;
;                 const v4u a0 = *(const v4u*)p, a1 = *(const v4u*)(p + 1024), a2 = *(const v4u*)(p + 2048);
;                 v4u o;
; #pragma unroll
;                 for (int q = 0; q < 4; ++q) {
;                     const float x0 = __builtin_bit_cast(float, a0[q] << 16), y0 = __builtin_bit_cast(float, a0[q] & 0xffff0000u);
;                     const float x1 = __builtin_bit_cast(float, a1[q] << 16), y1 = __builtin_bit_cast(float, a1[q] & 0xffff0000u);
;                     const float x2 = __builtin_bit_cast(float, a2[q] << 16), y2 = __builtin_bit_cast(float, a2[q] & 0xffff0000u);
;                     o[q] = pk2(w0 * x0 + w1 * x1 + w2 * x2, w0 * y0 + w1 * y1 + w2 * y2);
;                 }
;                 *(v4u*)(MIX + (size_t)m * DM + 1024 + e) = o;
;             }
	v_lshrrev_b32_e32 v13, 16, v13
	v_lshrrev_b32_e32 v12, 16, v12
	v_and_or_b32 v11, v11, s21, v12
	v_and_or_b32 v10, v10, s21, v13
	v_and_or_b32 v9, v18, s21, v9
	v_and_or_b32 v8, v19, s21, v8
	global_store_dwordx4 v[0:1], v[8:11], off
	s_nop 1
	v_mov_b32_e32 v8, v124
	v_mov_b32_e32 v9, v125
	v_mov_b32_e32 v10, v126
	v_mov_b32_e32 v11, v127
	v_mov_b32_e32 v12, v128
	v_mov_b32_e32 v13, v129
	v_mov_b32_e32 v14, v130
	v_mov_b32_e32 v15, v131
	v_mov_b32_e32 v16, v132
	v_mov_b32_e32 v17, v133
	v_mov_b32_e32 v18, v134
	v_mov_b32_e32 v19, v135
	v_mov_b32_e32 v34, v139
	v_mov_b32_e32 v35, v140
	v_mov_b32_e32 v36, v141
	v_add_u32_e32 v148, 0x14800000, v154
	v_add_u32_e32 v149, 0x14801000, v154
	v_add_u32_e32 v150, 0x14802000, v154
	v_add_u32_e32 v151, 0xc200000, v155
	v_add_u32_e32 v152, 0xc300000, v155
	v_add_u32_e32 v153, 0xc400000, v155
	global_load_dwordx4 v[112:115], v149, s[26:27] offset:1024
	global_load_dword v136, v151, s[26:27]
	global_load_dwordx4 v[116:119], v149, s[26:27] offset:3072
	global_load_dword v137, v152, s[26:27]
	global_load_dword v138, v153, s[26:27]
	global_load_dwordx4 v[120:123], v148, s[26:27] offset:3072
	global_load_dword v139, v151, s[26:27] offset:16
	global_load_dword v140, v152, s[26:27] offset:16
	global_load_dword v141, v153, s[26:27] offset:16
	global_load_dwordx4 v[124:127], v149, s[26:27]
	global_load_dwordx4 v[128:131], v149, s[26:27] offset:2048
	global_load_dwordx4 v[132:135], v150, s[26:27]
	v_add_u32_e32 v154, s12, v154
	v_add_u32_e32 v155, s14, v155
	v_max3_f32 v32, v34, v35, v36
	v_sub_f32_e32 v33, v34, v32
	v_sub_f32_e32 v34, v35, v32
	v_sub_f32_e32 v32, v36, v32
	v_mul_f32_e32 v33, 0x3fb8aa3b, v33
	v_mul_f32_e32 v34, 0x3fb8aa3b, v34
	v_mul_f32_e32 v35, 0x3fb8aa3b, v32
	v_exp_f32_e32 v33, v33
	v_exp_f32_e32 v32, v34
	v_exp_f32_e32 v35, v35
	v_lshlrev_b32_e32 v21, 16, v9
	v_and_b32_e32 v23, 0xffff0000, v9
	v_add_f32_e32 v34, v33, v32
	v_add_f32_e32 v34, v35, v34
	v_div_scale_f32 v36, s[0:1], v34, v34, 1.0
	v_rcp_f32_e32 v38, v36
	v_div_scale_f32 v37, vcc, 1.0, v34, 1.0
	v_lshlrev_b32_e32 v25, 16, v13
	v_fma_f32 v39, -v36, v38, 1.0
	v_fmac_f32_e32 v38, v39, v38
	v_mul_f32_e32 v39, v37, v38
	v_fma_f32 v40, -v36, v39, v37
	v_fmac_f32_e32 v39, v40, v38
	v_fma_f32 v36, -v36, v39, v37
	v_div_fmas_f32 v36, v36, v38, v39
	v_div_fixup_f32 v34, v36, v34, 1.0
	v_lshlrev_b32_e32 v24, 16, v8
	v_and_b32_e32 v9, 0xffff0000, v13
	v_and_b32_e32 v8, 0xffff0000, v8
	v_lshlrev_b32_e32 v31, 16, v15
	v_lshlrev_b32_e32 v30, 16, v10
	v_pk_mul_f32 v[32:33], v[32:33], v[34:35] op_sel_hi:[1,0]
	v_lshlrev_b32_e32 v20, 16, v12
	v_and_b32_e32 v22, 0xffff0000, v12
	v_lshlrev_b32_e32 v27, 16, v11
	v_lshlrev_b32_e32 v26, 16, v14
	v_and_b32_e32 v29, 0xffff0000, v11
	v_and_b32_e32 v11, 0xffff0000, v15
	v_and_b32_e32 v10, 0xffff0000, v10
	v_pk_mul_f32 v[24:25], v[32:33], v[24:25] op_sel:[1,0] op_sel_hi:[0,1]
	v_pk_mul_f32 v[8:9], v[32:33], v[8:9] op_sel:[1,0] op_sel_hi:[0,1]
	v_pk_mul_f32 v[30:31], v[32:33], v[30:31] op_sel:[1,0] op_sel_hi:[0,1]
	v_lshlrev_b32_e32 v13, 16, v17
	v_lshlrev_b32_e32 v12, 16, v16
	v_and_b32_e32 v28, 0xffff0000, v14
	v_lshlrev_b32_e32 v15, 16, v19
	v_lshlrev_b32_e32 v14, 16, v18
	v_mul_f32_e32 v36, v35, v34
	v_pk_mul_f32 v[10:11], v[32:33], v[10:11] op_sel:[1,0] op_sel_hi:[0,1]
	v_pk_fma_f32 v[20:21], v[32:33], v[20:21], v[24:25]
	v_pk_fma_f32 v[8:9], v[32:33], v[22:23], v[8:9]
	v_pk_fma_f32 v[22:23], v[32:33], v[26:27], v[30:31]
	v_and_b32_e32 v17, 0xffff0000, v17
	v_and_b32_e32 v16, 0xffff0000, v16
	v_and_b32_e32 v19, 0xffff0000, v19
	v_and_b32_e32 v18, 0xffff0000, v18
	v_pk_fma_f32 v[10:11], v[32:33], v[28:29], v[10:11]
	v_pk_fma_f32 v[12:13], v[36:37], v[12:13], v[20:21] op_sel_hi:[0,1,1]
	v_pk_fma_f32 v[14:15], v[36:37], v[14:15], v[22:23] op_sel_hi:[0,1,1]
	v_pk_fma_f32 v[8:9], v[36:37], v[16:17], v[8:9] op_sel_hi:[0,1,1]
	v_pk_fma_f32 v[10:11], v[36:37], v[18:19], v[10:11] op_sel_hi:[0,1,1]
	v_bfe_u32 v20, v12, 16, 1
	v_bfe_u32 v21, v13, 16, 1
	v_bfe_u32 v22, v14, 16, 1
	v_bfe_u32 v23, v15, 16, 1
	v_bfe_u32 v16, v11, 16, 1
	v_bfe_u32 v17, v10, 16, 1
	v_bfe_u32 v18, v9, 16, 1
	v_bfe_u32 v19, v8, 16, 1
	v_add3_u32 v15, v15, v23, s28
	v_add3_u32 v14, v14, v22, s28
	v_add3_u32 v13, v13, v21, s28
	v_add3_u32 v12, v12, v20, s28
	v_add3_u32 v8, v8, v19, s28
	v_add3_u32 v9, v9, v18, s28
	v_add3_u32 v10, v10, v17, s28
	v_add3_u32 v11, v11, v16, s28
	v_lshrrev_b32_e32 v12, 16, v12
	v_lshrrev_b32_e32 v13, 16, v13
	v_lshrrev_b32_e32 v14, 16, v14
	v_lshrrev_b32_e32 v15, 16, v15
	v_and_or_b32 v11, v11, s21, v15
	v_and_or_b32 v10, v10, s21, v14
	v_and_or_b32 v9, v9, s21, v13
	v_and_or_b32 v8, v8, s21, v12
	global_store_dwordx4 v[0:1], v[8:11], off offset:1024
	v_lshl_add_u64 v[0:1], v[0:1], 0, s[4:5]
	s_nop 0
	s_waitcnt vmcnt(29)
; __device__ __forceinline__ unsigned pk2(float lo, float hi) { return f2bf(lo) | (f2bf(hi) << 16); }
; __global__ void __launch_bounds__(NWAVES * 64, 2) mk_fwd(Args args) {
;     ...
;         for (int m = gw; m < MTOK; m += NGW) {
; #pragma unroll
;             for (int j = 0; j < 2; ++j) {
;                 const int e = j * 512 + lane * 8, h = e >> 7;
;                 const float l0 = LSE[((size_t)0 * MTOK + m) * 8 + h], l1 = LSE[((size_t)1 * MTOK + m) * 8 + h], l2 = LSE[((size_t)2 * MTOK + m) * 8 + h];
;                 const float mx = fmaxf(l0, fmaxf(l1, l2)); float w0 = __expf(l0 - mx), w1 = __expf(l1 - mx), w2 = __expf(l2 - mx);
;                 const float inv = 1.0f / (w0 + w1 + w2); w0 *= inv; w1 *= inv; w2 *= inv;
;                 const bf16r* p = PROJ + (size_t)m * INW + O_QB + e;
;                 const v4u a0 = *(const v4u*)p, a1 = *(const v4u*)(p + 1024), a2 = *(const v4u*)(p + 2048);
;                 v4u o;
; #pragma unroll
;                 for (int q = 0; q < 4; ++q) {
;                     const float x0 = __builtin_bit_cast(float, a0[q] << 16), y0 = __builtin_bit_cast(float, a0[q] & 0xffff0000u);
;                     const float x1 = __builtin_bit_cast(float, a1[q] << 16), y1 = __builtin_bit_cast(float, a1[q] & 0xffff0000u);
;                     const float x2 = __builtin_bit_cast(float, a2[q] << 16), y2 = __builtin_bit_cast(float, a2[q] & 0xffff0000u);
;                     o[q] = pk2(w0 * x0 + w1 * x1 + w2 * x2, w0 * y0 + w1 * y1 + w2 * y2);
;                 }
;                 *(v4u*)(MIX + (size_t)m * DM + 1024 + e) = o;
;             }
	v_mov_b32_e32 v10, v52
	v_mov_b32_e32 v11, v53
	v_mov_b32_e32 v12, v54
	v_mov_b32_e32 v13, v55
	v_mov_b32_e32 v14, v56
	v_mov_b32_e32 v15, v57
	v_mov_b32_e32 v16, v58
	v_mov_b32_e32 v17, v59
	v_mov_b32_e32 v18, v60
	v_mov_b32_e32 v19, v61
	v_mov_b32_e32 v20, v62
	v_mov_b32_e32 v21, v63
	v_mov_b32_e32 v46, v76
	v_mov_b32_e32 v47, v77
	v_mov_b32_e32 v48, v78
	v_lshlrev_b32_e32 v23, 16, v11
	v_and_b32_e32 v35, 0xffff0000, v11
	v_lshlrev_b32_e32 v41, 16, v13
	v_and_b32_e32 v43, 0xffff0000, v13
	v_lshlrev_b32_e32 v8, 16, v10
	v_and_b32_e32 v10, 0xffff0000, v10
	v_max3_f32 v49, v46, v47, v48
	v_lshlrev_b32_e32 v9, 16, v19
	v_and_b32_e32 v11, 0xffff0000, v19
	v_lshlrev_b32_e32 v22, 16, v18
	v_and_b32_e32 v34, 0xffff0000, v18
	v_sub_f32_e32 v18, v46, v49
	v_sub_f32_e32 v19, v47, v49
	v_lshlrev_b32_e32 v39, 16, v21
	v_and_b32_e32 v13, 0xffff0000, v21
	v_lshlrev_b32_e32 v40, 16, v20
	v_and_b32_e32 v42, 0xffff0000, v20
	v_sub_f32_e32 v20, v48, v49
	v_mul_f32_e32 v18, 0x3fb8aa3b, v18
	v_mul_f32_e32 v21, 0x3fb8aa3b, v19
	v_mul_f32_e32 v20, 0x3fb8aa3b, v20
	v_exp_f32_e32 v19, v18
	v_exp_f32_e32 v18, v21
	v_exp_f32_e32 v21, v20
	v_lshlrev_b32_e32 v38, 16, v12
	v_and_b32_e32 v12, 0xffff0000, v12
	v_add_f32_e32 v20, v19, v18
	v_add_f32_e32 v20, v21, v20
	v_div_scale_f32 v46, s[0:1], v20, v20, 1.0
	v_rcp_f32_e32 v48, v46
	v_div_scale_f32 v47, vcc, 1.0, v20, 1.0
	v_lshlrev_b32_e32 v37, 16, v15
	v_fma_f32 v49, -v46, v48, 1.0
	v_fmac_f32_e32 v48, v49, v48
	v_mul_f32_e32 v49, v47, v48
	v_fma_f32 v50, -v46, v49, v47
	v_fmac_f32_e32 v49, v50, v48
	v_fma_f32 v46, -v46, v49, v47
	v_div_fmas_f32 v46, v46, v48, v49
	v_div_fixup_f32 v20, v46, v20, 1.0
	v_pk_mul_f32 v[18:19], v[18:19], v[20:21] op_sel_hi:[1,0]
	v_mul_f32_e32 v46, v21, v20
	v_pk_mul_f32 v[20:21], v[18:19], v[22:23] op_sel:[1,0] op_sel_hi:[0,1]
	v_pk_mul_f32 v[22:23], v[18:19], v[34:35] op_sel:[1,0] op_sel_hi:[0,1]
	v_pk_mul_f32 v[34:35], v[18:19], v[40:41] op_sel:[1,0] op_sel_hi:[0,1]
	v_pk_mul_f32 v[40:41], v[18:19], v[42:43] op_sel:[1,0] op_sel_hi:[0,1]
	v_lshlrev_b32_e32 v36, 16, v14
	v_and_b32_e32 v15, 0xffff0000, v15
	v_and_b32_e32 v14, 0xffff0000, v14
	v_lshlrev_b32_e32 v45, 16, v17
	v_lshlrev_b32_e32 v44, 16, v16
	v_and_b32_e32 v17, 0xffff0000, v17
	v_and_b32_e32 v16, 0xffff0000, v16
	v_pk_fma_f32 v[8:9], v[18:19], v[8:9], v[20:21]
	v_pk_fma_f32 v[10:11], v[18:19], v[10:11], v[22:23]
	v_pk_fma_f32 v[20:21], v[18:19], v[38:39], v[34:35]
	v_pk_fma_f32 v[12:13], v[18:19], v[12:13], v[40:41]
	v_pk_fma_f32 v[8:9], v[46:47], v[36:37], v[8:9] op_sel_hi:[0,1,1]
	v_pk_fma_f32 v[10:11], v[46:47], v[14:15], v[10:11] op_sel_hi:[0,1,1]
	v_pk_fma_f32 v[14:15], v[46:47], v[44:45], v[20:21] op_sel_hi:[0,1,1]
	v_pk_fma_f32 v[12:13], v[46:47], v[16:17], v[12:13] op_sel_hi:[0,1,1]
	v_bfe_u32 v16, v13, 16, 1
	v_bfe_u32 v17, v12, 16, 1
	v_bfe_u32 v18, v11, 16, 1
	v_bfe_u32 v19, v10, 16, 1
	v_bfe_u32 v20, v8, 16, 1
	v_bfe_u32 v21, v9, 16, 1
	v_bfe_u32 v22, v14, 16, 1
	v_bfe_u32 v23, v15, 16, 1
	v_add3_u32 v19, v10, v19, s28
	v_add3_u32 v18, v11, v18, s28
	v_add3_u32 v10, v12, v17, s28
	v_add3_u32 v11, v13, v16, s28
	v_add3_u32 v12, v15, v23, s28
	v_add3_u32 v13, v14, v22, s28
	v_add3_u32 v9, v9, v21, s28
	v_add3_u32 v8, v8, v20, s28
	v_lshrrev_b32_e32 v8, 16, v8
	v_lshrrev_b32_e32 v9, 16, v9
	v_lshrrev_b32_e32 v13, 16, v13
	v_lshrrev_b32_e32 v12, 16, v12
	v_and_or_b32 v11, v11, s21, v12
	v_and_or_b32 v10, v10, s21, v13
	v_and_or_b32 v9, v18, s21, v9
	v_and_or_b32 v8, v19, s21, v8
	global_store_dwordx4 v[0:1], v[8:11], off
	s_nop 1
	v_mov_b32_e32 v8, v64
	v_mov_b32_e32 v9, v65
	v_mov_b32_e32 v10, v66
	v_mov_b32_e32 v11, v67
	v_mov_b32_e32 v12, v68
	v_mov_b32_e32 v13, v69
	v_mov_b32_e32 v14, v70
	v_mov_b32_e32 v15, v71
	v_mov_b32_e32 v16, v72
	v_mov_b32_e32 v17, v73
	v_mov_b32_e32 v18, v74
	v_mov_b32_e32 v19, v75
	v_mov_b32_e32 v34, v79
	v_mov_b32_e32 v35, v80
	v_mov_b32_e32 v36, v81
	v_add_u32_e32 v142, 0x14800000, v154
	v_add_u32_e32 v143, 0x14801000, v154
	v_add_u32_e32 v144, 0x14802000, v154
	v_add_u32_e32 v145, 0xc200000, v155
	v_add_u32_e32 v146, 0xc300000, v155
	v_add_u32_e32 v147, 0xc400000, v155
	global_load_dwordx4 v[52:55], v143, s[26:27] offset:1024
	global_load_dword v76, v145, s[26:27]
	global_load_dwordx4 v[56:59], v143, s[26:27] offset:3072
	global_load_dword v77, v146, s[26:27]
	global_load_dword v78, v147, s[26:27]
	global_load_dwordx4 v[60:63], v142, s[26:27] offset:3072
	global_load_dword v79, v145, s[26:27] offset:16
	global_load_dword v80, v146, s[26:27] offset:16
	global_load_dword v81, v147, s[26:27] offset:16
	global_load_dwordx4 v[64:67], v143, s[26:27]
	global_load_dwordx4 v[68:71], v143, s[26:27] offset:2048
	global_load_dwordx4 v[72:75], v144, s[26:27]
	v_add_u32_e32 v154, s12, v154
	v_add_u32_e32 v155, s14, v155
	v_max3_f32 v32, v34, v35, v36
	v_sub_f32_e32 v33, v34, v32
	v_sub_f32_e32 v34, v35, v32
	v_sub_f32_e32 v32, v36, v32
	v_mul_f32_e32 v33, 0x3fb8aa3b, v33
	v_mul_f32_e32 v34, 0x3fb8aa3b, v34
	v_mul_f32_e32 v35, 0x3fb8aa3b, v32
	v_exp_f32_e32 v33, v33
	v_exp_f32_e32 v32, v34
	v_exp_f32_e32 v35, v35
	v_lshlrev_b32_e32 v21, 16, v9
	v_and_b32_e32 v23, 0xffff0000, v9
	v_add_f32_e32 v34, v33, v32
	v_add_f32_e32 v34, v35, v34
	v_div_scale_f32 v36, s[0:1], v34, v34, 1.0
	v_rcp_f32_e32 v38, v36
	v_div_scale_f32 v37, vcc, 1.0, v34, 1.0
	v_lshlrev_b32_e32 v25, 16, v13
	v_fma_f32 v39, -v36, v38, 1.0
	v_fmac_f32_e32 v38, v39, v38
	v_mul_f32_e32 v39, v37, v38
	v_fma_f32 v40, -v36, v39, v37
	v_fmac_f32_e32 v39, v40, v38
	v_fma_f32 v36, -v36, v39, v37
	v_div_fmas_f32 v36, v36, v38, v39
	v_div_fixup_f32 v34, v36, v34, 1.0
	v_lshlrev_b32_e32 v24, 16, v8
	v_and_b32_e32 v9, 0xffff0000, v13
; __device__ __forceinline__ unsigned pk2(float lo, float hi) { return f2bf(lo) | (f2bf(hi) << 16); }
; __global__ void __launch_bounds__(NWAVES * 64, 2) mk_fwd(Args args) {
;     ...
;         for (int m = gw; m < MTOK; m += NGW) {
; #pragma unroll
;             for (int j = 0; j < 2; ++j) {
;                 const int e = j * 512 + lane * 8, h = e >> 7;
;                 const float l0 = LSE[((size_t)0 * MTOK + m) * 8 + h], l1 = LSE[((size_t)1 * MTOK + m) * 8 + h], l2 = LSE[((size_t)2 * MTOK + m) * 8 + h];
;                 const float mx = fmaxf(l0, fmaxf(l1, l2)); float w0 = __expf(l0 - mx), w1 = __expf(l1 - mx), w2 = __expf(l2 - mx);
;                 const float inv = 1.0f / (w0 + w1 + w2); w0 *= inv; w1 *= inv; w2 *= inv;
;                 const bf16r* p = PROJ + (size_t)m * INW + O_QB + e;
;                 const v4u a0 = *(const v4u*)p, a1 = *(const v4u*)(p + 1024), a2 = *(const v4u*)(p + 2048);
;                 v4u o;
; #pragma unroll
;                 for (int q = 0; q < 4; ++q) {
;                     const float x0 = __builtin_bit_cast(float, a0[q] << 16), y0 = __builtin_bit_cast(float, a0[q] & 0xffff0000u);
;                     const float x1 = __builtin_bit_cast(float, a1[q] << 16), y1 = __builtin_bit_cast(float, a1[q] & 0xffff0000u);
;                     const float x2 = __builtin_bit_cast(float, a2[q] << 16), y2 = __builtin_bit_cast(float, a2[q] & 0xffff0000u);
;                     o[q] = pk2(w0 * x0 + w1 * x1 + w2 * x2, w0 * y0 + w1 * y1 + w2 * y2);
;                 }
;                 *(v4u*)(MIX + (size_t)m * DM + 1024 + e) = o;
;             }
	v_and_b32_e32 v8, 0xffff0000, v8
	v_lshlrev_b32_e32 v31, 16, v15
	v_lshlrev_b32_e32 v30, 16, v10
	v_pk_mul_f32 v[32:33], v[32:33], v[34:35] op_sel_hi:[1,0]
	v_lshlrev_b32_e32 v20, 16, v12
	v_and_b32_e32 v22, 0xffff0000, v12
	v_lshlrev_b32_e32 v27, 16, v11
	v_lshlrev_b32_e32 v26, 16, v14
	v_and_b32_e32 v29, 0xffff0000, v11
	v_and_b32_e32 v11, 0xffff0000, v15
	v_and_b32_e32 v10, 0xffff0000, v10
	v_pk_mul_f32 v[24:25], v[32:33], v[24:25] op_sel:[1,0] op_sel_hi:[0,1]
	v_pk_mul_f32 v[8:9], v[32:33], v[8:9] op_sel:[1,0] op_sel_hi:[0,1]
	v_pk_mul_f32 v[30:31], v[32:33], v[30:31] op_sel:[1,0] op_sel_hi:[0,1]
	v_lshlrev_b32_e32 v13, 16, v17
	v_lshlrev_b32_e32 v12, 16, v16
	v_and_b32_e32 v28, 0xffff0000, v14
	v_lshlrev_b32_e32 v15, 16, v19
	v_lshlrev_b32_e32 v14, 16, v18
	v_mul_f32_e32 v36, v35, v34
	v_pk_mul_f32 v[10:11], v[32:33], v[10:11] op_sel:[1,0] op_sel_hi:[0,1]
	v_pk_fma_f32 v[20:21], v[32:33], v[20:21], v[24:25]
	v_pk_fma_f32 v[8:9], v[32:33], v[22:23], v[8:9]
	v_pk_fma_f32 v[22:23], v[32:33], v[26:27], v[30:31]
	v_and_b32_e32 v17, 0xffff0000, v17
	v_and_b32_e32 v16, 0xffff0000, v16
	v_and_b32_e32 v19, 0xffff0000, v19
	v_and_b32_e32 v18, 0xffff0000, v18
	v_pk_fma_f32 v[10:11], v[32:33], v[28:29], v[10:11]
	v_pk_fma_f32 v[12:13], v[36:37], v[12:13], v[20:21] op_sel_hi:[0,1,1]
	v_pk_fma_f32 v[14:15], v[36:37], v[14:15], v[22:23] op_sel_hi:[0,1,1]
	v_pk_fma_f32 v[8:9], v[36:37], v[16:17], v[8:9] op_sel_hi:[0,1,1]
	v_pk_fma_f32 v[10:11], v[36:37], v[18:19], v[10:11] op_sel_hi:[0,1,1]
	v_bfe_u32 v20, v12, 16, 1
	v_bfe_u32 v21, v13, 16, 1
	v_bfe_u32 v22, v14, 16, 1
	v_bfe_u32 v23, v15, 16, 1
	v_bfe_u32 v16, v11, 16, 1
	v_bfe_u32 v17, v10, 16, 1
	v_bfe_u32 v18, v9, 16, 1
	v_bfe_u32 v19, v8, 16, 1
	v_add3_u32 v15, v15, v23, s28
	v_add3_u32 v14, v14, v22, s28
	v_add3_u32 v13, v13, v21, s28
	v_add3_u32 v12, v12, v20, s28
	v_add3_u32 v8, v8, v19, s28
	v_add3_u32 v9, v9, v18, s28
	v_add3_u32 v10, v10, v17, s28
	v_add3_u32 v11, v11, v16, s28
	v_lshrrev_b32_e32 v12, 16, v12
	v_lshrrev_b32_e32 v13, 16, v13
	v_lshrrev_b32_e32 v14, 16, v14
	v_lshrrev_b32_e32 v15, 16, v15
	v_and_or_b32 v11, v11, s21, v15
	v_and_or_b32 v10, v10, s21, v14
	v_and_or_b32 v9, v9, s21, v13
	v_and_or_b32 v8, v8, s21, v12
	global_store_dwordx4 v[0:1], v[8:11], off offset:1024
	v_lshl_add_u64 v[0:1], v[0:1], 0, s[4:5]
	s_nop 0
	s_waitcnt vmcnt(29)
	v_mov_b32_e32 v10, v82
	v_mov_b32_e32 v11, v83
	v_mov_b32_e32 v12, v84
	v_mov_b32_e32 v13, v85
	v_mov_b32_e32 v14, v86
	v_mov_b32_e32 v15, v87
	v_mov_b32_e32 v16, v88
	v_mov_b32_e32 v17, v89
	v_mov_b32_e32 v18, v90
	v_mov_b32_e32 v19, v91
	v_mov_b32_e32 v20, v92
	v_mov_b32_e32 v21, v93
	v_mov_b32_e32 v46, v106
	v_mov_b32_e32 v47, v107
	v_mov_b32_e32 v48, v108
	v_lshlrev_b32_e32 v23, 16, v11
	v_and_b32_e32 v35, 0xffff0000, v11
	v_lshlrev_b32_e32 v41, 16, v13
	v_and_b32_e32 v43, 0xffff0000, v13
	v_lshlrev_b32_e32 v8, 16, v10
	v_and_b32_e32 v10, 0xffff0000, v10
	v_max3_f32 v49, v46, v47, v48
	v_lshlrev_b32_e32 v9, 16, v19
	v_and_b32_e32 v11, 0xffff0000, v19
	v_lshlrev_b32_e32 v22, 16, v18
	v_and_b32_e32 v34, 0xffff0000, v18
	v_sub_f32_e32 v18, v46, v49
	v_sub_f32_e32 v19, v47, v49
	v_lshlrev_b32_e32 v39, 16, v21
	v_and_b32_e32 v13, 0xffff0000, v21
	v_lshlrev_b32_e32 v40, 16, v20
	v_and_b32_e32 v42, 0xffff0000, v20
	v_sub_f32_e32 v20, v48, v49
	v_mul_f32_e32 v18, 0x3fb8aa3b, v18
	v_mul_f32_e32 v21, 0x3fb8aa3b, v19
	v_mul_f32_e32 v20, 0x3fb8aa3b, v20
	v_exp_f32_e32 v19, v18
	v_exp_f32_e32 v18, v21
	v_exp_f32_e32 v21, v20
	v_lshlrev_b32_e32 v38, 16, v12
	v_and_b32_e32 v12, 0xffff0000, v12
	v_add_f32_e32 v20, v19, v18
	v_add_f32_e32 v20, v21, v20
	v_div_scale_f32 v46, s[0:1], v20, v20, 1.0
	v_rcp_f32_e32 v48, v46
	v_div_scale_f32 v47, vcc, 1.0, v20, 1.0
	v_lshlrev_b32_e32 v37, 16, v15
	v_fma_f32 v49, -v46, v48, 1.0
	v_fmac_f32_e32 v48, v49, v48
	v_mul_f32_e32 v49, v47, v48
	v_fma_f32 v50, -v46, v49, v47
	v_fmac_f32_e32 v49, v50, v48
	v_fma_f32 v46, -v46, v49, v47
	v_div_fmas_f32 v46, v46, v48, v49
	v_div_fixup_f32 v20, v46, v20, 1.0
	v_pk_mul_f32 v[18:19], v[18:19], v[20:21] op_sel_hi:[1,0]
	v_mul_f32_e32 v46, v21, v20
	v_pk_mul_f32 v[20:21], v[18:19], v[22:23] op_sel:[1,0] op_sel_hi:[0,1]
	v_pk_mul_f32 v[22:23], v[18:19], v[34:35] op_sel:[1,0] op_sel_hi:[0,1]
	v_pk_mul_f32 v[34:35], v[18:19], v[40:41] op_sel:[1,0] op_sel_hi:[0,1]
	v_pk_mul_f32 v[40:41], v[18:19], v[42:43] op_sel:[1,0] op_sel_hi:[0,1]
	v_lshlrev_b32_e32 v36, 16, v14
	v_and_b32_e32 v15, 0xffff0000, v15
	v_and_b32_e32 v14, 0xffff0000, v14
	v_lshlrev_b32_e32 v45, 16, v17
	v_lshlrev_b32_e32 v44, 16, v16
	v_and_b32_e32 v17, 0xffff0000, v17
	v_and_b32_e32 v16, 0xffff0000, v16
	v_pk_fma_f32 v[8:9], v[18:19], v[8:9], v[20:21]
	v_pk_fma_f32 v[10:11], v[18:19], v[10:11], v[22:23]
	v_pk_fma_f32 v[20:21], v[18:19], v[38:39], v[34:35]
	v_pk_fma_f32 v[12:13], v[18:19], v[12:13], v[40:41]
	v_pk_fma_f32 v[8:9], v[46:47], v[36:37], v[8:9] op_sel_hi:[0,1,1]
	v_pk_fma_f32 v[10:11], v[46:47], v[14:15], v[10:11] op_sel_hi:[0,1,1]
	v_pk_fma_f32 v[14:15], v[46:47], v[44:45], v[20:21] op_sel_hi:[0,1,1]
	v_pk_fma_f32 v[12:13], v[46:47], v[16:17], v[12:13] op_sel_hi:[0,1,1]
	v_bfe_u32 v16, v13, 16, 1
	v_bfe_u32 v17, v12, 16, 1
	v_bfe_u32 v18, v11, 16, 1
	v_bfe_u32 v19, v10, 16, 1
	v_bfe_u32 v20, v8, 16, 1
	v_bfe_u32 v21, v9, 16, 1
	v_bfe_u32 v22, v14, 16, 1
	v_bfe_u32 v23, v15, 16, 1
	v_add3_u32 v19, v10, v19, s28
	v_add3_u32 v18, v11, v18, s28
	v_add3_u32 v10, v12, v17, s28
	v_add3_u32 v11, v13, v16, s28
	v_add3_u32 v12, v15, v23, s28
	v_add3_u32 v13, v14, v22, s28
	v_add3_u32 v9, v9, v21, s28
	v_add3_u32 v8, v8, v20, s28
	v_lshrrev_b32_e32 v8, 16, v8
	v_lshrrev_b32_e32 v9, 16, v9
; __device__ __forceinline__ unsigned pk2(float lo, float hi) { return f2bf(lo) | (f2bf(hi) << 16); }
; __global__ void __launch_bounds__(NWAVES * 64, 2) mk_fwd(Args args) {
;     ...
;         for (int m = gw; m < MTOK; m += NGW) {
; #pragma unroll
;             for (int j = 0; j < 2; ++j) {
;                 const int e = j * 512 + lane * 8, h = e >> 7;
;                 const float l0 = LSE[((size_t)0 * MTOK + m) * 8 + h], l1 = LSE[((size_t)1 * MTOK + m) * 8 + h], l2 = LSE[((size_t)2 * MTOK + m) * 8 + h];
;                 const float mx = fmaxf(l0, fmaxf(l1, l2)); float w0 = __expf(l0 - mx), w1 = __expf(l1 - mx), w2 = __expf(l2 - mx);
;                 const float inv = 1.0f / (w0 + w1 + w2); w0 *= inv; w1 *= inv; w2 *= inv;
;                 const bf16r* p = PROJ + (size_t)m * INW + O_QB + e;
;                 const v4u a0 = *(const v4u*)p, a1 = *(const v4u*)(p + 1024), a2 = *(const v4u*)(p + 2048);
;                 v4u o;
; #pragma unroll
;                 for (int q = 0; q < 4; ++q) {
;                     const float x0 = __builtin_bit_cast(float, a0[q] << 16), y0 = __builtin_bit_cast(float, a0[q] & 0xffff0000u);
;                     const float x1 = __builtin_bit_cast(float, a1[q] << 16), y1 = __builtin_bit_cast(float, a1[q] & 0xffff0000u);
;                     const float x2 = __builtin_bit_cast(float, a2[q] << 16), y2 = __builtin_bit_cast(float, a2[q] & 0xffff0000u);
;                     o[q] = pk2(w0 * x0 + w1 * x1 + w2 * x2, w0 * y0 + w1 * y1 + w2 * y2);
;                 }
;                 *(v4u*)(MIX + (size_t)m * DM + 1024 + e) = o;
;             }
	v_lshrrev_b32_e32 v13, 16, v13
	v_lshrrev_b32_e32 v12, 16, v12
	v_and_or_b32 v11, v11, s21, v12
	v_and_or_b32 v10, v10, s21, v13
	v_and_or_b32 v9, v18, s21, v9
	v_and_or_b32 v8, v19, s21, v8
	global_store_dwordx4 v[0:1], v[8:11], off
	s_nop 1
	v_mov_b32_e32 v8, v94
	v_mov_b32_e32 v9, v95
	v_mov_b32_e32 v10, v96
	v_mov_b32_e32 v11, v97
	v_mov_b32_e32 v12, v98
	v_mov_b32_e32 v13, v99
	v_mov_b32_e32 v14, v100
	v_mov_b32_e32 v15, v101
	v_mov_b32_e32 v16, v102
	v_mov_b32_e32 v17, v103
	v_mov_b32_e32 v18, v104
	v_mov_b32_e32 v19, v105
	v_mov_b32_e32 v34, v109
	v_mov_b32_e32 v35, v110
	v_mov_b32_e32 v36, v111
	v_add_u32_e32 v148, 0x14800000, v154
	v_add_u32_e32 v149, 0x14801000, v154
	v_add_u32_e32 v150, 0x14802000, v154
	v_add_u32_e32 v151, 0xc200000, v155
	v_add_u32_e32 v152, 0xc300000, v155
	v_add_u32_e32 v153, 0xc400000, v155
	global_load_dwordx4 v[82:85], v149, s[26:27] offset:1024
	global_load_dword v106, v151, s[26:27]
	global_load_dwordx4 v[86:89], v149, s[26:27] offset:3072
	global_load_dword v107, v152, s[26:27]
	global_load_dword v108, v153, s[26:27]
	global_load_dwordx4 v[90:93], v148, s[26:27] offset:3072
	global_load_dword v109, v151, s[26:27] offset:16
	global_load_dword v110, v152, s[26:27] offset:16
	global_load_dword v111, v153, s[26:27] offset:16
	global_load_dwordx4 v[94:97], v149, s[26:27]
	global_load_dwordx4 v[98:101], v149, s[26:27] offset:2048
	global_load_dwordx4 v[102:105], v150, s[26:27]
	v_add_u32_e32 v154, s12, v154
	v_add_u32_e32 v155, s14, v155
	v_max3_f32 v32, v34, v35, v36
	v_sub_f32_e32 v33, v34, v32
	v_sub_f32_e32 v34, v35, v32
	v_sub_f32_e32 v32, v36, v32
	v_mul_f32_e32 v33, 0x3fb8aa3b, v33
	v_mul_f32_e32 v34, 0x3fb8aa3b, v34
	v_mul_f32_e32 v35, 0x3fb8aa3b, v32
	v_exp_f32_e32 v33, v33
	v_exp_f32_e32 v32, v34
	v_exp_f32_e32 v35, v35
	v_lshlrev_b32_e32 v21, 16, v9
	v_and_b32_e32 v23, 0xffff0000, v9
	v_add_f32_e32 v34, v33, v32
	v_add_f32_e32 v34, v35, v34
	v_div_scale_f32 v36, s[0:1], v34, v34, 1.0
	v_rcp_f32_e32 v38, v36
	v_div_scale_f32 v37, vcc, 1.0, v34, 1.0
	v_lshlrev_b32_e32 v25, 16, v13
	v_fma_f32 v39, -v36, v38, 1.0
	v_fmac_f32_e32 v38, v39, v38
	v_mul_f32_e32 v39, v37, v38
	v_fma_f32 v40, -v36, v39, v37
	v_fmac_f32_e32 v39, v40, v38
	v_fma_f32 v36, -v36, v39, v37
	v_div_fmas_f32 v36, v36, v38, v39
	v_div_fixup_f32 v34, v36, v34, 1.0
	v_lshlrev_b32_e32 v24, 16, v8
	v_and_b32_e32 v9, 0xffff0000, v13
	v_and_b32_e32 v8, 0xffff0000, v8
	v_lshlrev_b32_e32 v31, 16, v15
	v_lshlrev_b32_e32 v30, 16, v10
	v_pk_mul_f32 v[32:33], v[32:33], v[34:35] op_sel_hi:[1,0]
	v_lshlrev_b32_e32 v20, 16, v12
	v_and_b32_e32 v22, 0xffff0000, v12
	v_lshlrev_b32_e32 v27, 16, v11
	v_lshlrev_b32_e32 v26, 16, v14
	v_and_b32_e32 v29, 0xffff0000, v11
	v_and_b32_e32 v11, 0xffff0000, v15
	v_and_b32_e32 v10, 0xffff0000, v10
	v_pk_mul_f32 v[24:25], v[32:33], v[24:25] op_sel:[1,0] op_sel_hi:[0,1]
	v_pk_mul_f32 v[8:9], v[32:33], v[8:9] op_sel:[1,0] op_sel_hi:[0,1]
	v_pk_mul_f32 v[30:31], v[32:33], v[30:31] op_sel:[1,0] op_sel_hi:[0,1]
	v_lshlrev_b32_e32 v13, 16, v17
	v_lshlrev_b32_e32 v12, 16, v16
	v_and_b32_e32 v28, 0xffff0000, v14
	v_lshlrev_b32_e32 v15, 16, v19
	v_lshlrev_b32_e32 v14, 16, v18
	v_mul_f32_e32 v36, v35, v34
	v_pk_mul_f32 v[10:11], v[32:33], v[10:11] op_sel:[1,0] op_sel_hi:[0,1]
	v_pk_fma_f32 v[20:21], v[32:33], v[20:21], v[24:25]
	v_pk_fma_f32 v[8:9], v[32:33], v[22:23], v[8:9]
	v_pk_fma_f32 v[22:23], v[32:33], v[26:27], v[30:31]
	v_and_b32_e32 v17, 0xffff0000, v17
	v_and_b32_e32 v16, 0xffff0000, v16
	v_and_b32_e32 v19, 0xffff0000, v19
	v_and_b32_e32 v18, 0xffff0000, v18
	v_pk_fma_f32 v[10:11], v[32:33], v[28:29], v[10:11]
	v_pk_fma_f32 v[12:13], v[36:37], v[12:13], v[20:21] op_sel_hi:[0,1,1]
	v_pk_fma_f32 v[14:15], v[36:37], v[14:15], v[22:23] op_sel_hi:[0,1,1]
	v_pk_fma_f32 v[8:9], v[36:37], v[16:17], v[8:9] op_sel_hi:[0,1,1]
	v_pk_fma_f32 v[10:11], v[36:37], v[18:19], v[10:11] op_sel_hi:[0,1,1]
	v_bfe_u32 v20, v12, 16, 1
	v_bfe_u32 v21, v13, 16, 1
	v_bfe_u32 v22, v14, 16, 1
	v_bfe_u32 v23, v15, 16, 1
	v_bfe_u32 v16, v11, 16, 1
	v_bfe_u32 v17, v10, 16, 1
	v_bfe_u32 v18, v9, 16, 1
	v_bfe_u32 v19, v8, 16, 1
	v_add3_u32 v15, v15, v23, s28
	v_add3_u32 v14, v14, v22, s28
	v_add3_u32 v13, v13, v21, s28
	v_add3_u32 v12, v12, v20, s28
	v_add3_u32 v8, v8, v19, s28
	v_add3_u32 v9, v9, v18, s28
	v_add3_u32 v10, v10, v17, s28
	v_add3_u32 v11, v11, v16, s28
	v_lshrrev_b32_e32 v12, 16, v12
	v_lshrrev_b32_e32 v13, 16, v13
	v_lshrrev_b32_e32 v14, 16, v14
	v_lshrrev_b32_e32 v15, 16, v15
	v_and_or_b32 v11, v11, s21, v15
	v_and_or_b32 v10, v10, s21, v14
	v_and_or_b32 v9, v9, s21, v13
	v_and_or_b32 v8, v8, s21, v12
	global_store_dwordx4 v[0:1], v[8:11], off offset:1024
	v_lshl_add_u64 v[0:1], v[0:1], 0, s[4:5]
	s_nop 0
	s_waitcnt vmcnt(29)
; __device__ __forceinline__ unsigned pk2(float lo, float hi) { return f2bf(lo) | (f2bf(hi) << 16); }
; __global__ void __launch_bounds__(NWAVES * 64, 2) mk_fwd(Args args) {
;     ...
;         for (int m = gw; m < MTOK; m += NGW) {
; #pragma unroll
;             for (int j = 0; j < 2; ++j) {
;                 const int e = j * 512 + lane * 8, h = e >> 7;
;                 const float l0 = LSE[((size_t)0 * MTOK + m) * 8 + h], l1 = LSE[((size_t)1 * MTOK + m) * 8 + h], l2 = LSE[((size_t)2 * MTOK + m) * 8 + h];
;                 const float mx = fmaxf(l0, fmaxf(l1, l2)); float w0 = __expf(l0 - mx), w1 = __expf(l1 - mx), w2 = __expf(l2 - mx);
;                 const float inv = 1.0f / (w0 + w1 + w2); w0 *= inv; w1 *= inv; w2 *= inv;
;                 const bf16r* p = PROJ + (size_t)m * INW + O_QB + e;
;                 const v4u a0 = *(const v4u*)p, a1 = *(const v4u*)(p + 1024), a2 = *(const v4u*)(p + 2048);
;                 v4u o;
; #pragma unroll
;                 for (int q = 0; q < 4; ++q) {
;                     const float x0 = __builtin_bit_cast(float, a0[q] << 16), y0 = __builtin_bit_cast(float, a0[q] & 0xffff0000u);
;                     const float x1 = __builtin_bit_cast(float, a1[q] << 16), y1 = __builtin_bit_cast(float, a1[q] & 0xffff0000u);
;                     const float x2 = __builtin_bit_cast(float, a2[q] << 16), y2 = __builtin_bit_cast(float, a2[q] & 0xffff0000u);
;                     o[q] = pk2(w0 * x0 + w1 * x1 + w2 * x2, w0 * y0 + w1 * y1 + w2 * y2);
;                 }
;                 *(v4u*)(MIX + (size_t)m * DM + 1024 + e) = o;
;             }
	v_mov_b32_e32 v10, v112
	v_mov_b32_e32 v11, v113
	v_mov_b32_e32 v12, v114
	v_mov_b32_e32 v13, v115
	v_mov_b32_e32 v14, v116
	v_mov_b32_e32 v15, v117
	v_mov_b32_e32 v16, v118
	v_mov_b32_e32 v17, v119
	v_mov_b32_e32 v18, v120
	v_mov_b32_e32 v19, v121
	v_mov_b32_e32 v20, v122
	v_mov_b32_e32 v21, v123
	v_mov_b32_e32 v46, v136
	v_mov_b32_e32 v47, v137
	v_mov_b32_e32 v48, v138
	v_lshlrev_b32_e32 v23, 16, v11
	v_and_b32_e32 v35, 0xffff0000, v11
	v_lshlrev_b32_e32 v41, 16, v13
	v_and_b32_e32 v43, 0xffff0000, v13
	v_lshlrev_b32_e32 v8, 16, v10
	v_and_b32_e32 v10, 0xffff0000, v10
	v_max3_f32 v49, v46, v47, v48
	v_lshlrev_b32_e32 v9, 16, v19
	v_and_b32_e32 v11, 0xffff0000, v19
	v_lshlrev_b32_e32 v22, 16, v18
	v_and_b32_e32 v34, 0xffff0000, v18
	v_sub_f32_e32 v18, v46, v49
	v_sub_f32_e32 v19, v47, v49
	v_lshlrev_b32_e32 v39, 16, v21
	v_and_b32_e32 v13, 0xffff0000, v21
	v_lshlrev_b32_e32 v40, 16, v20
	v_and_b32_e32 v42, 0xffff0000, v20
	v_sub_f32_e32 v20, v48, v49
	v_mul_f32_e32 v18, 0x3fb8aa3b, v18
	v_mul_f32_e32 v21, 0x3fb8aa3b, v19
	v_mul_f32_e32 v20, 0x3fb8aa3b, v20
	v_exp_f32_e32 v19, v18
	v_exp_f32_e32 v18, v21
	v_exp_f32_e32 v21, v20
	v_lshlrev_b32_e32 v38, 16, v12
	v_and_b32_e32 v12, 0xffff0000, v12
	v_add_f32_e32 v20, v19, v18
	v_add_f32_e32 v20, v21, v20
	v_div_scale_f32 v46, s[0:1], v20, v20, 1.0
	v_rcp_f32_e32 v48, v46
	v_div_scale_f32 v47, vcc, 1.0, v20, 1.0
	v_lshlrev_b32_e32 v37, 16, v15
	v_fma_f32 v49, -v46, v48, 1.0
	v_fmac_f32_e32 v48, v49, v48
	v_mul_f32_e32 v49, v47, v48
	v_fma_f32 v50, -v46, v49, v47
	v_fmac_f32_e32 v49, v50, v48
	v_fma_f32 v46, -v46, v49, v47
	v_div_fmas_f32 v46, v46, v48, v49
	v_div_fixup_f32 v20, v46, v20, 1.0
	v_pk_mul_f32 v[18:19], v[18:19], v[20:21] op_sel_hi:[1,0]
	v_mul_f32_e32 v46, v21, v20
	v_pk_mul_f32 v[20:21], v[18:19], v[22:23] op_sel:[1,0] op_sel_hi:[0,1]
	v_pk_mul_f32 v[22:23], v[18:19], v[34:35] op_sel:[1,0] op_sel_hi:[0,1]
	v_pk_mul_f32 v[34:35], v[18:19], v[40:41] op_sel:[1,0] op_sel_hi:[0,1]
	v_pk_mul_f32 v[40:41], v[18:19], v[42:43] op_sel:[1,0] op_sel_hi:[0,1]
	v_lshlrev_b32_e32 v36, 16, v14
	v_and_b32_e32 v15, 0xffff0000, v15
	v_and_b32_e32 v14, 0xffff0000, v14
	v_lshlrev_b32_e32 v45, 16, v17
	v_lshlrev_b32_e32 v44, 16, v16
	v_and_b32_e32 v17, 0xffff0000, v17
	v_and_b32_e32 v16, 0xffff0000, v16
	v_pk_fma_f32 v[8:9], v[18:19], v[8:9], v[20:21]
	v_pk_fma_f32 v[10:11], v[18:19], v[10:11], v[22:23]
	v_pk_fma_f32 v[20:21], v[18:19], v[38:39], v[34:35]
	v_pk_fma_f32 v[12:13], v[18:19], v[12:13], v[40:41]
	v_pk_fma_f32 v[8:9], v[46:47], v[36:37], v[8:9] op_sel_hi:[0,1,1]
	v_pk_fma_f32 v[10:11], v[46:47], v[14:15], v[10:11] op_sel_hi:[0,1,1]
	v_pk_fma_f32 v[14:15], v[46:47], v[44:45], v[20:21] op_sel_hi:[0,1,1]
	v_pk_fma_f32 v[12:13], v[46:47], v[16:17], v[12:13] op_sel_hi:[0,1,1]
	v_bfe_u32 v16, v13, 16, 1
	v_bfe_u32 v17, v12, 16, 1
	v_bfe_u32 v18, v11, 16, 1
	v_bfe_u32 v19, v10, 16, 1
	v_bfe_u32 v20, v8, 16, 1
	v_bfe_u32 v21, v9, 16, 1
	v_bfe_u32 v22, v14, 16, 1
	v_bfe_u32 v23, v15, 16, 1
	v_add3_u32 v19, v10, v19, s28
	v_add3_u32 v18, v11, v18, s28
	v_add3_u32 v10, v12, v17, s28
	v_add3_u32 v11, v13, v16, s28
	v_add3_u32 v12, v15, v23, s28
	v_add3_u32 v13, v14, v22, s28
	v_add3_u32 v9, v9, v21, s28
	v_add3_u32 v8, v8, v20, s28
	v_lshrrev_b32_e32 v8, 16, v8
	v_lshrrev_b32_e32 v9, 16, v9
	v_lshrrev_b32_e32 v13, 16, v13
	v_lshrrev_b32_e32 v12, 16, v12
	v_and_or_b32 v11, v11, s21, v12
	v_and_or_b32 v10, v10, s21, v13
	v_and_or_b32 v9, v18, s21, v9
	v_and_or_b32 v8, v19, s21, v8
	global_store_dwordx4 v[0:1], v[8:11], off
	s_nop 1
	v_mov_b32_e32 v8, v124
	v_mov_b32_e32 v9, v125
	v_mov_b32_e32 v10, v126
	v_mov_b32_e32 v11, v127
	v_mov_b32_e32 v12, v128
	v_mov_b32_e32 v13, v129
	v_mov_b32_e32 v14, v130
	v_mov_b32_e32 v15, v131
	v_mov_b32_e32 v16, v132
	v_mov_b32_e32 v17, v133
	v_mov_b32_e32 v18, v134
	v_mov_b32_e32 v19, v135
	v_mov_b32_e32 v34, v139
	v_mov_b32_e32 v35, v140
	v_mov_b32_e32 v36, v141
	v_add_u32_e32 v142, 0x14800000, v154
	v_add_u32_e32 v143, 0x14801000, v154
	v_add_u32_e32 v144, 0x14802000, v154
	v_add_u32_e32 v145, 0xc200000, v155
	v_add_u32_e32 v146, 0xc300000, v155
	v_add_u32_e32 v147, 0xc400000, v155
	global_load_dwordx4 v[112:115], v143, s[26:27] offset:1024
	global_load_dword v136, v145, s[26:27]
	global_load_dwordx4 v[116:119], v143, s[26:27] offset:3072
	global_load_dword v137, v146, s[26:27]
	global_load_dword v138, v147, s[26:27]
	global_load_dwordx4 v[120:123], v142, s[26:27] offset:3072
	global_load_dword v139, v145, s[26:27] offset:16
	global_load_dword v140, v146, s[26:27] offset:16
	global_load_dword v141, v147, s[26:27] offset:16
	global_load_dwordx4 v[124:127], v143, s[26:27]
	global_load_dwordx4 v[128:131], v143, s[26:27] offset:2048
	global_load_dwordx4 v[132:135], v144, s[26:27]
	v_add_u32_e32 v154, s12, v154
	v_add_u32_e32 v155, s14, v155
	v_max3_f32 v32, v34, v35, v36
	v_sub_f32_e32 v33, v34, v32
	v_sub_f32_e32 v34, v35, v32
	v_sub_f32_e32 v32, v36, v32
	v_mul_f32_e32 v33, 0x3fb8aa3b, v33
	v_mul_f32_e32 v34, 0x3fb8aa3b, v34
	v_mul_f32_e32 v35, 0x3fb8aa3b, v32
	v_exp_f32_e32 v33, v33
	v_exp_f32_e32 v32, v34
	v_exp_f32_e32 v35, v35
	v_lshlrev_b32_e32 v21, 16, v9
	v_and_b32_e32 v23, 0xffff0000, v9
	v_add_f32_e32 v34, v33, v32
	v_add_f32_e32 v34, v35, v34
	v_div_scale_f32 v36, s[0:1], v34, v34, 1.0
	v_rcp_f32_e32 v38, v36
	v_div_scale_f32 v37, vcc, 1.0, v34, 1.0
	v_lshlrev_b32_e32 v25, 16, v13
	v_fma_f32 v39, -v36, v38, 1.0
	v_fmac_f32_e32 v38, v39, v38
	v_mul_f32_e32 v39, v37, v38
	v_fma_f32 v40, -v36, v39, v37
	v_fmac_f32_e32 v39, v40, v38
	v_fma_f32 v36, -v36, v39, v37
	v_div_fmas_f32 v36, v36, v38, v39
	v_div_fixup_f32 v34, v36, v34, 1.0
	v_lshlrev_b32_e32 v24, 16, v8
; __device__ __forceinline__ unsigned pk2(float lo, float hi) { return f2bf(lo) | (f2bf(hi) << 16); }
; __global__ void __launch_bounds__(NWAVES * 64, 2) mk_fwd(Args args) {
;     ...
;         for (int m = gw; m < MTOK; m += NGW) {
; #pragma unroll
;             for (int j = 0; j < 2; ++j) {
;                 const int e = j * 512 + lane * 8, h = e >> 7;
;                 const float l0 = LSE[((size_t)0 * MTOK + m) * 8 + h], l1 = LSE[((size_t)1 * MTOK + m) * 8 + h], l2 = LSE[((size_t)2 * MTOK + m) * 8 + h];
;                 const float mx = fmaxf(l0, fmaxf(l1, l2)); float w0 = __expf(l0 - mx), w1 = __expf(l1 - mx), w2 = __expf(l2 - mx);
;                 const float inv = 1.0f / (w0 + w1 + w2); w0 *= inv; w1 *= inv; w2 *= inv;
;                 const bf16r* p = PROJ + (size_t)m * INW + O_QB + e;
;                 const v4u a0 = *(const v4u*)p, a1 = *(const v4u*)(p + 1024), a2 = *(const v4u*)(p + 2048);
;                 v4u o;
; #pragma unroll
;                 for (int q = 0; q < 4; ++q) {
;                     const float x0 = __builtin_bit_cast(float, a0[q] << 16), y0 = __builtin_bit_cast(float, a0[q] & 0xffff0000u);
;                     const float x1 = __builtin_bit_cast(float, a1[q] << 16), y1 = __builtin_bit_cast(float, a1[q] & 0xffff0000u);
;                     const float x2 = __builtin_bit_cast(float, a2[q] << 16), y2 = __builtin_bit_cast(float, a2[q] & 0xffff0000u);
;                     o[q] = pk2(w0 * x0 + w1 * x1 + w2 * x2, w0 * y0 + w1 * y1 + w2 * y2);
;                 }
;                 *(v4u*)(MIX + (size_t)m * DM + 1024 + e) = o;
;             }
	v_and_b32_e32 v9, 0xffff0000, v13
	v_and_b32_e32 v8, 0xffff0000, v8
	v_lshlrev_b32_e32 v31, 16, v15
	v_lshlrev_b32_e32 v30, 16, v10
	v_pk_mul_f32 v[32:33], v[32:33], v[34:35] op_sel_hi:[1,0]
	v_lshlrev_b32_e32 v20, 16, v12
	v_and_b32_e32 v22, 0xffff0000, v12
	v_lshlrev_b32_e32 v27, 16, v11
	v_lshlrev_b32_e32 v26, 16, v14
	v_and_b32_e32 v29, 0xffff0000, v11
	v_and_b32_e32 v11, 0xffff0000, v15
	v_and_b32_e32 v10, 0xffff0000, v10
	v_pk_mul_f32 v[24:25], v[32:33], v[24:25] op_sel:[1,0] op_sel_hi:[0,1]
	v_pk_mul_f32 v[8:9], v[32:33], v[8:9] op_sel:[1,0] op_sel_hi:[0,1]
	v_pk_mul_f32 v[30:31], v[32:33], v[30:31] op_sel:[1,0] op_sel_hi:[0,1]
	v_lshlrev_b32_e32 v13, 16, v17
	v_lshlrev_b32_e32 v12, 16, v16
	v_and_b32_e32 v28, 0xffff0000, v14
	v_lshlrev_b32_e32 v15, 16, v19
	v_lshlrev_b32_e32 v14, 16, v18
	v_mul_f32_e32 v36, v35, v34
	v_pk_mul_f32 v[10:11], v[32:33], v[10:11] op_sel:[1,0] op_sel_hi:[0,1]
	v_pk_fma_f32 v[20:21], v[32:33], v[20:21], v[24:25]
	v_pk_fma_f32 v[8:9], v[32:33], v[22:23], v[8:9]
	v_pk_fma_f32 v[22:23], v[32:33], v[26:27], v[30:31]
	v_and_b32_e32 v17, 0xffff0000, v17
	v_and_b32_e32 v16, 0xffff0000, v16
	v_and_b32_e32 v19, 0xffff0000, v19
	v_and_b32_e32 v18, 0xffff0000, v18
	v_pk_fma_f32 v[10:11], v[32:33], v[28:29], v[10:11]
	v_pk_fma_f32 v[12:13], v[36:37], v[12:13], v[20:21] op_sel_hi:[0,1,1]
	v_pk_fma_f32 v[14:15], v[36:37], v[14:15], v[22:23] op_sel_hi:[0,1,1]
	v_pk_fma_f32 v[8:9], v[36:37], v[16:17], v[8:9] op_sel_hi:[0,1,1]
	v_pk_fma_f32 v[10:11], v[36:37], v[18:19], v[10:11] op_sel_hi:[0,1,1]
	v_bfe_u32 v20, v12, 16, 1
	v_bfe_u32 v21, v13, 16, 1
	v_bfe_u32 v22, v14, 16, 1
	v_bfe_u32 v23, v15, 16, 1
	v_bfe_u32 v16, v11, 16, 1
	v_bfe_u32 v17, v10, 16, 1
	v_bfe_u32 v18, v9, 16, 1
	v_bfe_u32 v19, v8, 16, 1
	v_add3_u32 v15, v15, v23, s28
	v_add3_u32 v14, v14, v22, s28
	v_add3_u32 v13, v13, v21, s28
	v_add3_u32 v12, v12, v20, s28
	v_add3_u32 v8, v8, v19, s28
	v_add3_u32 v9, v9, v18, s28
	v_add3_u32 v10, v10, v17, s28
	v_add3_u32 v11, v11, v16, s28
	v_lshrrev_b32_e32 v12, 16, v12
	v_lshrrev_b32_e32 v13, 16, v13
	v_lshrrev_b32_e32 v14, 16, v14
	v_lshrrev_b32_e32 v15, 16, v15
	v_and_or_b32 v11, v11, s21, v15
	v_and_or_b32 v10, v10, s21, v14
	v_and_or_b32 v9, v9, s21, v13
	v_and_or_b32 v8, v8, s21, v12
	global_store_dwordx4 v[0:1], v[8:11], off offset:1024
	v_lshl_add_u64 v[0:1], v[0:1], 0, s[4:5]
	s_nop 0
	s_waitcnt vmcnt(29)
	v_mov_b32_e32 v10, v52
	v_mov_b32_e32 v11, v53
	v_mov_b32_e32 v12, v54
	v_mov_b32_e32 v13, v55
	v_mov_b32_e32 v14, v56
	v_mov_b32_e32 v15, v57
	v_mov_b32_e32 v16, v58
	v_mov_b32_e32 v17, v59
	v_mov_b32_e32 v18, v60
	v_mov_b32_e32 v19, v61
	v_mov_b32_e32 v20, v62
	v_mov_b32_e32 v21, v63
	v_mov_b32_e32 v46, v76
	v_mov_b32_e32 v47, v77
	v_mov_b32_e32 v48, v78
	v_lshlrev_b32_e32 v23, 16, v11
	v_and_b32_e32 v35, 0xffff0000, v11
	v_lshlrev_b32_e32 v41, 16, v13
	v_and_b32_e32 v43, 0xffff0000, v13
	v_lshlrev_b32_e32 v8, 16, v10
	v_and_b32_e32 v10, 0xffff0000, v10
	v_max3_f32 v49, v46, v47, v48
	v_lshlrev_b32_e32 v9, 16, v19
	v_and_b32_e32 v11, 0xffff0000, v19
	v_lshlrev_b32_e32 v22, 16, v18
	v_and_b32_e32 v34, 0xffff0000, v18
	v_sub_f32_e32 v18, v46, v49
	v_sub_f32_e32 v19, v47, v49
	v_lshlrev_b32_e32 v39, 16, v21
	v_and_b32_e32 v13, 0xffff0000, v21
	v_lshlrev_b32_e32 v40, 16, v20
	v_and_b32_e32 v42, 0xffff0000, v20
	v_sub_f32_e32 v20, v48, v49
	v_mul_f32_e32 v18, 0x3fb8aa3b, v18
	v_mul_f32_e32 v21, 0x3fb8aa3b, v19
	v_mul_f32_e32 v20, 0x3fb8aa3b, v20
	v_exp_f32_e32 v19, v18
	v_exp_f32_e32 v18, v21
	v_exp_f32_e32 v21, v20
	v_lshlrev_b32_e32 v38, 16, v12
	v_and_b32_e32 v12, 0xffff0000, v12
	v_add_f32_e32 v20, v19, v18
	v_add_f32_e32 v20, v21, v20
	v_div_scale_f32 v46, s[0:1], v20, v20, 1.0
	v_rcp_f32_e32 v48, v46
	v_div_scale_f32 v47, vcc, 1.0, v20, 1.0
	v_lshlrev_b32_e32 v37, 16, v15
	v_fma_f32 v49, -v46, v48, 1.0
	v_fmac_f32_e32 v48, v49, v48
	v_mul_f32_e32 v49, v47, v48
	v_fma_f32 v50, -v46, v49, v47
	v_fmac_f32_e32 v49, v50, v48
	v_fma_f32 v46, -v46, v49, v47
	v_div_fmas_f32 v46, v46, v48, v49
	v_div_fixup_f32 v20, v46, v20, 1.0
	v_pk_mul_f32 v[18:19], v[18:19], v[20:21] op_sel_hi:[1,0]
	v_mul_f32_e32 v46, v21, v20
	v_pk_mul_f32 v[20:21], v[18:19], v[22:23] op_sel:[1,0] op_sel_hi:[0,1]
	v_pk_mul_f32 v[22:23], v[18:19], v[34:35] op_sel:[1,0] op_sel_hi:[0,1]
	v_pk_mul_f32 v[34:35], v[18:19], v[40:41] op_sel:[1,0] op_sel_hi:[0,1]
	v_pk_mul_f32 v[40:41], v[18:19], v[42:43] op_sel:[1,0] op_sel_hi:[0,1]
	v_lshlrev_b32_e32 v36, 16, v14
	v_and_b32_e32 v15, 0xffff0000, v15
	v_and_b32_e32 v14, 0xffff0000, v14
	v_lshlrev_b32_e32 v45, 16, v17
	v_lshlrev_b32_e32 v44, 16, v16
	v_and_b32_e32 v17, 0xffff0000, v17
	v_and_b32_e32 v16, 0xffff0000, v16
	v_pk_fma_f32 v[8:9], v[18:19], v[8:9], v[20:21]
	v_pk_fma_f32 v[10:11], v[18:19], v[10:11], v[22:23]
	v_pk_fma_f32 v[20:21], v[18:19], v[38:39], v[34:35]
	v_pk_fma_f32 v[12:13], v[18:19], v[12:13], v[40:41]
	v_pk_fma_f32 v[8:9], v[46:47], v[36:37], v[8:9] op_sel_hi:[0,1,1]
	v_pk_fma_f32 v[10:11], v[46:47], v[14:15], v[10:11] op_sel_hi:[0,1,1]
	v_pk_fma_f32 v[14:15], v[46:47], v[44:45], v[20:21] op_sel_hi:[0,1,1]
	v_pk_fma_f32 v[12:13], v[46:47], v[16:17], v[12:13] op_sel_hi:[0,1,1]
	v_bfe_u32 v16, v13, 16, 1
	v_bfe_u32 v17, v12, 16, 1
	v_bfe_u32 v18, v11, 16, 1
	v_bfe_u32 v19, v10, 16, 1
	v_bfe_u32 v20, v8, 16, 1
	v_bfe_u32 v21, v9, 16, 1
	v_bfe_u32 v22, v14, 16, 1
	v_bfe_u32 v23, v15, 16, 1
	v_add3_u32 v19, v10, v19, s28
	v_add3_u32 v18, v11, v18, s28
	v_add3_u32 v10, v12, v17, s28
	v_add3_u32 v11, v13, v16, s28
	v_add3_u32 v12, v15, v23, s28
	v_add3_u32 v13, v14, v22, s28
	v_add3_u32 v9, v9, v21, s28
	v_add3_u32 v8, v8, v20, s28
	v_lshrrev_b32_e32 v8, 16, v8
; __device__ __forceinline__ unsigned pk2(float lo, float hi) { return f2bf(lo) | (f2bf(hi) << 16); }
; __global__ void __launch_bounds__(NWAVES * 64, 2) mk_fwd(Args args) {
;     ...
;         for (int m = gw; m < MTOK; m += NGW) {
; #pragma unroll
;             for (int j = 0; j < 2; ++j) {
;                 const int e = j * 512 + lane * 8, h = e >> 7;
;                 const float l0 = LSE[((size_t)0 * MTOK + m) * 8 + h], l1 = LSE[((size_t)1 * MTOK + m) * 8 + h], l2 = LSE[((size_t)2 * MTOK + m) * 8 + h];
;                 const float mx = fmaxf(l0, fmaxf(l1, l2)); float w0 = __expf(l0 - mx), w1 = __expf(l1 - mx), w2 = __expf(l2 - mx);
;                 const float inv = 1.0f / (w0 + w1 + w2); w0 *= inv; w1 *= inv; w2 *= inv;
;                 const bf16r* p = PROJ + (size_t)m * INW + O_QB + e;
;                 const v4u a0 = *(const v4u*)p, a1 = *(const v4u*)(p + 1024), a2 = *(const v4u*)(p + 2048);
;                 v4u o;
; #pragma unroll
;                 for (int q = 0; q < 4; ++q) {
;                     const float x0 = __builtin_bit_cast(float, a0[q] << 16), y0 = __builtin_bit_cast(float, a0[q] & 0xffff0000u);
;                     const float x1 = __builtin_bit_cast(float, a1[q] << 16), y1 = __builtin_bit_cast(float, a1[q] & 0xffff0000u);
;                     const float x2 = __builtin_bit_cast(float, a2[q] << 16), y2 = __builtin_bit_cast(float, a2[q] & 0xffff0000u);
;                     o[q] = pk2(w0 * x0 + w1 * x1 + w2 * x2, w0 * y0 + w1 * y1 + w2 * y2);
;                 }
;                 *(v4u*)(MIX + (size_t)m * DM + 1024 + e) = o;
;             }
	v_lshrrev_b32_e32 v9, 16, v9
	v_lshrrev_b32_e32 v13, 16, v13
	v_lshrrev_b32_e32 v12, 16, v12
	v_and_or_b32 v11, v11, s21, v12
	v_and_or_b32 v10, v10, s21, v13
	v_and_or_b32 v9, v18, s21, v9
	v_and_or_b32 v8, v19, s21, v8
	global_store_dwordx4 v[0:1], v[8:11], off
	s_nop 1
	v_mov_b32_e32 v8, v64
	v_mov_b32_e32 v9, v65
	v_mov_b32_e32 v10, v66
	v_mov_b32_e32 v11, v67
	v_mov_b32_e32 v12, v68
	v_mov_b32_e32 v13, v69
	v_mov_b32_e32 v14, v70
	v_mov_b32_e32 v15, v71
	v_mov_b32_e32 v16, v72
	v_mov_b32_e32 v17, v73
	v_mov_b32_e32 v18, v74
	v_mov_b32_e32 v19, v75
	v_mov_b32_e32 v34, v79
	v_mov_b32_e32 v35, v80
	v_mov_b32_e32 v36, v81
	v_add_u32_e32 v148, 0x14800000, v154
	v_add_u32_e32 v149, 0x14801000, v154
	v_add_u32_e32 v150, 0x14802000, v154
	v_add_u32_e32 v151, 0xc200000, v155
	v_add_u32_e32 v152, 0xc300000, v155
	v_add_u32_e32 v153, 0xc400000, v155
	global_load_dwordx4 v[52:55], v149, s[26:27] offset:1024
	global_load_dword v76, v151, s[26:27]
	global_load_dwordx4 v[56:59], v149, s[26:27] offset:3072
	global_load_dword v77, v152, s[26:27]
	global_load_dword v78, v153, s[26:27]
	global_load_dwordx4 v[60:63], v148, s[26:27] offset:3072
	global_load_dword v79, v151, s[26:27] offset:16
	global_load_dword v80, v152, s[26:27] offset:16
	global_load_dword v81, v153, s[26:27] offset:16
	global_load_dwordx4 v[64:67], v149, s[26:27]
	global_load_dwordx4 v[68:71], v149, s[26:27] offset:2048
	global_load_dwordx4 v[72:75], v150, s[26:27]
	v_add_u32_e32 v154, s12, v154
	v_add_u32_e32 v155, s14, v155
	v_max3_f32 v32, v34, v35, v36
	v_sub_f32_e32 v33, v34, v32
	v_sub_f32_e32 v34, v35, v32
	v_sub_f32_e32 v32, v36, v32
	v_mul_f32_e32 v33, 0x3fb8aa3b, v33
	v_mul_f32_e32 v34, 0x3fb8aa3b, v34
	v_mul_f32_e32 v35, 0x3fb8aa3b, v32
	v_exp_f32_e32 v33, v33
	v_exp_f32_e32 v32, v34
	v_exp_f32_e32 v35, v35
	v_lshlrev_b32_e32 v21, 16, v9
	v_and_b32_e32 v23, 0xffff0000, v9
	v_add_f32_e32 v34, v33, v32
	v_add_f32_e32 v34, v35, v34
	v_div_scale_f32 v36, s[0:1], v34, v34, 1.0
	v_rcp_f32_e32 v38, v36
	v_div_scale_f32 v37, vcc, 1.0, v34, 1.0
	v_lshlrev_b32_e32 v25, 16, v13
	v_fma_f32 v39, -v36, v38, 1.0
	v_fmac_f32_e32 v38, v39, v38
	v_mul_f32_e32 v39, v37, v38
	v_fma_f32 v40, -v36, v39, v37
	v_fmac_f32_e32 v39, v40, v38
	v_fma_f32 v36, -v36, v39, v37
	v_div_fmas_f32 v36, v36, v38, v39
	v_div_fixup_f32 v34, v36, v34, 1.0
	v_lshlrev_b32_e32 v24, 16, v8
	v_and_b32_e32 v9, 0xffff0000, v13
	v_and_b32_e32 v8, 0xffff0000, v8
	v_lshlrev_b32_e32 v31, 16, v15
	v_lshlrev_b32_e32 v30, 16, v10
	v_pk_mul_f32 v[32:33], v[32:33], v[34:35] op_sel_hi:[1,0]
	v_lshlrev_b32_e32 v20, 16, v12
	v_and_b32_e32 v22, 0xffff0000, v12
	v_lshlrev_b32_e32 v27, 16, v11
	v_lshlrev_b32_e32 v26, 16, v14
	v_and_b32_e32 v29, 0xffff0000, v11
	v_and_b32_e32 v11, 0xffff0000, v15
	v_and_b32_e32 v10, 0xffff0000, v10
	v_pk_mul_f32 v[24:25], v[32:33], v[24:25] op_sel:[1,0] op_sel_hi:[0,1]
	v_pk_mul_f32 v[8:9], v[32:33], v[8:9] op_sel:[1,0] op_sel_hi:[0,1]
	v_pk_mul_f32 v[30:31], v[32:33], v[30:31] op_sel:[1,0] op_sel_hi:[0,1]
	v_lshlrev_b32_e32 v13, 16, v17
	v_lshlrev_b32_e32 v12, 16, v16
	v_and_b32_e32 v28, 0xffff0000, v14
	v_lshlrev_b32_e32 v15, 16, v19
	v_lshlrev_b32_e32 v14, 16, v18
	v_mul_f32_e32 v36, v35, v34
	v_pk_mul_f32 v[10:11], v[32:33], v[10:11] op_sel:[1,0] op_sel_hi:[0,1]
	v_pk_fma_f32 v[20:21], v[32:33], v[20:21], v[24:25]
	v_pk_fma_f32 v[8:9], v[32:33], v[22:23], v[8:9]
	v_pk_fma_f32 v[22:23], v[32:33], v[26:27], v[30:31]
	v_and_b32_e32 v17, 0xffff0000, v17
	v_and_b32_e32 v16, 0xffff0000, v16
	v_and_b32_e32 v19, 0xffff0000, v19
	v_and_b32_e32 v18, 0xffff0000, v18
	v_pk_fma_f32 v[10:11], v[32:33], v[28:29], v[10:11]
	v_pk_fma_f32 v[12:13], v[36:37], v[12:13], v[20:21] op_sel_hi:[0,1,1]
	v_pk_fma_f32 v[14:15], v[36:37], v[14:15], v[22:23] op_sel_hi:[0,1,1]
	v_pk_fma_f32 v[8:9], v[36:37], v[16:17], v[8:9] op_sel_hi:[0,1,1]
	v_pk_fma_f32 v[10:11], v[36:37], v[18:19], v[10:11] op_sel_hi:[0,1,1]
	v_bfe_u32 v20, v12, 16, 1
	v_bfe_u32 v21, v13, 16, 1
	v_bfe_u32 v22, v14, 16, 1
	v_bfe_u32 v23, v15, 16, 1
	v_bfe_u32 v16, v11, 16, 1
	v_bfe_u32 v17, v10, 16, 1
	v_bfe_u32 v18, v9, 16, 1
	v_bfe_u32 v19, v8, 16, 1
	v_add3_u32 v15, v15, v23, s28
	v_add3_u32 v14, v14, v22, s28
	v_add3_u32 v13, v13, v21, s28
	v_add3_u32 v12, v12, v20, s28
	v_add3_u32 v8, v8, v19, s28
	v_add3_u32 v9, v9, v18, s28
	v_add3_u32 v10, v10, v17, s28
	v_add3_u32 v11, v11, v16, s28
	v_lshrrev_b32_e32 v12, 16, v12
	v_lshrrev_b32_e32 v13, 16, v13
	v_lshrrev_b32_e32 v14, 16, v14
	v_lshrrev_b32_e32 v15, 16, v15
	v_and_or_b32 v11, v11, s21, v15
	v_and_or_b32 v10, v10, s21, v14
	v_and_or_b32 v9, v9, s21, v13
	v_and_or_b32 v8, v8, s21, v12
	global_store_dwordx4 v[0:1], v[8:11], off offset:1024
	v_lshl_add_u64 v[0:1], v[0:1], 0, s[4:5]
	s_nop 0
	s_waitcnt vmcnt(29)
; __device__ __forceinline__ unsigned pk2(float lo, float hi) { return f2bf(lo) | (f2bf(hi) << 16); }
; __global__ void __launch_bounds__(NWAVES * 64, 2) mk_fwd(Args args) {
;     ...
;         for (int m = gw; m < MTOK; m += NGW) {
; #pragma unroll
;             for (int j = 0; j < 2; ++j) {
;                 const int e = j * 512 + lane * 8, h = e >> 7;
;                 const float l0 = LSE[((size_t)0 * MTOK + m) * 8 + h], l1 = LSE[((size_t)1 * MTOK + m) * 8 + h], l2 = LSE[((size_t)2 * MTOK + m) * 8 + h];
;                 const float mx = fmaxf(l0, fmaxf(l1, l2)); float w0 = __expf(l0 - mx), w1 = __expf(l1 - mx), w2 = __expf(l2 - mx);
;                 const float inv = 1.0f / (w0 + w1 + w2); w0 *= inv; w1 *= inv; w2 *= inv;
;                 const bf16r* p = PROJ + (size_t)m * INW + O_QB + e;
;                 const v4u a0 = *(const v4u*)p, a1 = *(const v4u*)(p + 1024), a2 = *(const v4u*)(p + 2048);
;                 v4u o;
; #pragma unroll
;                 for (int q = 0; q < 4; ++q) {
;                     const float x0 = __builtin_bit_cast(float, a0[q] << 16), y0 = __builtin_bit_cast(float, a0[q] & 0xffff0000u);
;                     const float x1 = __builtin_bit_cast(float, a1[q] << 16), y1 = __builtin_bit_cast(float, a1[q] & 0xffff0000u);
;                     const float x2 = __builtin_bit_cast(float, a2[q] << 16), y2 = __builtin_bit_cast(float, a2[q] & 0xffff0000u);
;                     o[q] = pk2(w0 * x0 + w1 * x1 + w2 * x2, w0 * y0 + w1 * y1 + w2 * y2);
;                 }
;                 *(v4u*)(MIX + (size_t)m * DM + 1024 + e) = o;
;             }
	v_mov_b32_e32 v10, v82
	v_mov_b32_e32 v11, v83
	v_mov_b32_e32 v12, v84
	v_mov_b32_e32 v13, v85
	v_mov_b32_e32 v14, v86
	v_mov_b32_e32 v15, v87
	v_mov_b32_e32 v16, v88
	v_mov_b32_e32 v17, v89
	v_mov_b32_e32 v18, v90
	v_mov_b32_e32 v19, v91
	v_mov_b32_e32 v20, v92
	v_mov_b32_e32 v21, v93
	v_mov_b32_e32 v46, v106
	v_mov_b32_e32 v47, v107
	v_mov_b32_e32 v48, v108
	v_lshlrev_b32_e32 v23, 16, v11
	v_and_b32_e32 v35, 0xffff0000, v11
	v_lshlrev_b32_e32 v41, 16, v13
	v_and_b32_e32 v43, 0xffff0000, v13
	v_lshlrev_b32_e32 v8, 16, v10
	v_and_b32_e32 v10, 0xffff0000, v10
	v_max3_f32 v49, v46, v47, v48
	v_lshlrev_b32_e32 v9, 16, v19
	v_and_b32_e32 v11, 0xffff0000, v19
	v_lshlrev_b32_e32 v22, 16, v18
	v_and_b32_e32 v34, 0xffff0000, v18
	v_sub_f32_e32 v18, v46, v49
	v_sub_f32_e32 v19, v47, v49
	v_lshlrev_b32_e32 v39, 16, v21
	v_and_b32_e32 v13, 0xffff0000, v21
	v_lshlrev_b32_e32 v40, 16, v20
	v_and_b32_e32 v42, 0xffff0000, v20
	v_sub_f32_e32 v20, v48, v49
	v_mul_f32_e32 v18, 0x3fb8aa3b, v18
	v_mul_f32_e32 v21, 0x3fb8aa3b, v19
	v_mul_f32_e32 v20, 0x3fb8aa3b, v20
	v_exp_f32_e32 v19, v18
	v_exp_f32_e32 v18, v21
	v_exp_f32_e32 v21, v20
	v_lshlrev_b32_e32 v38, 16, v12
	v_and_b32_e32 v12, 0xffff0000, v12
	v_add_f32_e32 v20, v19, v18
	v_add_f32_e32 v20, v21, v20
	v_div_scale_f32 v46, s[0:1], v20, v20, 1.0
	v_rcp_f32_e32 v48, v46
	v_div_scale_f32 v47, vcc, 1.0, v20, 1.0
	v_lshlrev_b32_e32 v37, 16, v15
	v_fma_f32 v49, -v46, v48, 1.0
	v_fmac_f32_e32 v48, v49, v48
	v_mul_f32_e32 v49, v47, v48
	v_fma_f32 v50, -v46, v49, v47
	v_fmac_f32_e32 v49, v50, v48
	v_fma_f32 v46, -v46, v49, v47
	v_div_fmas_f32 v46, v46, v48, v49
	v_div_fixup_f32 v20, v46, v20, 1.0
	v_pk_mul_f32 v[18:19], v[18:19], v[20:21] op_sel_hi:[1,0]
	v_mul_f32_e32 v46, v21, v20
	v_pk_mul_f32 v[20:21], v[18:19], v[22:23] op_sel:[1,0] op_sel_hi:[0,1]
	v_pk_mul_f32 v[22:23], v[18:19], v[34:35] op_sel:[1,0] op_sel_hi:[0,1]
	v_pk_mul_f32 v[34:35], v[18:19], v[40:41] op_sel:[1,0] op_sel_hi:[0,1]
	v_pk_mul_f32 v[40:41], v[18:19], v[42:43] op_sel:[1,0] op_sel_hi:[0,1]
	v_lshlrev_b32_e32 v36, 16, v14
	v_and_b32_e32 v15, 0xffff0000, v15
	v_and_b32_e32 v14, 0xffff0000, v14
	v_lshlrev_b32_e32 v45, 16, v17
	v_lshlrev_b32_e32 v44, 16, v16
	v_and_b32_e32 v17, 0xffff0000, v17
	v_and_b32_e32 v16, 0xffff0000, v16
	v_pk_fma_f32 v[8:9], v[18:19], v[8:9], v[20:21]
	v_pk_fma_f32 v[10:11], v[18:19], v[10:11], v[22:23]
	v_pk_fma_f32 v[20:21], v[18:19], v[38:39], v[34:35]
	v_pk_fma_f32 v[12:13], v[18:19], v[12:13], v[40:41]
	v_pk_fma_f32 v[8:9], v[46:47], v[36:37], v[8:9] op_sel_hi:[0,1,1]
	v_pk_fma_f32 v[10:11], v[46:47], v[14:15], v[10:11] op_sel_hi:[0,1,1]
	v_pk_fma_f32 v[14:15], v[46:47], v[44:45], v[20:21] op_sel_hi:[0,1,1]
	v_pk_fma_f32 v[12:13], v[46:47], v[16:17], v[12:13] op_sel_hi:[0,1,1]
	v_bfe_u32 v16, v13, 16, 1
	v_bfe_u32 v17, v12, 16, 1
	v_bfe_u32 v18, v11, 16, 1
	v_bfe_u32 v19, v10, 16, 1
	v_bfe_u32 v20, v8, 16, 1
	v_bfe_u32 v21, v9, 16, 1
	v_bfe_u32 v22, v14, 16, 1
	v_bfe_u32 v23, v15, 16, 1
	v_add3_u32 v19, v10, v19, s28
	v_add3_u32 v18, v11, v18, s28
	v_add3_u32 v10, v12, v17, s28
	v_add3_u32 v11, v13, v16, s28
	v_add3_u32 v12, v15, v23, s28
	v_add3_u32 v13, v14, v22, s28
	v_add3_u32 v9, v9, v21, s28
	v_add3_u32 v8, v8, v20, s28
	v_lshrrev_b32_e32 v8, 16, v8
	v_lshrrev_b32_e32 v9, 16, v9
	v_lshrrev_b32_e32 v13, 16, v13
	v_lshrrev_b32_e32 v12, 16, v12
	v_and_or_b32 v11, v11, s21, v12
	v_and_or_b32 v10, v10, s21, v13
	v_and_or_b32 v9, v18, s21, v9
	v_and_or_b32 v8, v19, s21, v8
	global_store_dwordx4 v[0:1], v[8:11], off
	s_nop 1
	v_mov_b32_e32 v8, v94
	v_mov_b32_e32 v9, v95
	v_mov_b32_e32 v10, v96
	v_mov_b32_e32 v11, v97
	v_mov_b32_e32 v12, v98
	v_mov_b32_e32 v13, v99
	v_mov_b32_e32 v14, v100
	v_mov_b32_e32 v15, v101
	v_mov_b32_e32 v16, v102
	v_mov_b32_e32 v17, v103
	v_mov_b32_e32 v18, v104
	v_mov_b32_e32 v19, v105
	v_mov_b32_e32 v34, v109
	v_mov_b32_e32 v35, v110
	v_mov_b32_e32 v36, v111
	v_max3_f32 v32, v34, v35, v36
	v_sub_f32_e32 v33, v34, v32
	v_sub_f32_e32 v34, v35, v32
	v_sub_f32_e32 v32, v36, v32
	v_mul_f32_e32 v33, 0x3fb8aa3b, v33
	v_mul_f32_e32 v34, 0x3fb8aa3b, v34
	v_mul_f32_e32 v35, 0x3fb8aa3b, v32
	v_exp_f32_e32 v33, v33
	v_exp_f32_e32 v32, v34
	v_exp_f32_e32 v35, v35
	v_lshlrev_b32_e32 v21, 16, v9
	v_and_b32_e32 v23, 0xffff0000, v9
	v_add_f32_e32 v34, v33, v32
	v_add_f32_e32 v34, v35, v34
	v_div_scale_f32 v36, s[0:1], v34, v34, 1.0
	v_rcp_f32_e32 v38, v36
	v_div_scale_f32 v37, vcc, 1.0, v34, 1.0
	v_lshlrev_b32_e32 v25, 16, v13
	v_fma_f32 v39, -v36, v38, 1.0
	v_fmac_f32_e32 v38, v39, v38
	v_mul_f32_e32 v39, v37, v38
	v_fma_f32 v40, -v36, v39, v37
	v_fmac_f32_e32 v39, v40, v38
	v_fma_f32 v36, -v36, v39, v37
	v_div_fmas_f32 v36, v36, v38, v39
	v_div_fixup_f32 v34, v36, v34, 1.0
	v_lshlrev_b32_e32 v24, 16, v8
	v_and_b32_e32 v9, 0xffff0000, v13
	v_and_b32_e32 v8, 0xffff0000, v8
	v_lshlrev_b32_e32 v31, 16, v15
	v_lshlrev_b32_e32 v30, 16, v10
	v_pk_mul_f32 v[32:33], v[32:33], v[34:35] op_sel_hi:[1,0]
	v_lshlrev_b32_e32 v20, 16, v12
	v_and_b32_e32 v22, 0xffff0000, v12
	v_lshlrev_b32_e32 v27, 16, v11
	v_lshlrev_b32_e32 v26, 16, v14
	v_and_b32_e32 v29, 0xffff0000, v11
	v_and_b32_e32 v11, 0xffff0000, v15
	v_and_b32_e32 v10, 0xffff0000, v10
	v_pk_mul_f32 v[24:25], v[32:33], v[24:25] op_sel:[1,0] op_sel_hi:[0,1]
	v_pk_mul_f32 v[8:9], v[32:33], v[8:9] op_sel:[1,0] op_sel_hi:[0,1]
	v_pk_mul_f32 v[30:31], v[32:33], v[30:31] op_sel:[1,0] op_sel_hi:[0,1]
	v_lshlrev_b32_e32 v13, 16, v17
	v_lshlrev_b32_e32 v12, 16, v16
	v_and_b32_e32 v28, 0xffff0000, v14
	v_lshlrev_b32_e32 v15, 16, v19
	v_lshlrev_b32_e32 v14, 16, v18
	v_mul_f32_e32 v36, v35, v34
	v_pk_mul_f32 v[10:11], v[32:33], v[10:11] op_sel:[1,0] op_sel_hi:[0,1]
; __device__ __forceinline__ unsigned pk2(float lo, float hi) { return f2bf(lo) | (f2bf(hi) << 16); }
; __global__ void __launch_bounds__(NWAVES * 64, 2) mk_fwd(Args args) {
;     ...
;         for (int m = gw; m < MTOK; m += NGW) {
; #pragma unroll
;             for (int j = 0; j < 2; ++j) {
;                 const int e = j * 512 + lane * 8, h = e >> 7;
;                 const float l0 = LSE[((size_t)0 * MTOK + m) * 8 + h], l1 = LSE[((size_t)1 * MTOK + m) * 8 + h], l2 = LSE[((size_t)2 * MTOK + m) * 8 + h];
;                 const float mx = fmaxf(l0, fmaxf(l1, l2)); float w0 = __expf(l0 - mx), w1 = __expf(l1 - mx), w2 = __expf(l2 - mx);
;                 const float inv = 1.0f / (w0 + w1 + w2); w0 *= inv; w1 *= inv; w2 *= inv;
;                 const bf16r* p = PROJ + (size_t)m * INW + O_QB + e;
;                 const v4u a0 = *(const v4u*)p, a1 = *(const v4u*)(p + 1024), a2 = *(const v4u*)(p + 2048);
;                 v4u o;
; #pragma unroll
;                 for (int q = 0; q < 4; ++q) {
;                     const float x0 = __builtin_bit_cast(float, a0[q] << 16), y0 = __builtin_bit_cast(float, a0[q] & 0xffff0000u);
;                     const float x1 = __builtin_bit_cast(float, a1[q] << 16), y1 = __builtin_bit_cast(float, a1[q] & 0xffff0000u);
;                     const float x2 = __builtin_bit_cast(float, a2[q] << 16), y2 = __builtin_bit_cast(float, a2[q] & 0xffff0000u);
;                     o[q] = pk2(w0 * x0 + w1 * x1 + w2 * x2, w0 * y0 + w1 * y1 + w2 * y2);
;                 }
;                 *(v4u*)(MIX + (size_t)m * DM + 1024 + e) = o;
;             }
	v_pk_fma_f32 v[20:21], v[32:33], v[20:21], v[24:25]
	v_pk_fma_f32 v[8:9], v[32:33], v[22:23], v[8:9]
	v_pk_fma_f32 v[22:23], v[32:33], v[26:27], v[30:31]
	v_and_b32_e32 v17, 0xffff0000, v17
	v_and_b32_e32 v16, 0xffff0000, v16
	v_and_b32_e32 v19, 0xffff0000, v19
	v_and_b32_e32 v18, 0xffff0000, v18
	v_pk_fma_f32 v[10:11], v[32:33], v[28:29], v[10:11]
	v_pk_fma_f32 v[12:13], v[36:37], v[12:13], v[20:21] op_sel_hi:[0,1,1]
	v_pk_fma_f32 v[14:15], v[36:37], v[14:15], v[22:23] op_sel_hi:[0,1,1]
	v_pk_fma_f32 v[8:9], v[36:37], v[16:17], v[8:9] op_sel_hi:[0,1,1]
	v_pk_fma_f32 v[10:11], v[36:37], v[18:19], v[10:11] op_sel_hi:[0,1,1]
	v_bfe_u32 v20, v12, 16, 1
	v_bfe_u32 v21, v13, 16, 1
	v_bfe_u32 v22, v14, 16, 1
	v_bfe_u32 v23, v15, 16, 1
	v_bfe_u32 v16, v11, 16, 1
	v_bfe_u32 v17, v10, 16, 1
	v_bfe_u32 v18, v9, 16, 1
	v_bfe_u32 v19, v8, 16, 1
	v_add3_u32 v15, v15, v23, s28
	v_add3_u32 v14, v14, v22, s28
	v_add3_u32 v13, v13, v21, s28
	v_add3_u32 v12, v12, v20, s28
	v_add3_u32 v8, v8, v19, s28
	v_add3_u32 v9, v9, v18, s28
	v_add3_u32 v10, v10, v17, s28
	v_add3_u32 v11, v11, v16, s28
	v_lshrrev_b32_e32 v12, 16, v12
	v_lshrrev_b32_e32 v13, 16, v13
	v_lshrrev_b32_e32 v14, 16, v14
	v_lshrrev_b32_e32 v15, 16, v15
	v_and_or_b32 v11, v11, s21, v15
	v_and_or_b32 v10, v10, s21, v14
	v_and_or_b32 v9, v9, s21, v13
	v_and_or_b32 v8, v8, s21, v12
	global_store_dwordx4 v[0:1], v[8:11], off offset:1024
	v_lshl_add_u64 v[0:1], v[0:1], 0, s[4:5]
	s_nop 0
	s_waitcnt vmcnt(17)
	v_mov_b32_e32 v10, v112
	v_mov_b32_e32 v11, v113
	v_mov_b32_e32 v12, v114
	v_mov_b32_e32 v13, v115
	v_mov_b32_e32 v14, v116
	v_mov_b32_e32 v15, v117
	v_mov_b32_e32 v16, v118
	v_mov_b32_e32 v17, v119
	v_mov_b32_e32 v18, v120
	v_mov_b32_e32 v19, v121
	v_mov_b32_e32 v20, v122
	v_mov_b32_e32 v21, v123
	v_mov_b32_e32 v46, v136
	v_mov_b32_e32 v47, v137
	v_mov_b32_e32 v48, v138
	v_lshlrev_b32_e32 v23, 16, v11
	v_and_b32_e32 v35, 0xffff0000, v11
	v_lshlrev_b32_e32 v41, 16, v13
	v_and_b32_e32 v43, 0xffff0000, v13
	v_lshlrev_b32_e32 v8, 16, v10
	v_and_b32_e32 v10, 0xffff0000, v10
	v_max3_f32 v49, v46, v47, v48
	v_lshlrev_b32_e32 v9, 16, v19
	v_and_b32_e32 v11, 0xffff0000, v19
	v_lshlrev_b32_e32 v22, 16, v18
	v_and_b32_e32 v34, 0xffff0000, v18
	v_sub_f32_e32 v18, v46, v49
	v_sub_f32_e32 v19, v47, v49
	v_lshlrev_b32_e32 v39, 16, v21
	v_and_b32_e32 v13, 0xffff0000, v21
	v_lshlrev_b32_e32 v40, 16, v20
	v_and_b32_e32 v42, 0xffff0000, v20
	v_sub_f32_e32 v20, v48, v49
	v_mul_f32_e32 v18, 0x3fb8aa3b, v18
	v_mul_f32_e32 v21, 0x3fb8aa3b, v19
	v_mul_f32_e32 v20, 0x3fb8aa3b, v20
	v_exp_f32_e32 v19, v18
	v_exp_f32_e32 v18, v21
	v_exp_f32_e32 v21, v20
	v_lshlrev_b32_e32 v38, 16, v12
	v_and_b32_e32 v12, 0xffff0000, v12
	v_add_f32_e32 v20, v19, v18
	v_add_f32_e32 v20, v21, v20
	v_div_scale_f32 v46, s[0:1], v20, v20, 1.0
	v_rcp_f32_e32 v48, v46
	v_div_scale_f32 v47, vcc, 1.0, v20, 1.0
	v_lshlrev_b32_e32 v37, 16, v15
	v_fma_f32 v49, -v46, v48, 1.0
	v_fmac_f32_e32 v48, v49, v48
	v_mul_f32_e32 v49, v47, v48
	v_fma_f32 v50, -v46, v49, v47
	v_fmac_f32_e32 v49, v50, v48
	v_fma_f32 v46, -v46, v49, v47
	v_div_fmas_f32 v46, v46, v48, v49
	v_div_fixup_f32 v20, v46, v20, 1.0
	v_pk_mul_f32 v[18:19], v[18:19], v[20:21] op_sel_hi:[1,0]
	v_mul_f32_e32 v46, v21, v20
	v_pk_mul_f32 v[20:21], v[18:19], v[22:23] op_sel:[1,0] op_sel_hi:[0,1]
	v_pk_mul_f32 v[22:23], v[18:19], v[34:35] op_sel:[1,0] op_sel_hi:[0,1]
	v_pk_mul_f32 v[34:35], v[18:19], v[40:41] op_sel:[1,0] op_sel_hi:[0,1]
	v_pk_mul_f32 v[40:41], v[18:19], v[42:43] op_sel:[1,0] op_sel_hi:[0,1]
	v_lshlrev_b32_e32 v36, 16, v14
	v_and_b32_e32 v15, 0xffff0000, v15
	v_and_b32_e32 v14, 0xffff0000, v14
	v_lshlrev_b32_e32 v45, 16, v17
	v_lshlrev_b32_e32 v44, 16, v16
	v_and_b32_e32 v17, 0xffff0000, v17
	v_and_b32_e32 v16, 0xffff0000, v16
	v_pk_fma_f32 v[8:9], v[18:19], v[8:9], v[20:21]
	v_pk_fma_f32 v[10:11], v[18:19], v[10:11], v[22:23]
	v_pk_fma_f32 v[20:21], v[18:19], v[38:39], v[34:35]
	v_pk_fma_f32 v[12:13], v[18:19], v[12:13], v[40:41]
	v_pk_fma_f32 v[8:9], v[46:47], v[36:37], v[8:9] op_sel_hi:[0,1,1]
	v_pk_fma_f32 v[10:11], v[46:47], v[14:15], v[10:11] op_sel_hi:[0,1,1]
	v_pk_fma_f32 v[14:15], v[46:47], v[44:45], v[20:21] op_sel_hi:[0,1,1]
	v_pk_fma_f32 v[12:13], v[46:47], v[16:17], v[12:13] op_sel_hi:[0,1,1]
	v_bfe_u32 v16, v13, 16, 1
	v_bfe_u32 v17, v12, 16, 1
	v_bfe_u32 v18, v11, 16, 1
	v_bfe_u32 v19, v10, 16, 1
	v_bfe_u32 v20, v8, 16, 1
	v_bfe_u32 v21, v9, 16, 1
	v_bfe_u32 v22, v14, 16, 1
	v_bfe_u32 v23, v15, 16, 1
	v_add3_u32 v19, v10, v19, s28
	v_add3_u32 v18, v11, v18, s28
	v_add3_u32 v10, v12, v17, s28
	v_add3_u32 v11, v13, v16, s28
	v_add3_u32 v12, v15, v23, s28
	v_add3_u32 v13, v14, v22, s28
	v_add3_u32 v9, v9, v21, s28
	v_add3_u32 v8, v8, v20, s28
	v_lshrrev_b32_e32 v8, 16, v8
	v_lshrrev_b32_e32 v9, 16, v9
	v_lshrrev_b32_e32 v13, 16, v13
	v_lshrrev_b32_e32 v12, 16, v12
	v_and_or_b32 v11, v11, s21, v12
	v_and_or_b32 v10, v10, s21, v13
	v_and_or_b32 v9, v18, s21, v9
	v_and_or_b32 v8, v19, s21, v8
	global_store_dwordx4 v[0:1], v[8:11], off
	s_nop 1
	v_mov_b32_e32 v8, v124
	v_mov_b32_e32 v9, v125
	v_mov_b32_e32 v10, v126
	v_mov_b32_e32 v11, v127
	v_mov_b32_e32 v12, v128
	v_mov_b32_e32 v13, v129
	v_mov_b32_e32 v14, v130
	v_mov_b32_e32 v15, v131
	v_mov_b32_e32 v16, v132
	v_mov_b32_e32 v17, v133
	v_mov_b32_e32 v18, v134
	v_mov_b32_e32 v19, v135
	v_mov_b32_e32 v34, v139
	v_mov_b32_e32 v35, v140
	v_mov_b32_e32 v36, v141
	v_max3_f32 v32, v34, v35, v36
	v_sub_f32_e32 v33, v34, v32
	v_sub_f32_e32 v34, v35, v32
	v_sub_f32_e32 v32, v36, v32
	v_mul_f32_e32 v33, 0x3fb8aa3b, v33
	v_mul_f32_e32 v34, 0x3fb8aa3b, v34
	v_mul_f32_e32 v35, 0x3fb8aa3b, v32
	v_exp_f32_e32 v33, v33
; __device__ __forceinline__ unsigned pk2(float lo, float hi) { return f2bf(lo) | (f2bf(hi) << 16); }
; __global__ void __launch_bounds__(NWAVES * 64, 2) mk_fwd(Args args) {
;     ...
;         for (int m = gw; m < MTOK; m += NGW) {
; #pragma unroll
;             for (int j = 0; j < 2; ++j) {
;                 const int e = j * 512 + lane * 8, h = e >> 7;
;                 const float l0 = LSE[((size_t)0 * MTOK + m) * 8 + h], l1 = LSE[((size_t)1 * MTOK + m) * 8 + h], l2 = LSE[((size_t)2 * MTOK + m) * 8 + h];
;                 const float mx = fmaxf(l0, fmaxf(l1, l2)); float w0 = __expf(l0 - mx), w1 = __expf(l1 - mx), w2 = __expf(l2 - mx);
;                 const float inv = 1.0f / (w0 + w1 + w2); w0 *= inv; w1 *= inv; w2 *= inv;
;                 const bf16r* p = PROJ + (size_t)m * INW + O_QB + e;
;                 const v4u a0 = *(const v4u*)p, a1 = *(const v4u*)(p + 1024), a2 = *(const v4u*)(p + 2048);
;                 v4u o;
; #pragma unroll
;                 for (int q = 0; q < 4; ++q) {
;                     const float x0 = __builtin_bit_cast(float, a0[q] << 16), y0 = __builtin_bit_cast(float, a0[q] & 0xffff0000u);
;                     const float x1 = __builtin_bit_cast(float, a1[q] << 16), y1 = __builtin_bit_cast(float, a1[q] & 0xffff0000u);
;                     const float x2 = __builtin_bit_cast(float, a2[q] << 16), y2 = __builtin_bit_cast(float, a2[q] & 0xffff0000u);
;                     o[q] = pk2(w0 * x0 + w1 * x1 + w2 * x2, w0 * y0 + w1 * y1 + w2 * y2);
;                 }
;                 *(v4u*)(MIX + (size_t)m * DM + 1024 + e) = o;
;             }
	v_exp_f32_e32 v32, v34
	v_exp_f32_e32 v35, v35
	v_lshlrev_b32_e32 v21, 16, v9
	v_and_b32_e32 v23, 0xffff0000, v9
	v_add_f32_e32 v34, v33, v32
	v_add_f32_e32 v34, v35, v34
	v_div_scale_f32 v36, s[0:1], v34, v34, 1.0
	v_rcp_f32_e32 v38, v36
	v_div_scale_f32 v37, vcc, 1.0, v34, 1.0
	v_lshlrev_b32_e32 v25, 16, v13
	v_fma_f32 v39, -v36, v38, 1.0
	v_fmac_f32_e32 v38, v39, v38
	v_mul_f32_e32 v39, v37, v38
	v_fma_f32 v40, -v36, v39, v37
	v_fmac_f32_e32 v39, v40, v38
	v_fma_f32 v36, -v36, v39, v37
	v_div_fmas_f32 v36, v36, v38, v39
	v_div_fixup_f32 v34, v36, v34, 1.0
	v_lshlrev_b32_e32 v24, 16, v8
	v_and_b32_e32 v9, 0xffff0000, v13
	v_and_b32_e32 v8, 0xffff0000, v8
	v_lshlrev_b32_e32 v31, 16, v15
	v_lshlrev_b32_e32 v30, 16, v10
	v_pk_mul_f32 v[32:33], v[32:33], v[34:35] op_sel_hi:[1,0]
	v_lshlrev_b32_e32 v20, 16, v12
	v_and_b32_e32 v22, 0xffff0000, v12
	v_lshlrev_b32_e32 v27, 16, v11
	v_lshlrev_b32_e32 v26, 16, v14
	v_and_b32_e32 v29, 0xffff0000, v11
	v_and_b32_e32 v11, 0xffff0000, v15
	v_and_b32_e32 v10, 0xffff0000, v10
	v_pk_mul_f32 v[24:25], v[32:33], v[24:25] op_sel:[1,0] op_sel_hi:[0,1]
	v_pk_mul_f32 v[8:9], v[32:33], v[8:9] op_sel:[1,0] op_sel_hi:[0,1]
	v_pk_mul_f32 v[30:31], v[32:33], v[30:31] op_sel:[1,0] op_sel_hi:[0,1]
	v_lshlrev_b32_e32 v13, 16, v17
	v_lshlrev_b32_e32 v12, 16, v16
	v_and_b32_e32 v28, 0xffff0000, v14
	v_lshlrev_b32_e32 v15, 16, v19
	v_lshlrev_b32_e32 v14, 16, v18
	v_mul_f32_e32 v36, v35, v34
	v_pk_mul_f32 v[10:11], v[32:33], v[10:11] op_sel:[1,0] op_sel_hi:[0,1]
	v_pk_fma_f32 v[20:21], v[32:33], v[20:21], v[24:25]
	v_pk_fma_f32 v[8:9], v[32:33], v[22:23], v[8:9]
	v_pk_fma_f32 v[22:23], v[32:33], v[26:27], v[30:31]
	v_and_b32_e32 v17, 0xffff0000, v17
	v_and_b32_e32 v16, 0xffff0000, v16
	v_and_b32_e32 v19, 0xffff0000, v19
	v_and_b32_e32 v18, 0xffff0000, v18
	v_pk_fma_f32 v[10:11], v[32:33], v[28:29], v[10:11]
	v_pk_fma_f32 v[12:13], v[36:37], v[12:13], v[20:21] op_sel_hi:[0,1,1]
	v_pk_fma_f32 v[14:15], v[36:37], v[14:15], v[22:23] op_sel_hi:[0,1,1]
	v_pk_fma_f32 v[8:9], v[36:37], v[16:17], v[8:9] op_sel_hi:[0,1,1]
	v_pk_fma_f32 v[10:11], v[36:37], v[18:19], v[10:11] op_sel_hi:[0,1,1]
	v_bfe_u32 v20, v12, 16, 1
	v_bfe_u32 v21, v13, 16, 1
	v_bfe_u32 v22, v14, 16, 1
	v_bfe_u32 v23, v15, 16, 1
	v_bfe_u32 v16, v11, 16, 1
	v_bfe_u32 v17, v10, 16, 1
	v_bfe_u32 v18, v9, 16, 1
	v_bfe_u32 v19, v8, 16, 1
	v_add3_u32 v15, v15, v23, s28
	v_add3_u32 v14, v14, v22, s28
	v_add3_u32 v13, v13, v21, s28
	v_add3_u32 v12, v12, v20, s28
	v_add3_u32 v8, v8, v19, s28
	v_add3_u32 v9, v9, v18, s28
	v_add3_u32 v10, v10, v17, s28
	v_add3_u32 v11, v11, v16, s28
	v_lshrrev_b32_e32 v12, 16, v12
	v_lshrrev_b32_e32 v13, 16, v13
	v_lshrrev_b32_e32 v14, 16, v14
	v_lshrrev_b32_e32 v15, 16, v15
	v_and_or_b32 v11, v11, s21, v15
	v_and_or_b32 v10, v10, s21, v14
	v_and_or_b32 v9, v9, s21, v13
	v_and_or_b32 v8, v8, s21, v12
	global_store_dwordx4 v[0:1], v[8:11], off offset:1024
	v_lshl_add_u64 v[0:1], v[0:1], 0, s[4:5]
	s_nop 0
	s_waitcnt vmcnt(5)
	v_mov_b32_e32 v10, v52
	v_mov_b32_e32 v11, v53
	v_mov_b32_e32 v12, v54
	v_mov_b32_e32 v13, v55
	v_mov_b32_e32 v14, v56
	v_mov_b32_e32 v15, v57
	v_mov_b32_e32 v16, v58
	v_mov_b32_e32 v17, v59
	v_mov_b32_e32 v18, v60
	v_mov_b32_e32 v19, v61
	v_mov_b32_e32 v20, v62
	v_mov_b32_e32 v21, v63
	v_mov_b32_e32 v46, v76
	v_mov_b32_e32 v47, v77
	v_mov_b32_e32 v48, v78
	v_lshlrev_b32_e32 v23, 16, v11
	v_and_b32_e32 v35, 0xffff0000, v11
	v_lshlrev_b32_e32 v41, 16, v13
	v_and_b32_e32 v43, 0xffff0000, v13
	v_lshlrev_b32_e32 v8, 16, v10
	v_and_b32_e32 v10, 0xffff0000, v10
	v_max3_f32 v49, v46, v47, v48
	v_lshlrev_b32_e32 v9, 16, v19
	v_and_b32_e32 v11, 0xffff0000, v19
	v_lshlrev_b32_e32 v22, 16, v18
	v_and_b32_e32 v34, 0xffff0000, v18
	v_sub_f32_e32 v18, v46, v49
	v_sub_f32_e32 v19, v47, v49
	v_lshlrev_b32_e32 v39, 16, v21
	v_and_b32_e32 v13, 0xffff0000, v21
	v_lshlrev_b32_e32 v40, 16, v20
	v_and_b32_e32 v42, 0xffff0000, v20
	v_sub_f32_e32 v20, v48, v49
	v_mul_f32_e32 v18, 0x3fb8aa3b, v18
	v_mul_f32_e32 v21, 0x3fb8aa3b, v19
	v_mul_f32_e32 v20, 0x3fb8aa3b, v20
	v_exp_f32_e32 v19, v18
	v_exp_f32_e32 v18, v21
	v_exp_f32_e32 v21, v20
	v_lshlrev_b32_e32 v38, 16, v12
	v_and_b32_e32 v12, 0xffff0000, v12
	v_add_f32_e32 v20, v19, v18
	v_add_f32_e32 v20, v21, v20
	v_div_scale_f32 v46, s[0:1], v20, v20, 1.0
	v_rcp_f32_e32 v48, v46
	v_div_scale_f32 v47, vcc, 1.0, v20, 1.0
	v_lshlrev_b32_e32 v37, 16, v15
	v_fma_f32 v49, -v46, v48, 1.0
	v_fmac_f32_e32 v48, v49, v48
	v_mul_f32_e32 v49, v47, v48
	v_fma_f32 v50, -v46, v49, v47
	v_fmac_f32_e32 v49, v50, v48
	v_fma_f32 v46, -v46, v49, v47
	v_div_fmas_f32 v46, v46, v48, v49
	v_div_fixup_f32 v20, v46, v20, 1.0
	v_pk_mul_f32 v[18:19], v[18:19], v[20:21] op_sel_hi:[1,0]
	v_mul_f32_e32 v46, v21, v20
	v_pk_mul_f32 v[20:21], v[18:19], v[22:23] op_sel:[1,0] op_sel_hi:[0,1]
	v_pk_mul_f32 v[22:23], v[18:19], v[34:35] op_sel:[1,0] op_sel_hi:[0,1]
	v_pk_mul_f32 v[34:35], v[18:19], v[40:41] op_sel:[1,0] op_sel_hi:[0,1]
	v_pk_mul_f32 v[40:41], v[18:19], v[42:43] op_sel:[1,0] op_sel_hi:[0,1]
	v_lshlrev_b32_e32 v36, 16, v14
; __device__ __forceinline__ unsigned pk2(float lo, float hi) { return f2bf(lo) | (f2bf(hi) << 16); }
; __global__ void __launch_bounds__(NWAVES * 64, 2) mk_fwd(Args args) {
;     ...
;         for (int m = gw; m < MTOK; m += NGW) {
; #pragma unroll
;             for (int j = 0; j < 2; ++j) {
;                 const int e = j * 512 + lane * 8, h = e >> 7;
;                 const float l0 = LSE[((size_t)0 * MTOK + m) * 8 + h], l1 = LSE[((size_t)1 * MTOK + m) * 8 + h], l2 = LSE[((size_t)2 * MTOK + m) * 8 + h];
;                 const float mx = fmaxf(l0, fmaxf(l1, l2)); float w0 = __expf(l0 - mx), w1 = __expf(l1 - mx), w2 = __expf(l2 - mx);
;                 const float inv = 1.0f / (w0 + w1 + w2); w0 *= inv; w1 *= inv; w2 *= inv;
;                 const bf16r* p = PROJ + (size_t)m * INW + O_QB + e;
;                 const v4u a0 = *(const v4u*)p, a1 = *(const v4u*)(p + 1024), a2 = *(const v4u*)(p + 2048);
;                 v4u o;
; #pragma unroll
;                 for (int q = 0; q < 4; ++q) {
;                     const float x0 = __builtin_bit_cast(float, a0[q] << 16), y0 = __builtin_bit_cast(float, a0[q] & 0xffff0000u);
;                     const float x1 = __builtin_bit_cast(float, a1[q] << 16), y1 = __builtin_bit_cast(float, a1[q] & 0xffff0000u);
;                     const float x2 = __builtin_bit_cast(float, a2[q] << 16), y2 = __builtin_bit_cast(float, a2[q] & 0xffff0000u);
;                     o[q] = pk2(w0 * x0 + w1 * x1 + w2 * x2, w0 * y0 + w1 * y1 + w2 * y2);
;                 }
;                 *(v4u*)(MIX + (size_t)m * DM + 1024 + e) = o;
;             }
	v_and_b32_e32 v15, 0xffff0000, v15
	v_and_b32_e32 v14, 0xffff0000, v14
	v_lshlrev_b32_e32 v45, 16, v17
	v_lshlrev_b32_e32 v44, 16, v16
	v_and_b32_e32 v17, 0xffff0000, v17
	v_and_b32_e32 v16, 0xffff0000, v16
	v_pk_fma_f32 v[8:9], v[18:19], v[8:9], v[20:21]
	v_pk_fma_f32 v[10:11], v[18:19], v[10:11], v[22:23]
	v_pk_fma_f32 v[20:21], v[18:19], v[38:39], v[34:35]
	v_pk_fma_f32 v[12:13], v[18:19], v[12:13], v[40:41]
	v_pk_fma_f32 v[8:9], v[46:47], v[36:37], v[8:9] op_sel_hi:[0,1,1]
	v_pk_fma_f32 v[10:11], v[46:47], v[14:15], v[10:11] op_sel_hi:[0,1,1]
	v_pk_fma_f32 v[14:15], v[46:47], v[44:45], v[20:21] op_sel_hi:[0,1,1]
	v_pk_fma_f32 v[12:13], v[46:47], v[16:17], v[12:13] op_sel_hi:[0,1,1]
	v_bfe_u32 v16, v13, 16, 1
	v_bfe_u32 v17, v12, 16, 1
	v_bfe_u32 v18, v11, 16, 1
	v_bfe_u32 v19, v10, 16, 1
	v_bfe_u32 v20, v8, 16, 1
	v_bfe_u32 v21, v9, 16, 1
	v_bfe_u32 v22, v14, 16, 1
	v_bfe_u32 v23, v15, 16, 1
	v_add3_u32 v19, v10, v19, s28
	v_add3_u32 v18, v11, v18, s28
	v_add3_u32 v10, v12, v17, s28
	v_add3_u32 v11, v13, v16, s28
	v_add3_u32 v12, v15, v23, s28
	v_add3_u32 v13, v14, v22, s28
	v_add3_u32 v9, v9, v21, s28
	v_add3_u32 v8, v8, v20, s28
	v_lshrrev_b32_e32 v8, 16, v8
	v_lshrrev_b32_e32 v9, 16, v9
	v_lshrrev_b32_e32 v13, 16, v13
	v_lshrrev_b32_e32 v12, 16, v12
	v_and_or_b32 v11, v11, s21, v12
	v_and_or_b32 v10, v10, s21, v13
	v_and_or_b32 v9, v18, s21, v9
	v_and_or_b32 v8, v19, s21, v8
	global_store_dwordx4 v[0:1], v[8:11], off
	s_nop 1
	v_mov_b32_e32 v8, v64
	v_mov_b32_e32 v9, v65
	v_mov_b32_e32 v10, v66
	v_mov_b32_e32 v11, v67
	v_mov_b32_e32 v12, v68
	v_mov_b32_e32 v13, v69
	v_mov_b32_e32 v14, v70
	v_mov_b32_e32 v15, v71
	v_mov_b32_e32 v16, v72
	v_mov_b32_e32 v17, v73
	v_mov_b32_e32 v18, v74
	v_mov_b32_e32 v19, v75
	v_mov_b32_e32 v34, v79
	v_mov_b32_e32 v35, v80
	v_mov_b32_e32 v36, v81
	v_max3_f32 v32, v34, v35, v36
	v_sub_f32_e32 v33, v34, v32
	v_sub_f32_e32 v34, v35, v32
	v_sub_f32_e32 v32, v36, v32
	v_mul_f32_e32 v33, 0x3fb8aa3b, v33
	v_mul_f32_e32 v34, 0x3fb8aa3b, v34
	v_mul_f32_e32 v35, 0x3fb8aa3b, v32
	v_exp_f32_e32 v33, v33
	v_exp_f32_e32 v32, v34
	v_exp_f32_e32 v35, v35
	v_lshlrev_b32_e32 v21, 16, v9
	v_and_b32_e32 v23, 0xffff0000, v9
	v_add_f32_e32 v34, v33, v32
	v_add_f32_e32 v34, v35, v34
	v_div_scale_f32 v36, s[0:1], v34, v34, 1.0
	v_rcp_f32_e32 v38, v36
	v_div_scale_f32 v37, vcc, 1.0, v34, 1.0
	v_lshlrev_b32_e32 v25, 16, v13
	v_fma_f32 v39, -v36, v38, 1.0
	v_fmac_f32_e32 v38, v39, v38
	v_mul_f32_e32 v39, v37, v38
	v_fma_f32 v40, -v36, v39, v37
	v_fmac_f32_e32 v39, v40, v38
	v_fma_f32 v36, -v36, v39, v37
	v_div_fmas_f32 v36, v36, v38, v39
	v_div_fixup_f32 v34, v36, v34, 1.0
	v_lshlrev_b32_e32 v24, 16, v8
	v_and_b32_e32 v9, 0xffff0000, v13
	v_and_b32_e32 v8, 0xffff0000, v8
	v_lshlrev_b32_e32 v31, 16, v15
	v_lshlrev_b32_e32 v30, 16, v10
	v_pk_mul_f32 v[32:33], v[32:33], v[34:35] op_sel_hi:[1,0]
	v_lshlrev_b32_e32 v20, 16, v12
	v_and_b32_e32 v22, 0xffff0000, v12
	v_lshlrev_b32_e32 v27, 16, v11
	v_lshlrev_b32_e32 v26, 16, v14
	v_and_b32_e32 v29, 0xffff0000, v11
	v_and_b32_e32 v11, 0xffff0000, v15
	v_and_b32_e32 v10, 0xffff0000, v10
	v_pk_mul_f32 v[24:25], v[32:33], v[24:25] op_sel:[1,0] op_sel_hi:[0,1]
	v_pk_mul_f32 v[8:9], v[32:33], v[8:9] op_sel:[1,0] op_sel_hi:[0,1]
	v_pk_mul_f32 v[30:31], v[32:33], v[30:31] op_sel:[1,0] op_sel_hi:[0,1]
	v_lshlrev_b32_e32 v13, 16, v17
	v_lshlrev_b32_e32 v12, 16, v16
	v_and_b32_e32 v28, 0xffff0000, v14
	v_lshlrev_b32_e32 v15, 16, v19
	v_lshlrev_b32_e32 v14, 16, v18
	v_mul_f32_e32 v36, v35, v34
	v_pk_mul_f32 v[10:11], v[32:33], v[10:11] op_sel:[1,0] op_sel_hi:[0,1]
	v_pk_fma_f32 v[20:21], v[32:33], v[20:21], v[24:25]
	v_pk_fma_f32 v[8:9], v[32:33], v[22:23], v[8:9]
	v_pk_fma_f32 v[22:23], v[32:33], v[26:27], v[30:31]
	v_and_b32_e32 v17, 0xffff0000, v17
	v_and_b32_e32 v16, 0xffff0000, v16
	v_and_b32_e32 v19, 0xffff0000, v19
	v_and_b32_e32 v18, 0xffff0000, v18
	v_pk_fma_f32 v[10:11], v[32:33], v[28:29], v[10:11]
	v_pk_fma_f32 v[12:13], v[36:37], v[12:13], v[20:21] op_sel_hi:[0,1,1]
	v_pk_fma_f32 v[14:15], v[36:37], v[14:15], v[22:23] op_sel_hi:[0,1,1]
	v_pk_fma_f32 v[8:9], v[36:37], v[16:17], v[8:9] op_sel_hi:[0,1,1]
	v_pk_fma_f32 v[10:11], v[36:37], v[18:19], v[10:11] op_sel_hi:[0,1,1]
	v_bfe_u32 v20, v12, 16, 1
	v_bfe_u32 v21, v13, 16, 1
	v_bfe_u32 v22, v14, 16, 1
	v_bfe_u32 v23, v15, 16, 1
	v_bfe_u32 v16, v11, 16, 1
	v_bfe_u32 v17, v10, 16, 1
	v_bfe_u32 v18, v9, 16, 1
	v_bfe_u32 v19, v8, 16, 1
	v_add3_u32 v15, v15, v23, s28
	v_add3_u32 v14, v14, v22, s28
	v_add3_u32 v13, v13, v21, s28
	v_add3_u32 v12, v12, v20, s28
	v_add3_u32 v8, v8, v19, s28
	v_add3_u32 v9, v9, v18, s28
	v_add3_u32 v10, v10, v17, s28
	v_add3_u32 v11, v11, v16, s28
	v_lshrrev_b32_e32 v12, 16, v12
	v_lshrrev_b32_e32 v13, 16, v13
	v_lshrrev_b32_e32 v14, 16, v14
	v_lshrrev_b32_e32 v15, 16, v15
	v_and_or_b32 v11, v11, s21, v15
	v_and_or_b32 v10, v10, s21, v14
	v_and_or_b32 v9, v9, s21, v13
	v_and_or_b32 v8, v8, s21, v12
	global_store_dwordx4 v[0:1], v[8:11], off offset:1024
	v_lshl_add_u64 v[0:1], v[0:1], 0, s[4:5]
	s_nop 0
	s_add_i32 s30, s30, 0x8000
	s_branch .LBB0_610
